# s5b item rewritten: f32 MFMA 16x16x4 for B*u and C*h plus DPP Kogge-Stone scan (replaces VALU/LDS version)
# speedup vs baseline: 1.0573x; 1.0573x over previous
.LBB0_406:
	s_mov_b64 s[38:39], 0
	s_branch .LBB0_1016
.LBB0_408:
	s_mov_b32 s0, s84
	s_add_i32 s23, s0, s23
	s_cmpk_gt_i32 s23, 0x3ff
	s_cbranch_scc1 .LBB0_552

.LBB0_524:
	s_and_b64 vcc, exec, s[0:1]
	s_cbranch_vccz .LBB0_408
	s_lshr_b32 s0, s23, 1
	s_and_b32 s1, s23, 1
	v_lshrrev_b32_e32 v0, 6, v135
	v_readlane_b32 s6, v249, 47
	v_readlane_b32 s10, v251, 1
	v_readlane_b32 s11, v251, 2
	v_readfirstlane_b32 s4, v0
	s_nop 3
	s_sub_u32 s10, s10, 0x168
	s_subb_u32 s11, s11, 0
	s_load_dwordx4 s[16:19], s[10:11], 0xd8
	s_load_dwordx2 s[20:21], s[10:11], 0xe8
	s_lshl_b32 s5, s1, 3
	s_add_i32 s5, s5, s4
	v_and_b32_e32 v2, 63, v135
	v_lshrrev_b32_e32 v3, 4, v2
	v_and_b32_e32 v4, 15, v2
	v_lshlrev_b32_e32 v5, 10, v4
	v_lshl_add_u32 v5, v3, 4, v5
	v_add_u32_e32 v6, 0x4000, v5
	v_lshlrev_b32_e32 v7, 2, v4
	v_lshl_add_u32 v7, v3, 12, v7
	v_add_u32_e32 v8, 0x4000, v7
	v_lshlrev_b32_e32 v9, 1, v4
	v_lshl_add_u32 v9, v3, 11, v9
	v_add_u32_e32 v10, 0x2000, v9
	v_lshlrev_b32_e32 v11, 4, v4
	v_lshl_add_u32 v11, v3, 11, v11
	v_lshlrev_b32_e32 v12, 8, v4
	v_lshl_add_u32 v12, v3, 4, v12
	v_lshlrev_b32_e32 v13, 5, v3
	v_lshlrev_b32_e32 v14, 3, v2
	v_lshlrev_b32_e32 v15, 2, v4
	v_lshlrev_b32_e32 v16, 4, v3
	s_lshl_b32 s54, s4, 12
	s_add_i32 s54, s54, 0x10000
	v_lshl_add_u32 v17, v2, 2, s54
	v_lshl_add_u32 v18, v3, 4, s54
	s_lshl_b32 s55, s0, 15
	s_lshl_b32 s56, s5, 6
	s_add_u32 s55, s55, s56
	s_add_u32 s8, s94, 0x8a40000
	s_addc_u32 s9, s95, 0
	s_add_u32 s8, s8, s55
	s_addc_u32 s9, s9, 0
	s_lshl_b32 s55, s0, 14
	s_lshl_b32 s56, s5, 5
	s_add_u32 s55, s55, s56
	s_add_u32 s44, s94, 0x11640000
	s_addc_u32 s45, s95, 0
	s_add_u32 s44, s44, s55
	s_addc_u32 s45, s45, 0
	s_mov_b32 s52, 0x00010001
	s_mov_b32 s53, 0x00010001
	s_mov_b32 s62, 0x80008000
	s_mov_b32 s63, 0x80008000
	global_load_dwordx4 v[20:23], v5, s[8:9]
	global_load_dwordx4 v[24:27], v6, s[8:9]
	s_waitcnt lgkmcnt(0)
	s_lshl_b32 s55, s6, 10
	s_lshl_b32 s56, s5, 6
	s_add_u32 s55, s55, s56
	s_add_u32 s20, s20, s55
	s_addc_u32 s21, s21, 0
	s_add_i32 s55, s5, 0
	s_lshl_b32 s56, s55, 13
	s_add_u32 s12, s94, 0x12d96000
	s_addc_u32 s13, s95, 0
	s_add_u32 s12, s12, s56
	s_addc_u32 s13, s13, 0
	s_lshl_b32 s56, s55, 9
	s_add_u32 s38, s94, 0x12d92000
	s_addc_u32 s39, s95, 0
	s_add_u32 s38, s38, s56
	s_addc_u32 s39, s39, 0
	s_lshl_b32 s56, s6, 1
	s_add_i32 s56, s56, 0
	s_lshl_b32 s56, s56, 4
	s_add_i32 s56, s56, s5
	s_lshl_b32 s56, s56, 12
	s_add_u32 s14, s16, s56
	s_addc_u32 s15, s17, 0
	s_add_u32 s24, s18, s56
	s_addc_u32 s25, s19, 0
	s_lshl_b32 s56, s0, 5
	s_lshl_b32 s55, s5, 1
	s_add_i32 s56, s56, s55
	s_add_i32 s56, s56, 0
	s_lshl_b32 s56, s56, 9
	s_add_u32 s36, s94, 0x133d6000
	s_addc_u32 s37, s95, 0
	s_add_u32 s36, s36, s56
	s_addc_u32 s37, s37, 0
	global_load_dwordx2 v[2:3], v14, s[38:39]
	global_load_dwordx4 v[28:31], v11, s[12:13] offset:0
	global_load_dwordx4 v[32:35], v11, s[12:13] offset:1024
	global_load_dwordx4 v[36:39], v11, s[12:13] offset:256
	global_load_dwordx4 v[40:43], v11, s[12:13] offset:1280
	global_load_dwordx4 v[44:47], v11, s[12:13] offset:512
	global_load_dwordx4 v[48:51], v11, s[12:13] offset:1536
	global_load_dwordx4 v[52:55], v11, s[12:13] offset:768
	global_load_dwordx4 v[56:59], v11, s[12:13] offset:1792
	global_load_dwordx4 v[124:127], v13, s[36:37] offset:0
	global_load_dwordx4 v[128:131], v13, s[36:37] offset:16
	global_load_dwordx4 v[140:143], v13, s[36:37] offset:128
	global_load_dwordx4 v[144:147], v13, s[36:37] offset:144
	global_load_dwordx4 v[148:151], v13, s[36:37] offset:256
	global_load_dwordx4 v[152:155], v13, s[36:37] offset:272
	global_load_dwordx4 v[156:159], v13, s[36:37] offset:384
	global_load_dwordx4 v[168:171], v13, s[36:37] offset:400
	global_load_dwordx4 v[60:63], v12, s[14:15] offset:0
	global_load_dwordx4 v[64:67], v12, s[24:25] offset:0
	global_load_dwordx4 v[68:71], v12, s[14:15] offset:64
	global_load_dwordx4 v[72:75], v12, s[24:25] offset:64
	global_load_dwordx4 v[76:79], v12, s[14:15] offset:128
	global_load_dwordx4 v[80:83], v12, s[24:25] offset:128
	global_load_dwordx4 v[84:87], v12, s[14:15] offset:192
	global_load_dwordx4 v[88:91], v12, s[24:25] offset:192
	s_waitcnt vmcnt(24)
	ds_write_b32 v17, v2 offset:0
	ds_write_b32 v17, v3 offset:256
	v_mul_f32_e32 v232, v3, v3
	v_mul_f32_e32 v233, v2, v3
	v_fma_f32 v2, v2, v2, -v232
	v_add_f32_e32 v3, v233, v233
	ds_write_b32 v17, v2 offset:512
	ds_write_b32 v17, v3 offset:768
	v_mul_f32_e32 v232, v3, v3
	v_mul_f32_e32 v233, v2, v3
	v_fma_f32 v2, v2, v2, -v232
	v_add_f32_e32 v3, v233, v233
	ds_write_b32 v17, v2 offset:1024
	ds_write_b32 v17, v3 offset:1280
	v_mul_f32_e32 v232, v3, v3
	v_mul_f32_e32 v233, v2, v3
	v_fma_f32 v2, v2, v2, -v232
	v_add_f32_e32 v3, v233, v233
	ds_write_b32 v17, v2 offset:1536
	ds_write_b32 v17, v3 offset:1792
	s_waitcnt lgkmcnt(0)
	s_waitcnt vmcnt(23)
	v_mfma_f32_16x16x4_f32 v[92:95], v28, v20, 0
	v_mfma_f32_16x16x4_f32 v[96:99], v29, v20, 0
	s_waitcnt vmcnt(21)
	v_mfma_f32_16x16x4_f32 v[100:103], v36, v20, 0
	v_mfma_f32_16x16x4_f32 v[104:107], v37, v20, 0
	s_waitcnt vmcnt(19)
	v_mfma_f32_16x16x4_f32 v[108:111], v44, v20, 0
	v_mfma_f32_16x16x4_f32 v[112:115], v45, v20, 0
	s_waitcnt vmcnt(17)
	v_mfma_f32_16x16x4_f32 v[116:119], v52, v20, 0
	v_mfma_f32_16x16x4_f32 v[120:123], v53, v20, 0
	v_mfma_f32_16x16x4_f32 v[92:95], v30, v21, v[92:95]
	v_mfma_f32_16x16x4_f32 v[96:99], v31, v21, v[96:99]
	v_mfma_f32_16x16x4_f32 v[100:103], v38, v21, v[100:103]
	v_mfma_f32_16x16x4_f32 v[104:107], v39, v21, v[104:107]
	v_mfma_f32_16x16x4_f32 v[108:111], v46, v21, v[108:111]
	v_mfma_f32_16x16x4_f32 v[112:115], v47, v21, v[112:115]
	v_mfma_f32_16x16x4_f32 v[116:119], v54, v21, v[116:119]
	v_mfma_f32_16x16x4_f32 v[120:123], v55, v21, v[120:123]
	v_mfma_f32_16x16x4_f32 v[92:95], v32, v22, v[92:95]
	v_mfma_f32_16x16x4_f32 v[96:99], v33, v22, v[96:99]
	v_mfma_f32_16x16x4_f32 v[100:103], v40, v22, v[100:103]
	v_mfma_f32_16x16x4_f32 v[104:107], v41, v22, v[104:107]
	v_mfma_f32_16x16x4_f32 v[108:111], v48, v22, v[108:111]
	v_mfma_f32_16x16x4_f32 v[112:115], v49, v22, v[112:115]
	s_waitcnt vmcnt(16)
	v_mfma_f32_16x16x4_f32 v[116:119], v56, v22, v[116:119]
	v_mfma_f32_16x16x4_f32 v[120:123], v57, v22, v[120:123]
	v_mfma_f32_16x16x4_f32 v[92:95], v34, v23, v[92:95]
	v_mfma_f32_16x16x4_f32 v[96:99], v35, v23, v[96:99]
	v_mfma_f32_16x16x4_f32 v[100:103], v42, v23, v[100:103]
	v_mfma_f32_16x16x4_f32 v[104:107], v43, v23, v[104:107]
	v_mfma_f32_16x16x4_f32 v[108:111], v50, v23, v[108:111]
	v_mfma_f32_16x16x4_f32 v[112:115], v51, v23, v[112:115]
	v_mfma_f32_16x16x4_f32 v[116:119], v58, v23, v[116:119]
	v_mfma_f32_16x16x4_f32 v[120:123], v59, v23, v[120:123]
	ds_read_b128 v[188:191], v18 offset:0
	ds_read_b128 v[192:195], v18 offset:256
	s_waitcnt vmcnt(15)
	s_waitcnt vmcnt(14)
	s_waitcnt vmcnt(13)
	s_waitcnt vmcnt(12)
	s_waitcnt vmcnt(11)
	s_waitcnt vmcnt(10)
	s_waitcnt vmcnt(9)
	s_waitcnt vmcnt(8)
	s_nop 9
	ds_read_b128 v[224:227], v18 offset:64
	ds_read_b128 v[228:231], v18 offset:320
	s_waitcnt lgkmcnt(2)
	s_mov_b64 exec, s[52:53]
	v_fmac_f32_e32 v92, v188, v124
	v_fmac_f32_e32 v93, v189, v126
	v_fmac_f32_e32 v94, v190, v128
	v_fmac_f32_e32 v95, v191, v130
	v_fma_f32 v92, -v192, v125, v92
	v_fma_f32 v93, -v193, v127, v93
	v_fma_f32 v94, -v194, v129, v94
	v_fma_f32 v95, -v195, v131, v95
	v_fmac_f32_e32 v96, v188, v125
	v_fmac_f32_e32 v97, v189, v127
	v_fmac_f32_e32 v98, v190, v129
	v_fmac_f32_e32 v99, v191, v131
	v_fmac_f32_e32 v96, v192, v124
	v_fmac_f32_e32 v97, v193, v126
	v_fmac_f32_e32 v98, v194, v128
	v_fmac_f32_e32 v99, v195, v130
	s_mov_b64 exec, -1
	v_mov_b32_e32 v232, v92
	v_mov_b32_e32 v233, v93
	v_mov_b32_e32 v234, v94
	v_mov_b32_e32 v235, v95
	s_nop 1
	v_fmac_f32_dpp v92, v92, v188 row_shr:1 row_mask:0xf bank_mask:0xf bound_ctrl:0
	v_fmac_f32_dpp v93, v93, v189 row_shr:1 row_mask:0xf bank_mask:0xf bound_ctrl:0
	v_fmac_f32_dpp v94, v94, v190 row_shr:1 row_mask:0xf bank_mask:0xf bound_ctrl:0
	v_fmac_f32_dpp v95, v95, v191 row_shr:1 row_mask:0xf bank_mask:0xf bound_ctrl:0
	v_fmac_f32_dpp v92, v96, -v192 row_shr:1 row_mask:0xf bank_mask:0xf bound_ctrl:0
	v_fmac_f32_dpp v93, v97, -v193 row_shr:1 row_mask:0xf bank_mask:0xf bound_ctrl:0
	v_fmac_f32_dpp v94, v98, -v194 row_shr:1 row_mask:0xf bank_mask:0xf bound_ctrl:0
	v_fmac_f32_dpp v95, v99, -v195 row_shr:1 row_mask:0xf bank_mask:0xf bound_ctrl:0
	v_fmac_f32_dpp v96, v96, v188 row_shr:1 row_mask:0xf bank_mask:0xf bound_ctrl:0
	v_fmac_f32_dpp v97, v97, v189 row_shr:1 row_mask:0xf bank_mask:0xf bound_ctrl:0
	v_fmac_f32_dpp v98, v98, v190 row_shr:1 row_mask:0xf bank_mask:0xf bound_ctrl:0
	v_fmac_f32_dpp v99, v99, v191 row_shr:1 row_mask:0xf bank_mask:0xf bound_ctrl:0
	v_fmac_f32_dpp v96, v232, v192 row_shr:1 row_mask:0xf bank_mask:0xf bound_ctrl:0
	v_fmac_f32_dpp v97, v233, v193 row_shr:1 row_mask:0xf bank_mask:0xf bound_ctrl:0
	v_fmac_f32_dpp v98, v234, v194 row_shr:1 row_mask:0xf bank_mask:0xf bound_ctrl:0
	v_fmac_f32_dpp v99, v235, v195 row_shr:1 row_mask:0xf bank_mask:0xf bound_ctrl:0
	ds_read_b128 v[188:191], v18 offset:128
	ds_read_b128 v[192:195], v18 offset:384
	s_waitcnt lgkmcnt(2)
	s_mov_b64 exec, s[52:53]
	v_fmac_f32_e32 v100, v224, v140
	v_fmac_f32_e32 v101, v225, v142
	v_fmac_f32_e32 v102, v226, v144
	v_fmac_f32_e32 v103, v227, v146
	v_fma_f32 v100, -v228, v141, v100
	v_fma_f32 v101, -v229, v143, v101
	v_fma_f32 v102, -v230, v145, v102
	v_fma_f32 v103, -v231, v147, v103
	v_fmac_f32_e32 v104, v224, v141
	v_fmac_f32_e32 v105, v225, v143
	v_fmac_f32_e32 v106, v226, v145
	v_fmac_f32_e32 v107, v227, v147
	v_fmac_f32_e32 v104, v228, v140
	v_fmac_f32_e32 v105, v229, v142
	v_fmac_f32_e32 v106, v230, v144
	v_fmac_f32_e32 v107, v231, v146
	s_mov_b64 exec, -1
	v_mov_b32_e32 v232, v100
	v_mov_b32_e32 v233, v101
	v_mov_b32_e32 v234, v102
	v_mov_b32_e32 v235, v103
	s_nop 1
	v_fmac_f32_dpp v100, v100, v224 row_shr:1 row_mask:0xf bank_mask:0xf bound_ctrl:0
	v_fmac_f32_dpp v101, v101, v225 row_shr:1 row_mask:0xf bank_mask:0xf bound_ctrl:0
	v_fmac_f32_dpp v102, v102, v226 row_shr:1 row_mask:0xf bank_mask:0xf bound_ctrl:0
	v_fmac_f32_dpp v103, v103, v227 row_shr:1 row_mask:0xf bank_mask:0xf bound_ctrl:0
	v_fmac_f32_dpp v100, v104, -v228 row_shr:1 row_mask:0xf bank_mask:0xf bound_ctrl:0
	v_fmac_f32_dpp v101, v105, -v229 row_shr:1 row_mask:0xf bank_mask:0xf bound_ctrl:0
	v_fmac_f32_dpp v102, v106, -v230 row_shr:1 row_mask:0xf bank_mask:0xf bound_ctrl:0
	v_fmac_f32_dpp v103, v107, -v231 row_shr:1 row_mask:0xf bank_mask:0xf bound_ctrl:0
	v_fmac_f32_dpp v104, v104, v224 row_shr:1 row_mask:0xf bank_mask:0xf bound_ctrl:0
	v_fmac_f32_dpp v105, v105, v225 row_shr:1 row_mask:0xf bank_mask:0xf bound_ctrl:0
	v_fmac_f32_dpp v106, v106, v226 row_shr:1 row_mask:0xf bank_mask:0xf bound_ctrl:0
	v_fmac_f32_dpp v107, v107, v227 row_shr:1 row_mask:0xf bank_mask:0xf bound_ctrl:0
	v_fmac_f32_dpp v104, v232, v228 row_shr:1 row_mask:0xf bank_mask:0xf bound_ctrl:0
	v_fmac_f32_dpp v105, v233, v229 row_shr:1 row_mask:0xf bank_mask:0xf bound_ctrl:0
	v_fmac_f32_dpp v106, v234, v230 row_shr:1 row_mask:0xf bank_mask:0xf bound_ctrl:0
	v_fmac_f32_dpp v107, v235, v231 row_shr:1 row_mask:0xf bank_mask:0xf bound_ctrl:0
	ds_read_b128 v[224:227], v18 offset:192
	ds_read_b128 v[228:231], v18 offset:448
	s_waitcnt lgkmcnt(2)
	s_mov_b64 exec, s[52:53]
	v_fmac_f32_e32 v108, v188, v148
	v_fmac_f32_e32 v109, v189, v150
	v_fmac_f32_e32 v110, v190, v152
	v_fmac_f32_e32 v111, v191, v154
	v_fma_f32 v108, -v192, v149, v108
	v_fma_f32 v109, -v193, v151, v109
	v_fma_f32 v110, -v194, v153, v110
	v_fma_f32 v111, -v195, v155, v111
	v_fmac_f32_e32 v112, v188, v149
	v_fmac_f32_e32 v113, v189, v151
	v_fmac_f32_e32 v114, v190, v153
	v_fmac_f32_e32 v115, v191, v155
	v_fmac_f32_e32 v112, v192, v148
	v_fmac_f32_e32 v113, v193, v150
	v_fmac_f32_e32 v114, v194, v152
	v_fmac_f32_e32 v115, v195, v154
	s_mov_b64 exec, -1
	v_mov_b32_e32 v232, v108
	v_mov_b32_e32 v233, v109
	v_mov_b32_e32 v234, v110
	v_mov_b32_e32 v235, v111
	s_nop 1
	v_fmac_f32_dpp v108, v108, v188 row_shr:1 row_mask:0xf bank_mask:0xf bound_ctrl:0
	v_fmac_f32_dpp v109, v109, v189 row_shr:1 row_mask:0xf bank_mask:0xf bound_ctrl:0
	v_fmac_f32_dpp v110, v110, v190 row_shr:1 row_mask:0xf bank_mask:0xf bound_ctrl:0
	v_fmac_f32_dpp v111, v111, v191 row_shr:1 row_mask:0xf bank_mask:0xf bound_ctrl:0
	v_fmac_f32_dpp v108, v112, -v192 row_shr:1 row_mask:0xf bank_mask:0xf bound_ctrl:0
	v_fmac_f32_dpp v109, v113, -v193 row_shr:1 row_mask:0xf bank_mask:0xf bound_ctrl:0
	v_fmac_f32_dpp v110, v114, -v194 row_shr:1 row_mask:0xf bank_mask:0xf bound_ctrl:0
	v_fmac_f32_dpp v111, v115, -v195 row_shr:1 row_mask:0xf bank_mask:0xf bound_ctrl:0
	v_fmac_f32_dpp v112, v112, v188 row_shr:1 row_mask:0xf bank_mask:0xf bound_ctrl:0
	v_fmac_f32_dpp v113, v113, v189 row_shr:1 row_mask:0xf bank_mask:0xf bound_ctrl:0
	v_fmac_f32_dpp v114, v114, v190 row_shr:1 row_mask:0xf bank_mask:0xf bound_ctrl:0
	v_fmac_f32_dpp v115, v115, v191 row_shr:1 row_mask:0xf bank_mask:0xf bound_ctrl:0
	v_fmac_f32_dpp v112, v232, v192 row_shr:1 row_mask:0xf bank_mask:0xf bound_ctrl:0
	v_fmac_f32_dpp v113, v233, v193 row_shr:1 row_mask:0xf bank_mask:0xf bound_ctrl:0
	v_fmac_f32_dpp v114, v234, v194 row_shr:1 row_mask:0xf bank_mask:0xf bound_ctrl:0
	v_fmac_f32_dpp v115, v235, v195 row_shr:1 row_mask:0xf bank_mask:0xf bound_ctrl:0
	ds_read_b128 v[188:191], v18 offset:512
	ds_read_b128 v[192:195], v18 offset:768
	s_waitcnt lgkmcnt(2)
	s_mov_b64 exec, s[52:53]
	v_fmac_f32_e32 v116, v224, v156
	v_fmac_f32_e32 v117, v225, v158
	v_fmac_f32_e32 v118, v226, v168
	v_fmac_f32_e32 v119, v227, v170
	v_fma_f32 v116, -v228, v157, v116
	v_fma_f32 v117, -v229, v159, v117
	v_fma_f32 v118, -v230, v169, v118
	v_fma_f32 v119, -v231, v171, v119
	v_fmac_f32_e32 v120, v224, v157
	v_fmac_f32_e32 v121, v225, v159
	v_fmac_f32_e32 v122, v226, v169
	v_fmac_f32_e32 v123, v227, v171
	v_fmac_f32_e32 v120, v228, v156
	v_fmac_f32_e32 v121, v229, v158
	v_fmac_f32_e32 v122, v230, v168
	v_fmac_f32_e32 v123, v231, v170
	s_mov_b64 exec, -1
	v_mov_b32_e32 v232, v116
	v_mov_b32_e32 v233, v117
	v_mov_b32_e32 v234, v118
	v_mov_b32_e32 v235, v119
	s_nop 1
	v_fmac_f32_dpp v116, v116, v224 row_shr:1 row_mask:0xf bank_mask:0xf bound_ctrl:0
	v_fmac_f32_dpp v117, v117, v225 row_shr:1 row_mask:0xf bank_mask:0xf bound_ctrl:0
	v_fmac_f32_dpp v118, v118, v226 row_shr:1 row_mask:0xf bank_mask:0xf bound_ctrl:0
	v_fmac_f32_dpp v119, v119, v227 row_shr:1 row_mask:0xf bank_mask:0xf bound_ctrl:0
	v_fmac_f32_dpp v116, v120, -v228 row_shr:1 row_mask:0xf bank_mask:0xf bound_ctrl:0
	v_fmac_f32_dpp v117, v121, -v229 row_shr:1 row_mask:0xf bank_mask:0xf bound_ctrl:0
	v_fmac_f32_dpp v118, v122, -v230 row_shr:1 row_mask:0xf bank_mask:0xf bound_ctrl:0
	v_fmac_f32_dpp v119, v123, -v231 row_shr:1 row_mask:0xf bank_mask:0xf bound_ctrl:0
	v_fmac_f32_dpp v120, v120, v224 row_shr:1 row_mask:0xf bank_mask:0xf bound_ctrl:0
	v_fmac_f32_dpp v121, v121, v225 row_shr:1 row_mask:0xf bank_mask:0xf bound_ctrl:0
	v_fmac_f32_dpp v122, v122, v226 row_shr:1 row_mask:0xf bank_mask:0xf bound_ctrl:0
	v_fmac_f32_dpp v123, v123, v227 row_shr:1 row_mask:0xf bank_mask:0xf bound_ctrl:0
	v_fmac_f32_dpp v120, v232, v228 row_shr:1 row_mask:0xf bank_mask:0xf bound_ctrl:0
	v_fmac_f32_dpp v121, v233, v229 row_shr:1 row_mask:0xf bank_mask:0xf bound_ctrl:0
	v_fmac_f32_dpp v122, v234, v230 row_shr:1 row_mask:0xf bank_mask:0xf bound_ctrl:0
	v_fmac_f32_dpp v123, v235, v231 row_shr:1 row_mask:0xf bank_mask:0xf bound_ctrl:0
	ds_read_b128 v[224:227], v18 offset:576
	ds_read_b128 v[228:231], v18 offset:832
	s_waitcnt lgkmcnt(2)
	v_mov_b32_e32 v232, v92
	v_mov_b32_e32 v233, v93
	v_mov_b32_e32 v234, v94
	v_mov_b32_e32 v235, v95
	v_fmac_f32_dpp v92, v92, v188 row_shr:2 row_mask:0xf bank_mask:0xf bound_ctrl:0
	v_fmac_f32_dpp v93, v93, v189 row_shr:2 row_mask:0xf bank_mask:0xf bound_ctrl:0
	v_fmac_f32_dpp v94, v94, v190 row_shr:2 row_mask:0xf bank_mask:0xf bound_ctrl:0
	v_fmac_f32_dpp v95, v95, v191 row_shr:2 row_mask:0xf bank_mask:0xf bound_ctrl:0
	v_fmac_f32_dpp v92, v96, -v192 row_shr:2 row_mask:0xf bank_mask:0xf bound_ctrl:0
	v_fmac_f32_dpp v93, v97, -v193 row_shr:2 row_mask:0xf bank_mask:0xf bound_ctrl:0
	v_fmac_f32_dpp v94, v98, -v194 row_shr:2 row_mask:0xf bank_mask:0xf bound_ctrl:0
	v_fmac_f32_dpp v95, v99, -v195 row_shr:2 row_mask:0xf bank_mask:0xf bound_ctrl:0
	v_fmac_f32_dpp v96, v96, v188 row_shr:2 row_mask:0xf bank_mask:0xf bound_ctrl:0
	v_fmac_f32_dpp v97, v97, v189 row_shr:2 row_mask:0xf bank_mask:0xf bound_ctrl:0
	v_fmac_f32_dpp v98, v98, v190 row_shr:2 row_mask:0xf bank_mask:0xf bound_ctrl:0
	v_fmac_f32_dpp v99, v99, v191 row_shr:2 row_mask:0xf bank_mask:0xf bound_ctrl:0
	v_fmac_f32_dpp v96, v232, v192 row_shr:2 row_mask:0xf bank_mask:0xf bound_ctrl:0
	v_fmac_f32_dpp v97, v233, v193 row_shr:2 row_mask:0xf bank_mask:0xf bound_ctrl:0
	v_fmac_f32_dpp v98, v234, v194 row_shr:2 row_mask:0xf bank_mask:0xf bound_ctrl:0
	v_fmac_f32_dpp v99, v235, v195 row_shr:2 row_mask:0xf bank_mask:0xf bound_ctrl:0
	ds_read_b128 v[188:191], v18 offset:640
	ds_read_b128 v[192:195], v18 offset:896
	s_waitcnt lgkmcnt(2)
	v_mov_b32_e32 v232, v100
	v_mov_b32_e32 v233, v101
	v_mov_b32_e32 v234, v102
	v_mov_b32_e32 v235, v103
	v_fmac_f32_dpp v100, v100, v224 row_shr:2 row_mask:0xf bank_mask:0xf bound_ctrl:0
	v_fmac_f32_dpp v101, v101, v225 row_shr:2 row_mask:0xf bank_mask:0xf bound_ctrl:0
	v_fmac_f32_dpp v102, v102, v226 row_shr:2 row_mask:0xf bank_mask:0xf bound_ctrl:0
	v_fmac_f32_dpp v103, v103, v227 row_shr:2 row_mask:0xf bank_mask:0xf bound_ctrl:0
	v_fmac_f32_dpp v100, v104, -v228 row_shr:2 row_mask:0xf bank_mask:0xf bound_ctrl:0
	v_fmac_f32_dpp v101, v105, -v229 row_shr:2 row_mask:0xf bank_mask:0xf bound_ctrl:0
	v_fmac_f32_dpp v102, v106, -v230 row_shr:2 row_mask:0xf bank_mask:0xf bound_ctrl:0
	v_fmac_f32_dpp v103, v107, -v231 row_shr:2 row_mask:0xf bank_mask:0xf bound_ctrl:0
	v_fmac_f32_dpp v104, v104, v224 row_shr:2 row_mask:0xf bank_mask:0xf bound_ctrl:0
	v_fmac_f32_dpp v105, v105, v225 row_shr:2 row_mask:0xf bank_mask:0xf bound_ctrl:0
	v_fmac_f32_dpp v106, v106, v226 row_shr:2 row_mask:0xf bank_mask:0xf bound_ctrl:0
	v_fmac_f32_dpp v107, v107, v227 row_shr:2 row_mask:0xf bank_mask:0xf bound_ctrl:0
	v_fmac_f32_dpp v104, v232, v228 row_shr:2 row_mask:0xf bank_mask:0xf bound_ctrl:0
	v_fmac_f32_dpp v105, v233, v229 row_shr:2 row_mask:0xf bank_mask:0xf bound_ctrl:0
	v_fmac_f32_dpp v106, v234, v230 row_shr:2 row_mask:0xf bank_mask:0xf bound_ctrl:0
	v_fmac_f32_dpp v107, v235, v231 row_shr:2 row_mask:0xf bank_mask:0xf bound_ctrl:0
	ds_read_b128 v[224:227], v18 offset:704
	ds_read_b128 v[228:231], v18 offset:960
	s_waitcnt lgkmcnt(2)
	v_mov_b32_e32 v232, v108
	v_mov_b32_e32 v233, v109
	v_mov_b32_e32 v234, v110
	v_mov_b32_e32 v235, v111
	v_fmac_f32_dpp v108, v108, v188 row_shr:2 row_mask:0xf bank_mask:0xf bound_ctrl:0
	v_fmac_f32_dpp v109, v109, v189 row_shr:2 row_mask:0xf bank_mask:0xf bound_ctrl:0
	v_fmac_f32_dpp v110, v110, v190 row_shr:2 row_mask:0xf bank_mask:0xf bound_ctrl:0
	v_fmac_f32_dpp v111, v111, v191 row_shr:2 row_mask:0xf bank_mask:0xf bound_ctrl:0
	v_fmac_f32_dpp v108, v112, -v192 row_shr:2 row_mask:0xf bank_mask:0xf bound_ctrl:0
	v_fmac_f32_dpp v109, v113, -v193 row_shr:2 row_mask:0xf bank_mask:0xf bound_ctrl:0
	v_fmac_f32_dpp v110, v114, -v194 row_shr:2 row_mask:0xf bank_mask:0xf bound_ctrl:0
	v_fmac_f32_dpp v111, v115, -v195 row_shr:2 row_mask:0xf bank_mask:0xf bound_ctrl:0
	v_fmac_f32_dpp v112, v112, v188 row_shr:2 row_mask:0xf bank_mask:0xf bound_ctrl:0
	v_fmac_f32_dpp v113, v113, v189 row_shr:2 row_mask:0xf bank_mask:0xf bound_ctrl:0
	v_fmac_f32_dpp v114, v114, v190 row_shr:2 row_mask:0xf bank_mask:0xf bound_ctrl:0
	v_fmac_f32_dpp v115, v115, v191 row_shr:2 row_mask:0xf bank_mask:0xf bound_ctrl:0
	v_fmac_f32_dpp v112, v232, v192 row_shr:2 row_mask:0xf bank_mask:0xf bound_ctrl:0
	v_fmac_f32_dpp v113, v233, v193 row_shr:2 row_mask:0xf bank_mask:0xf bound_ctrl:0
	v_fmac_f32_dpp v114, v234, v194 row_shr:2 row_mask:0xf bank_mask:0xf bound_ctrl:0
	v_fmac_f32_dpp v115, v235, v195 row_shr:2 row_mask:0xf bank_mask:0xf bound_ctrl:0
	ds_read_b128 v[188:191], v18 offset:1024
	ds_read_b128 v[192:195], v18 offset:1280
	s_waitcnt lgkmcnt(2)
	v_mov_b32_e32 v232, v116
	v_mov_b32_e32 v233, v117
	v_mov_b32_e32 v234, v118
	v_mov_b32_e32 v235, v119
	v_fmac_f32_dpp v116, v116, v224 row_shr:2 row_mask:0xf bank_mask:0xf bound_ctrl:0
	v_fmac_f32_dpp v117, v117, v225 row_shr:2 row_mask:0xf bank_mask:0xf bound_ctrl:0
	v_fmac_f32_dpp v118, v118, v226 row_shr:2 row_mask:0xf bank_mask:0xf bound_ctrl:0
	v_fmac_f32_dpp v119, v119, v227 row_shr:2 row_mask:0xf bank_mask:0xf bound_ctrl:0
	v_fmac_f32_dpp v116, v120, -v228 row_shr:2 row_mask:0xf bank_mask:0xf bound_ctrl:0
	v_fmac_f32_dpp v117, v121, -v229 row_shr:2 row_mask:0xf bank_mask:0xf bound_ctrl:0
	v_fmac_f32_dpp v118, v122, -v230 row_shr:2 row_mask:0xf bank_mask:0xf bound_ctrl:0
	v_fmac_f32_dpp v119, v123, -v231 row_shr:2 row_mask:0xf bank_mask:0xf bound_ctrl:0
	v_fmac_f32_dpp v120, v120, v224 row_shr:2 row_mask:0xf bank_mask:0xf bound_ctrl:0
	v_fmac_f32_dpp v121, v121, v225 row_shr:2 row_mask:0xf bank_mask:0xf bound_ctrl:0
	v_fmac_f32_dpp v122, v122, v226 row_shr:2 row_mask:0xf bank_mask:0xf bound_ctrl:0
	v_fmac_f32_dpp v123, v123, v227 row_shr:2 row_mask:0xf bank_mask:0xf bound_ctrl:0
	v_fmac_f32_dpp v120, v232, v228 row_shr:2 row_mask:0xf bank_mask:0xf bound_ctrl:0
	v_fmac_f32_dpp v121, v233, v229 row_shr:2 row_mask:0xf bank_mask:0xf bound_ctrl:0
	v_fmac_f32_dpp v122, v234, v230 row_shr:2 row_mask:0xf bank_mask:0xf bound_ctrl:0
	v_fmac_f32_dpp v123, v235, v231 row_shr:2 row_mask:0xf bank_mask:0xf bound_ctrl:0
	ds_read_b128 v[224:227], v18 offset:1088
	ds_read_b128 v[228:231], v18 offset:1344
	s_waitcnt lgkmcnt(2)
	v_mov_b32_e32 v232, v92
	v_mov_b32_e32 v233, v93
	v_mov_b32_e32 v234, v94
	v_mov_b32_e32 v235, v95
	v_fmac_f32_dpp v92, v92, v188 row_shr:4 row_mask:0xf bank_mask:0xf bound_ctrl:0
	v_fmac_f32_dpp v93, v93, v189 row_shr:4 row_mask:0xf bank_mask:0xf bound_ctrl:0
	v_fmac_f32_dpp v94, v94, v190 row_shr:4 row_mask:0xf bank_mask:0xf bound_ctrl:0
	v_fmac_f32_dpp v95, v95, v191 row_shr:4 row_mask:0xf bank_mask:0xf bound_ctrl:0
	v_fmac_f32_dpp v92, v96, -v192 row_shr:4 row_mask:0xf bank_mask:0xf bound_ctrl:0
	v_fmac_f32_dpp v93, v97, -v193 row_shr:4 row_mask:0xf bank_mask:0xf bound_ctrl:0
	v_fmac_f32_dpp v94, v98, -v194 row_shr:4 row_mask:0xf bank_mask:0xf bound_ctrl:0
	v_fmac_f32_dpp v95, v99, -v195 row_shr:4 row_mask:0xf bank_mask:0xf bound_ctrl:0
	v_fmac_f32_dpp v96, v96, v188 row_shr:4 row_mask:0xf bank_mask:0xf bound_ctrl:0
	v_fmac_f32_dpp v97, v97, v189 row_shr:4 row_mask:0xf bank_mask:0xf bound_ctrl:0
	v_fmac_f32_dpp v98, v98, v190 row_shr:4 row_mask:0xf bank_mask:0xf bound_ctrl:0
	v_fmac_f32_dpp v99, v99, v191 row_shr:4 row_mask:0xf bank_mask:0xf bound_ctrl:0
	v_fmac_f32_dpp v96, v232, v192 row_shr:4 row_mask:0xf bank_mask:0xf bound_ctrl:0
	v_fmac_f32_dpp v97, v233, v193 row_shr:4 row_mask:0xf bank_mask:0xf bound_ctrl:0
	v_fmac_f32_dpp v98, v234, v194 row_shr:4 row_mask:0xf bank_mask:0xf bound_ctrl:0
	v_fmac_f32_dpp v99, v235, v195 row_shr:4 row_mask:0xf bank_mask:0xf bound_ctrl:0
	ds_read_b128 v[188:191], v18 offset:1152
	ds_read_b128 v[192:195], v18 offset:1408
	s_waitcnt lgkmcnt(2)
	v_mov_b32_e32 v232, v100
	v_mov_b32_e32 v233, v101
	v_mov_b32_e32 v234, v102
	v_mov_b32_e32 v235, v103
	v_fmac_f32_dpp v100, v100, v224 row_shr:4 row_mask:0xf bank_mask:0xf bound_ctrl:0
	v_fmac_f32_dpp v101, v101, v225 row_shr:4 row_mask:0xf bank_mask:0xf bound_ctrl:0
	v_fmac_f32_dpp v102, v102, v226 row_shr:4 row_mask:0xf bank_mask:0xf bound_ctrl:0
	v_fmac_f32_dpp v103, v103, v227 row_shr:4 row_mask:0xf bank_mask:0xf bound_ctrl:0
	v_fmac_f32_dpp v100, v104, -v228 row_shr:4 row_mask:0xf bank_mask:0xf bound_ctrl:0
	v_fmac_f32_dpp v101, v105, -v229 row_shr:4 row_mask:0xf bank_mask:0xf bound_ctrl:0
	v_fmac_f32_dpp v102, v106, -v230 row_shr:4 row_mask:0xf bank_mask:0xf bound_ctrl:0
	v_fmac_f32_dpp v103, v107, -v231 row_shr:4 row_mask:0xf bank_mask:0xf bound_ctrl:0
	v_fmac_f32_dpp v104, v104, v224 row_shr:4 row_mask:0xf bank_mask:0xf bound_ctrl:0
	v_fmac_f32_dpp v105, v105, v225 row_shr:4 row_mask:0xf bank_mask:0xf bound_ctrl:0
	v_fmac_f32_dpp v106, v106, v226 row_shr:4 row_mask:0xf bank_mask:0xf bound_ctrl:0
	v_fmac_f32_dpp v107, v107, v227 row_shr:4 row_mask:0xf bank_mask:0xf bound_ctrl:0
	v_fmac_f32_dpp v104, v232, v228 row_shr:4 row_mask:0xf bank_mask:0xf bound_ctrl:0
	v_fmac_f32_dpp v105, v233, v229 row_shr:4 row_mask:0xf bank_mask:0xf bound_ctrl:0
	v_fmac_f32_dpp v106, v234, v230 row_shr:4 row_mask:0xf bank_mask:0xf bound_ctrl:0
	v_fmac_f32_dpp v107, v235, v231 row_shr:4 row_mask:0xf bank_mask:0xf bound_ctrl:0
	ds_read_b128 v[224:227], v18 offset:1216
	ds_read_b128 v[228:231], v18 offset:1472
	s_waitcnt lgkmcnt(2)
	v_mov_b32_e32 v232, v108
	v_mov_b32_e32 v233, v109
	v_mov_b32_e32 v234, v110
	v_mov_b32_e32 v235, v111
	v_fmac_f32_dpp v108, v108, v188 row_shr:4 row_mask:0xf bank_mask:0xf bound_ctrl:0
	v_fmac_f32_dpp v109, v109, v189 row_shr:4 row_mask:0xf bank_mask:0xf bound_ctrl:0
	v_fmac_f32_dpp v110, v110, v190 row_shr:4 row_mask:0xf bank_mask:0xf bound_ctrl:0
	v_fmac_f32_dpp v111, v111, v191 row_shr:4 row_mask:0xf bank_mask:0xf bound_ctrl:0
	v_fmac_f32_dpp v108, v112, -v192 row_shr:4 row_mask:0xf bank_mask:0xf bound_ctrl:0
	v_fmac_f32_dpp v109, v113, -v193 row_shr:4 row_mask:0xf bank_mask:0xf bound_ctrl:0
	v_fmac_f32_dpp v110, v114, -v194 row_shr:4 row_mask:0xf bank_mask:0xf bound_ctrl:0
	v_fmac_f32_dpp v111, v115, -v195 row_shr:4 row_mask:0xf bank_mask:0xf bound_ctrl:0
	v_fmac_f32_dpp v112, v112, v188 row_shr:4 row_mask:0xf bank_mask:0xf bound_ctrl:0
	v_fmac_f32_dpp v113, v113, v189 row_shr:4 row_mask:0xf bank_mask:0xf bound_ctrl:0
	v_fmac_f32_dpp v114, v114, v190 row_shr:4 row_mask:0xf bank_mask:0xf bound_ctrl:0
	v_fmac_f32_dpp v115, v115, v191 row_shr:4 row_mask:0xf bank_mask:0xf bound_ctrl:0
	v_fmac_f32_dpp v112, v232, v192 row_shr:4 row_mask:0xf bank_mask:0xf bound_ctrl:0
	v_fmac_f32_dpp v113, v233, v193 row_shr:4 row_mask:0xf bank_mask:0xf bound_ctrl:0
	v_fmac_f32_dpp v114, v234, v194 row_shr:4 row_mask:0xf bank_mask:0xf bound_ctrl:0
	v_fmac_f32_dpp v115, v235, v195 row_shr:4 row_mask:0xf bank_mask:0xf bound_ctrl:0
	ds_read_b128 v[188:191], v18 offset:1536
	ds_read_b128 v[192:195], v18 offset:1792
	s_waitcnt lgkmcnt(2)
	v_mov_b32_e32 v232, v116
	v_mov_b32_e32 v233, v117
	v_mov_b32_e32 v234, v118
	v_mov_b32_e32 v235, v119
	v_fmac_f32_dpp v116, v116, v224 row_shr:4 row_mask:0xf bank_mask:0xf bound_ctrl:0
	v_fmac_f32_dpp v117, v117, v225 row_shr:4 row_mask:0xf bank_mask:0xf bound_ctrl:0
	v_fmac_f32_dpp v118, v118, v226 row_shr:4 row_mask:0xf bank_mask:0xf bound_ctrl:0
	v_fmac_f32_dpp v119, v119, v227 row_shr:4 row_mask:0xf bank_mask:0xf bound_ctrl:0
	v_fmac_f32_dpp v116, v120, -v228 row_shr:4 row_mask:0xf bank_mask:0xf bound_ctrl:0
	v_fmac_f32_dpp v117, v121, -v229 row_shr:4 row_mask:0xf bank_mask:0xf bound_ctrl:0
	v_fmac_f32_dpp v118, v122, -v230 row_shr:4 row_mask:0xf bank_mask:0xf bound_ctrl:0
	v_fmac_f32_dpp v119, v123, -v231 row_shr:4 row_mask:0xf bank_mask:0xf bound_ctrl:0
	v_fmac_f32_dpp v120, v120, v224 row_shr:4 row_mask:0xf bank_mask:0xf bound_ctrl:0
	v_fmac_f32_dpp v121, v121, v225 row_shr:4 row_mask:0xf bank_mask:0xf bound_ctrl:0
	v_fmac_f32_dpp v122, v122, v226 row_shr:4 row_mask:0xf bank_mask:0xf bound_ctrl:0
	v_fmac_f32_dpp v123, v123, v227 row_shr:4 row_mask:0xf bank_mask:0xf bound_ctrl:0
	v_fmac_f32_dpp v120, v232, v228 row_shr:4 row_mask:0xf bank_mask:0xf bound_ctrl:0
	v_fmac_f32_dpp v121, v233, v229 row_shr:4 row_mask:0xf bank_mask:0xf bound_ctrl:0
	v_fmac_f32_dpp v122, v234, v230 row_shr:4 row_mask:0xf bank_mask:0xf bound_ctrl:0
	v_fmac_f32_dpp v123, v235, v231 row_shr:4 row_mask:0xf bank_mask:0xf bound_ctrl:0
	ds_read_b128 v[224:227], v18 offset:1600
	ds_read_b128 v[228:231], v18 offset:1856
	s_waitcnt lgkmcnt(2)
	v_mov_b32_e32 v232, v92
	v_mov_b32_e32 v233, v93
	v_mov_b32_e32 v234, v94
	v_mov_b32_e32 v235, v95
	v_fmac_f32_dpp v92, v92, v188 row_shr:8 row_mask:0xf bank_mask:0xf bound_ctrl:0
	v_fmac_f32_dpp v93, v93, v189 row_shr:8 row_mask:0xf bank_mask:0xf bound_ctrl:0
	v_fmac_f32_dpp v94, v94, v190 row_shr:8 row_mask:0xf bank_mask:0xf bound_ctrl:0
	v_fmac_f32_dpp v95, v95, v191 row_shr:8 row_mask:0xf bank_mask:0xf bound_ctrl:0
	v_fmac_f32_dpp v92, v96, -v192 row_shr:8 row_mask:0xf bank_mask:0xf bound_ctrl:0
	v_fmac_f32_dpp v93, v97, -v193 row_shr:8 row_mask:0xf bank_mask:0xf bound_ctrl:0
	v_fmac_f32_dpp v94, v98, -v194 row_shr:8 row_mask:0xf bank_mask:0xf bound_ctrl:0
	v_fmac_f32_dpp v95, v99, -v195 row_shr:8 row_mask:0xf bank_mask:0xf bound_ctrl:0
	v_fmac_f32_dpp v96, v96, v188 row_shr:8 row_mask:0xf bank_mask:0xf bound_ctrl:0
	v_fmac_f32_dpp v97, v97, v189 row_shr:8 row_mask:0xf bank_mask:0xf bound_ctrl:0
	v_fmac_f32_dpp v98, v98, v190 row_shr:8 row_mask:0xf bank_mask:0xf bound_ctrl:0
	v_fmac_f32_dpp v99, v99, v191 row_shr:8 row_mask:0xf bank_mask:0xf bound_ctrl:0
	v_fmac_f32_dpp v96, v232, v192 row_shr:8 row_mask:0xf bank_mask:0xf bound_ctrl:0
	v_fmac_f32_dpp v97, v233, v193 row_shr:8 row_mask:0xf bank_mask:0xf bound_ctrl:0
	v_fmac_f32_dpp v98, v234, v194 row_shr:8 row_mask:0xf bank_mask:0xf bound_ctrl:0
	v_fmac_f32_dpp v99, v235, v195 row_shr:8 row_mask:0xf bank_mask:0xf bound_ctrl:0
	ds_read_b128 v[188:191], v18 offset:1664
	ds_read_b128 v[192:195], v18 offset:1920
	s_waitcnt lgkmcnt(2)
	v_mov_b32_e32 v232, v100
	v_mov_b32_e32 v233, v101
	v_mov_b32_e32 v234, v102
	v_mov_b32_e32 v235, v103
	v_fmac_f32_dpp v100, v100, v224 row_shr:8 row_mask:0xf bank_mask:0xf bound_ctrl:0
	v_fmac_f32_dpp v101, v101, v225 row_shr:8 row_mask:0xf bank_mask:0xf bound_ctrl:0
	v_fmac_f32_dpp v102, v102, v226 row_shr:8 row_mask:0xf bank_mask:0xf bound_ctrl:0
	v_fmac_f32_dpp v103, v103, v227 row_shr:8 row_mask:0xf bank_mask:0xf bound_ctrl:0
	v_fmac_f32_dpp v100, v104, -v228 row_shr:8 row_mask:0xf bank_mask:0xf bound_ctrl:0
	v_fmac_f32_dpp v101, v105, -v229 row_shr:8 row_mask:0xf bank_mask:0xf bound_ctrl:0
	v_fmac_f32_dpp v102, v106, -v230 row_shr:8 row_mask:0xf bank_mask:0xf bound_ctrl:0
	v_fmac_f32_dpp v103, v107, -v231 row_shr:8 row_mask:0xf bank_mask:0xf bound_ctrl:0
	v_fmac_f32_dpp v104, v104, v224 row_shr:8 row_mask:0xf bank_mask:0xf bound_ctrl:0
	v_fmac_f32_dpp v105, v105, v225 row_shr:8 row_mask:0xf bank_mask:0xf bound_ctrl:0
	v_fmac_f32_dpp v106, v106, v226 row_shr:8 row_mask:0xf bank_mask:0xf bound_ctrl:0
	v_fmac_f32_dpp v107, v107, v227 row_shr:8 row_mask:0xf bank_mask:0xf bound_ctrl:0
	v_fmac_f32_dpp v104, v232, v228 row_shr:8 row_mask:0xf bank_mask:0xf bound_ctrl:0
	v_fmac_f32_dpp v105, v233, v229 row_shr:8 row_mask:0xf bank_mask:0xf bound_ctrl:0
	v_fmac_f32_dpp v106, v234, v230 row_shr:8 row_mask:0xf bank_mask:0xf bound_ctrl:0
	v_fmac_f32_dpp v107, v235, v231 row_shr:8 row_mask:0xf bank_mask:0xf bound_ctrl:0
	ds_read_b128 v[224:227], v18 offset:1728
	ds_read_b128 v[228:231], v18 offset:1984
	s_waitcnt lgkmcnt(2)
	v_mov_b32_e32 v232, v108
	v_mov_b32_e32 v233, v109
	v_mov_b32_e32 v234, v110
	v_mov_b32_e32 v235, v111
	v_fmac_f32_dpp v108, v108, v188 row_shr:8 row_mask:0xf bank_mask:0xf bound_ctrl:0
	v_fmac_f32_dpp v109, v109, v189 row_shr:8 row_mask:0xf bank_mask:0xf bound_ctrl:0
	v_fmac_f32_dpp v110, v110, v190 row_shr:8 row_mask:0xf bank_mask:0xf bound_ctrl:0
	v_fmac_f32_dpp v111, v111, v191 row_shr:8 row_mask:0xf bank_mask:0xf bound_ctrl:0
	v_fmac_f32_dpp v108, v112, -v192 row_shr:8 row_mask:0xf bank_mask:0xf bound_ctrl:0
	v_fmac_f32_dpp v109, v113, -v193 row_shr:8 row_mask:0xf bank_mask:0xf bound_ctrl:0
	v_fmac_f32_dpp v110, v114, -v194 row_shr:8 row_mask:0xf bank_mask:0xf bound_ctrl:0
	v_fmac_f32_dpp v111, v115, -v195 row_shr:8 row_mask:0xf bank_mask:0xf bound_ctrl:0
	v_fmac_f32_dpp v112, v112, v188 row_shr:8 row_mask:0xf bank_mask:0xf bound_ctrl:0
	v_fmac_f32_dpp v113, v113, v189 row_shr:8 row_mask:0xf bank_mask:0xf bound_ctrl:0
	v_fmac_f32_dpp v114, v114, v190 row_shr:8 row_mask:0xf bank_mask:0xf bound_ctrl:0
	v_fmac_f32_dpp v115, v115, v191 row_shr:8 row_mask:0xf bank_mask:0xf bound_ctrl:0
	v_fmac_f32_dpp v112, v232, v192 row_shr:8 row_mask:0xf bank_mask:0xf bound_ctrl:0
	v_fmac_f32_dpp v113, v233, v193 row_shr:8 row_mask:0xf bank_mask:0xf bound_ctrl:0
	v_fmac_f32_dpp v114, v234, v194 row_shr:8 row_mask:0xf bank_mask:0xf bound_ctrl:0
	v_fmac_f32_dpp v115, v235, v195 row_shr:8 row_mask:0xf bank_mask:0xf bound_ctrl:0
	s_waitcnt lgkmcnt(0)
	v_mov_b32_e32 v232, v116
	v_mov_b32_e32 v233, v117
	v_mov_b32_e32 v234, v118
	v_mov_b32_e32 v235, v119
	v_fmac_f32_dpp v116, v116, v224 row_shr:8 row_mask:0xf bank_mask:0xf bound_ctrl:0
	v_fmac_f32_dpp v117, v117, v225 row_shr:8 row_mask:0xf bank_mask:0xf bound_ctrl:0
	v_fmac_f32_dpp v118, v118, v226 row_shr:8 row_mask:0xf bank_mask:0xf bound_ctrl:0
	v_fmac_f32_dpp v119, v119, v227 row_shr:8 row_mask:0xf bank_mask:0xf bound_ctrl:0
	v_fmac_f32_dpp v116, v120, -v228 row_shr:8 row_mask:0xf bank_mask:0xf bound_ctrl:0
	v_fmac_f32_dpp v117, v121, -v229 row_shr:8 row_mask:0xf bank_mask:0xf bound_ctrl:0
	v_fmac_f32_dpp v118, v122, -v230 row_shr:8 row_mask:0xf bank_mask:0xf bound_ctrl:0
	v_fmac_f32_dpp v119, v123, -v231 row_shr:8 row_mask:0xf bank_mask:0xf bound_ctrl:0
	v_fmac_f32_dpp v120, v120, v224 row_shr:8 row_mask:0xf bank_mask:0xf bound_ctrl:0
	v_fmac_f32_dpp v121, v121, v225 row_shr:8 row_mask:0xf bank_mask:0xf bound_ctrl:0
	v_fmac_f32_dpp v122, v122, v226 row_shr:8 row_mask:0xf bank_mask:0xf bound_ctrl:0
	v_fmac_f32_dpp v123, v123, v227 row_shr:8 row_mask:0xf bank_mask:0xf bound_ctrl:0
	v_fmac_f32_dpp v120, v232, v228 row_shr:8 row_mask:0xf bank_mask:0xf bound_ctrl:0
	v_fmac_f32_dpp v121, v233, v229 row_shr:8 row_mask:0xf bank_mask:0xf bound_ctrl:0
	v_fmac_f32_dpp v122, v234, v230 row_shr:8 row_mask:0xf bank_mask:0xf bound_ctrl:0
	v_fmac_f32_dpp v123, v235, v231 row_shr:8 row_mask:0xf bank_mask:0xf bound_ctrl:0
	s_nop 1
	v_mov_b32_dpp v124, v92 row_newbcast:15 row_mask:0xf bank_mask:0xf
	v_mov_b32_dpp v125, v96 row_newbcast:15 row_mask:0xf bank_mask:0xf
	v_mov_b32_dpp v126, v93 row_newbcast:15 row_mask:0xf bank_mask:0xf
	v_mov_b32_dpp v127, v97 row_newbcast:15 row_mask:0xf bank_mask:0xf
	v_mov_b32_dpp v128, v94 row_newbcast:15 row_mask:0xf bank_mask:0xf
	v_mov_b32_dpp v129, v98 row_newbcast:15 row_mask:0xf bank_mask:0xf
	v_mov_b32_dpp v130, v95 row_newbcast:15 row_mask:0xf bank_mask:0xf
	v_mov_b32_dpp v131, v99 row_newbcast:15 row_mask:0xf bank_mask:0xf
	v_mov_b32_dpp v140, v100 row_newbcast:15 row_mask:0xf bank_mask:0xf
	v_mov_b32_dpp v141, v104 row_newbcast:15 row_mask:0xf bank_mask:0xf
	v_mov_b32_dpp v142, v101 row_newbcast:15 row_mask:0xf bank_mask:0xf
	v_mov_b32_dpp v143, v105 row_newbcast:15 row_mask:0xf bank_mask:0xf
	v_mov_b32_dpp v144, v102 row_newbcast:15 row_mask:0xf bank_mask:0xf
	v_mov_b32_dpp v145, v106 row_newbcast:15 row_mask:0xf bank_mask:0xf
	v_mov_b32_dpp v146, v103 row_newbcast:15 row_mask:0xf bank_mask:0xf
	v_mov_b32_dpp v147, v107 row_newbcast:15 row_mask:0xf bank_mask:0xf
	v_mov_b32_dpp v148, v108 row_newbcast:15 row_mask:0xf bank_mask:0xf
	v_mov_b32_dpp v149, v112 row_newbcast:15 row_mask:0xf bank_mask:0xf
	v_mov_b32_dpp v150, v109 row_newbcast:15 row_mask:0xf bank_mask:0xf
	v_mov_b32_dpp v151, v113 row_newbcast:15 row_mask:0xf bank_mask:0xf
	v_mov_b32_dpp v152, v110 row_newbcast:15 row_mask:0xf bank_mask:0xf
	v_mov_b32_dpp v153, v114 row_newbcast:15 row_mask:0xf bank_mask:0xf
	v_mov_b32_dpp v154, v111 row_newbcast:15 row_mask:0xf bank_mask:0xf
	v_mov_b32_dpp v155, v115 row_newbcast:15 row_mask:0xf bank_mask:0xf
	v_mov_b32_dpp v156, v116 row_newbcast:15 row_mask:0xf bank_mask:0xf
	v_mov_b32_dpp v157, v120 row_newbcast:15 row_mask:0xf bank_mask:0xf
	v_mov_b32_dpp v158, v117 row_newbcast:15 row_mask:0xf bank_mask:0xf
	v_mov_b32_dpp v159, v121 row_newbcast:15 row_mask:0xf bank_mask:0xf
	v_mov_b32_dpp v168, v118 row_newbcast:15 row_mask:0xf bank_mask:0xf
	v_mov_b32_dpp v169, v122 row_newbcast:15 row_mask:0xf bank_mask:0xf
	v_mov_b32_dpp v170, v119 row_newbcast:15 row_mask:0xf bank_mask:0xf
	v_mov_b32_dpp v171, v123 row_newbcast:15 row_mask:0xf bank_mask:0xf
	s_waitcnt vmcnt(7)
	s_waitcnt vmcnt(6)
	s_waitcnt vmcnt(5)
	s_waitcnt vmcnt(4)
	s_waitcnt vmcnt(3)
	s_waitcnt vmcnt(2)
	s_waitcnt vmcnt(1)
	s_waitcnt vmcnt(0)
	v_xor_b32_e32 v64, 0x80000000, v64
	v_xor_b32_e32 v65, 0x80000000, v65
	v_xor_b32_e32 v66, 0x80000000, v66
	v_xor_b32_e32 v67, 0x80000000, v67
	v_xor_b32_e32 v72, 0x80000000, v72
	v_xor_b32_e32 v73, 0x80000000, v73
	v_xor_b32_e32 v74, 0x80000000, v74
	v_xor_b32_e32 v75, 0x80000000, v75
	v_xor_b32_e32 v80, 0x80000000, v80
	v_xor_b32_e32 v81, 0x80000000, v81
	v_xor_b32_e32 v82, 0x80000000, v82
	v_xor_b32_e32 v83, 0x80000000, v83
	v_xor_b32_e32 v88, 0x80000000, v88
	v_xor_b32_e32 v89, 0x80000000, v89
	v_xor_b32_e32 v90, 0x80000000, v90
	v_xor_b32_e32 v91, 0x80000000, v91
	s_nop 1
	v_mfma_f32_16x16x4_f32 v[172:175], v92, v60, 0
	v_mfma_f32_16x16x4_f32 v[180:183], v96, v64, 0
	v_mfma_f32_16x16x4_f32 v[172:175], v93, v61, v[172:175]
	v_mfma_f32_16x16x4_f32 v[180:183], v97, v65, v[180:183]
	v_mfma_f32_16x16x4_f32 v[172:175], v94, v62, v[172:175]
	v_mfma_f32_16x16x4_f32 v[180:183], v98, v66, v[180:183]
	v_mfma_f32_16x16x4_f32 v[172:175], v95, v63, v[172:175]
	v_mfma_f32_16x16x4_f32 v[180:183], v99, v67, v[180:183]
	v_mfma_f32_16x16x4_f32 v[172:175], v100, v68, v[172:175]
	v_mfma_f32_16x16x4_f32 v[180:183], v104, v72, v[180:183]
	v_mfma_f32_16x16x4_f32 v[172:175], v101, v69, v[172:175]
	v_mfma_f32_16x16x4_f32 v[180:183], v105, v73, v[180:183]
	v_mfma_f32_16x16x4_f32 v[172:175], v102, v70, v[172:175]
	v_mfma_f32_16x16x4_f32 v[180:183], v106, v74, v[180:183]
	v_mfma_f32_16x16x4_f32 v[172:175], v103, v71, v[172:175]
	v_mfma_f32_16x16x4_f32 v[180:183], v107, v75, v[180:183]
	v_mfma_f32_16x16x4_f32 v[172:175], v108, v76, v[172:175]
	v_mfma_f32_16x16x4_f32 v[180:183], v112, v80, v[180:183]
	v_mfma_f32_16x16x4_f32 v[172:175], v109, v77, v[172:175]
	v_mfma_f32_16x16x4_f32 v[180:183], v113, v81, v[180:183]
	v_mfma_f32_16x16x4_f32 v[172:175], v110, v78, v[172:175]
	v_mfma_f32_16x16x4_f32 v[180:183], v114, v82, v[180:183]
	v_mfma_f32_16x16x4_f32 v[172:175], v111, v79, v[172:175]
	v_mfma_f32_16x16x4_f32 v[180:183], v115, v83, v[180:183]
	v_mfma_f32_16x16x4_f32 v[172:175], v116, v84, v[172:175]
	v_mfma_f32_16x16x4_f32 v[180:183], v120, v88, v[180:183]
	v_mfma_f32_16x16x4_f32 v[172:175], v117, v85, v[172:175]
	v_mfma_f32_16x16x4_f32 v[180:183], v121, v89, v[180:183]
	v_mfma_f32_16x16x4_f32 v[172:175], v118, v86, v[172:175]
	v_mfma_f32_16x16x4_f32 v[180:183], v122, v90, v[180:183]
	v_mfma_f32_16x16x4_f32 v[172:175], v119, v87, v[172:175]
	v_mfma_f32_16x16x4_f32 v[180:183], v123, v91, v[180:183]
	v_mfma_f32_16x16x4_f32 v[92:95], v28, v24, 0
	v_mfma_f32_16x16x4_f32 v[96:99], v29, v24, 0
	v_mfma_f32_16x16x4_f32 v[100:103], v36, v24, 0
	v_mfma_f32_16x16x4_f32 v[104:107], v37, v24, 0
	v_mfma_f32_16x16x4_f32 v[108:111], v44, v24, 0
	v_mfma_f32_16x16x4_f32 v[112:115], v45, v24, 0
	v_mfma_f32_16x16x4_f32 v[116:119], v52, v24, 0
	v_mfma_f32_16x16x4_f32 v[120:123], v53, v24, 0
	v_mfma_f32_16x16x4_f32 v[92:95], v30, v25, v[92:95]
	v_mfma_f32_16x16x4_f32 v[96:99], v31, v25, v[96:99]
	v_mfma_f32_16x16x4_f32 v[100:103], v38, v25, v[100:103]
	v_mfma_f32_16x16x4_f32 v[104:107], v39, v25, v[104:107]
	v_mfma_f32_16x16x4_f32 v[108:111], v46, v25, v[108:111]
	v_mfma_f32_16x16x4_f32 v[112:115], v47, v25, v[112:115]
	v_mfma_f32_16x16x4_f32 v[116:119], v54, v25, v[116:119]
	v_mfma_f32_16x16x4_f32 v[120:123], v55, v25, v[120:123]
	v_mfma_f32_16x16x4_f32 v[92:95], v32, v26, v[92:95]
	v_mfma_f32_16x16x4_f32 v[96:99], v33, v26, v[96:99]
	v_mfma_f32_16x16x4_f32 v[100:103], v40, v26, v[100:103]
	v_mfma_f32_16x16x4_f32 v[104:107], v41, v26, v[104:107]
	v_mfma_f32_16x16x4_f32 v[108:111], v48, v26, v[108:111]
	v_mfma_f32_16x16x4_f32 v[112:115], v49, v26, v[112:115]
	v_mfma_f32_16x16x4_f32 v[116:119], v56, v26, v[116:119]
	v_mfma_f32_16x16x4_f32 v[120:123], v57, v26, v[120:123]
	v_mfma_f32_16x16x4_f32 v[92:95], v34, v27, v[92:95]
	v_mfma_f32_16x16x4_f32 v[96:99], v35, v27, v[96:99]
	v_mfma_f32_16x16x4_f32 v[100:103], v42, v27, v[100:103]
	v_mfma_f32_16x16x4_f32 v[104:107], v43, v27, v[104:107]
	v_mfma_f32_16x16x4_f32 v[108:111], v50, v27, v[108:111]
	v_mfma_f32_16x16x4_f32 v[112:115], v51, v27, v[112:115]
	v_mfma_f32_16x16x4_f32 v[116:119], v58, v27, v[116:119]
	v_mfma_f32_16x16x4_f32 v[120:123], v59, v27, v[120:123]
	ds_read_b128 v[188:191], v18 offset:0
	ds_read_b128 v[192:195], v18 offset:256
	s_nop 9
	ds_read_b128 v[224:227], v18 offset:64
	ds_read_b128 v[228:231], v18 offset:320
	s_waitcnt lgkmcnt(2)
	s_mov_b64 exec, s[52:53]
	v_fmac_f32_e32 v92, v188, v124
	v_fmac_f32_e32 v93, v189, v126
	v_fmac_f32_e32 v94, v190, v128
	v_fmac_f32_e32 v95, v191, v130
	v_fma_f32 v92, -v192, v125, v92
	v_fma_f32 v93, -v193, v127, v93
	v_fma_f32 v94, -v194, v129, v94
	v_fma_f32 v95, -v195, v131, v95
	v_fmac_f32_e32 v96, v188, v125
	v_fmac_f32_e32 v97, v189, v127
	v_fmac_f32_e32 v98, v190, v129
	v_fmac_f32_e32 v99, v191, v131
	v_fmac_f32_e32 v96, v192, v124
	v_fmac_f32_e32 v97, v193, v126
	v_fmac_f32_e32 v98, v194, v128
	v_fmac_f32_e32 v99, v195, v130
	s_mov_b64 exec, -1
	v_mov_b32_e32 v232, v92
	v_mov_b32_e32 v233, v93
	v_mov_b32_e32 v234, v94
	v_mov_b32_e32 v235, v95
	s_nop 1
	v_fmac_f32_dpp v92, v92, v188 row_shr:1 row_mask:0xf bank_mask:0xf bound_ctrl:0
	v_fmac_f32_dpp v93, v93, v189 row_shr:1 row_mask:0xf bank_mask:0xf bound_ctrl:0
	v_fmac_f32_dpp v94, v94, v190 row_shr:1 row_mask:0xf bank_mask:0xf bound_ctrl:0
	v_fmac_f32_dpp v95, v95, v191 row_shr:1 row_mask:0xf bank_mask:0xf bound_ctrl:0
	v_fmac_f32_dpp v92, v96, -v192 row_shr:1 row_mask:0xf bank_mask:0xf bound_ctrl:0
	v_fmac_f32_dpp v93, v97, -v193 row_shr:1 row_mask:0xf bank_mask:0xf bound_ctrl:0
	v_fmac_f32_dpp v94, v98, -v194 row_shr:1 row_mask:0xf bank_mask:0xf bound_ctrl:0
	v_fmac_f32_dpp v95, v99, -v195 row_shr:1 row_mask:0xf bank_mask:0xf bound_ctrl:0
	v_fmac_f32_dpp v96, v96, v188 row_shr:1 row_mask:0xf bank_mask:0xf bound_ctrl:0
	v_fmac_f32_dpp v97, v97, v189 row_shr:1 row_mask:0xf bank_mask:0xf bound_ctrl:0
	v_fmac_f32_dpp v98, v98, v190 row_shr:1 row_mask:0xf bank_mask:0xf bound_ctrl:0
	v_fmac_f32_dpp v99, v99, v191 row_shr:1 row_mask:0xf bank_mask:0xf bound_ctrl:0
	v_fmac_f32_dpp v96, v232, v192 row_shr:1 row_mask:0xf bank_mask:0xf bound_ctrl:0
	v_fmac_f32_dpp v97, v233, v193 row_shr:1 row_mask:0xf bank_mask:0xf bound_ctrl:0
	v_fmac_f32_dpp v98, v234, v194 row_shr:1 row_mask:0xf bank_mask:0xf bound_ctrl:0
	v_fmac_f32_dpp v99, v235, v195 row_shr:1 row_mask:0xf bank_mask:0xf bound_ctrl:0
	ds_read_b128 v[188:191], v18 offset:128
	ds_read_b128 v[192:195], v18 offset:384
	s_waitcnt lgkmcnt(2)
	s_mov_b64 exec, s[52:53]
	v_fmac_f32_e32 v100, v224, v140
	v_fmac_f32_e32 v101, v225, v142
	v_fmac_f32_e32 v102, v226, v144
	v_fmac_f32_e32 v103, v227, v146
	v_fma_f32 v100, -v228, v141, v100
	v_fma_f32 v101, -v229, v143, v101
	v_fma_f32 v102, -v230, v145, v102
	v_fma_f32 v103, -v231, v147, v103
	v_fmac_f32_e32 v104, v224, v141
	v_fmac_f32_e32 v105, v225, v143
	v_fmac_f32_e32 v106, v226, v145
	v_fmac_f32_e32 v107, v227, v147
	v_fmac_f32_e32 v104, v228, v140
	v_fmac_f32_e32 v105, v229, v142
	v_fmac_f32_e32 v106, v230, v144
	v_fmac_f32_e32 v107, v231, v146
	s_mov_b64 exec, -1
	v_mov_b32_e32 v232, v100
	v_mov_b32_e32 v233, v101
	v_mov_b32_e32 v234, v102
	v_mov_b32_e32 v235, v103
	s_nop 1
	v_fmac_f32_dpp v100, v100, v224 row_shr:1 row_mask:0xf bank_mask:0xf bound_ctrl:0
	v_fmac_f32_dpp v101, v101, v225 row_shr:1 row_mask:0xf bank_mask:0xf bound_ctrl:0
	v_fmac_f32_dpp v102, v102, v226 row_shr:1 row_mask:0xf bank_mask:0xf bound_ctrl:0
	v_fmac_f32_dpp v103, v103, v227 row_shr:1 row_mask:0xf bank_mask:0xf bound_ctrl:0
	v_fmac_f32_dpp v100, v104, -v228 row_shr:1 row_mask:0xf bank_mask:0xf bound_ctrl:0
	v_fmac_f32_dpp v101, v105, -v229 row_shr:1 row_mask:0xf bank_mask:0xf bound_ctrl:0
	v_fmac_f32_dpp v102, v106, -v230 row_shr:1 row_mask:0xf bank_mask:0xf bound_ctrl:0
	v_fmac_f32_dpp v103, v107, -v231 row_shr:1 row_mask:0xf bank_mask:0xf bound_ctrl:0
	v_fmac_f32_dpp v104, v104, v224 row_shr:1 row_mask:0xf bank_mask:0xf bound_ctrl:0
	v_fmac_f32_dpp v105, v105, v225 row_shr:1 row_mask:0xf bank_mask:0xf bound_ctrl:0
	v_fmac_f32_dpp v106, v106, v226 row_shr:1 row_mask:0xf bank_mask:0xf bound_ctrl:0
	v_fmac_f32_dpp v107, v107, v227 row_shr:1 row_mask:0xf bank_mask:0xf bound_ctrl:0
	v_fmac_f32_dpp v104, v232, v228 row_shr:1 row_mask:0xf bank_mask:0xf bound_ctrl:0
	v_fmac_f32_dpp v105, v233, v229 row_shr:1 row_mask:0xf bank_mask:0xf bound_ctrl:0
	v_fmac_f32_dpp v106, v234, v230 row_shr:1 row_mask:0xf bank_mask:0xf bound_ctrl:0
	v_fmac_f32_dpp v107, v235, v231 row_shr:1 row_mask:0xf bank_mask:0xf bound_ctrl:0
	ds_read_b128 v[224:227], v18 offset:192
	ds_read_b128 v[228:231], v18 offset:448
	s_waitcnt lgkmcnt(2)
	s_mov_b64 exec, s[52:53]
	v_fmac_f32_e32 v108, v188, v148
	v_fmac_f32_e32 v109, v189, v150
	v_fmac_f32_e32 v110, v190, v152
	v_fmac_f32_e32 v111, v191, v154
	v_fma_f32 v108, -v192, v149, v108
	v_fma_f32 v109, -v193, v151, v109
	v_fma_f32 v110, -v194, v153, v110
	v_fma_f32 v111, -v195, v155, v111
	v_fmac_f32_e32 v112, v188, v149
	v_fmac_f32_e32 v113, v189, v151
	v_fmac_f32_e32 v114, v190, v153
	v_fmac_f32_e32 v115, v191, v155
	v_fmac_f32_e32 v112, v192, v148
	v_fmac_f32_e32 v113, v193, v150
	v_fmac_f32_e32 v114, v194, v152
	v_fmac_f32_e32 v115, v195, v154
	s_mov_b64 exec, -1
	v_mov_b32_e32 v232, v108
	v_mov_b32_e32 v233, v109
	v_mov_b32_e32 v234, v110
	v_mov_b32_e32 v235, v111
	s_nop 1
	v_fmac_f32_dpp v108, v108, v188 row_shr:1 row_mask:0xf bank_mask:0xf bound_ctrl:0
	v_fmac_f32_dpp v109, v109, v189 row_shr:1 row_mask:0xf bank_mask:0xf bound_ctrl:0
	v_fmac_f32_dpp v110, v110, v190 row_shr:1 row_mask:0xf bank_mask:0xf bound_ctrl:0
	v_fmac_f32_dpp v111, v111, v191 row_shr:1 row_mask:0xf bank_mask:0xf bound_ctrl:0
	v_fmac_f32_dpp v108, v112, -v192 row_shr:1 row_mask:0xf bank_mask:0xf bound_ctrl:0
	v_fmac_f32_dpp v109, v113, -v193 row_shr:1 row_mask:0xf bank_mask:0xf bound_ctrl:0
	v_fmac_f32_dpp v110, v114, -v194 row_shr:1 row_mask:0xf bank_mask:0xf bound_ctrl:0
	v_fmac_f32_dpp v111, v115, -v195 row_shr:1 row_mask:0xf bank_mask:0xf bound_ctrl:0
	v_fmac_f32_dpp v112, v112, v188 row_shr:1 row_mask:0xf bank_mask:0xf bound_ctrl:0
	v_fmac_f32_dpp v113, v113, v189 row_shr:1 row_mask:0xf bank_mask:0xf bound_ctrl:0
	v_fmac_f32_dpp v114, v114, v190 row_shr:1 row_mask:0xf bank_mask:0xf bound_ctrl:0
	v_fmac_f32_dpp v115, v115, v191 row_shr:1 row_mask:0xf bank_mask:0xf bound_ctrl:0
	v_fmac_f32_dpp v112, v232, v192 row_shr:1 row_mask:0xf bank_mask:0xf bound_ctrl:0
	v_fmac_f32_dpp v113, v233, v193 row_shr:1 row_mask:0xf bank_mask:0xf bound_ctrl:0
	v_fmac_f32_dpp v114, v234, v194 row_shr:1 row_mask:0xf bank_mask:0xf bound_ctrl:0
	v_fmac_f32_dpp v115, v235, v195 row_shr:1 row_mask:0xf bank_mask:0xf bound_ctrl:0
	ds_read_b128 v[188:191], v18 offset:512
	ds_read_b128 v[192:195], v18 offset:768
	s_waitcnt lgkmcnt(2)
	s_mov_b64 exec, s[52:53]
	v_fmac_f32_e32 v116, v224, v156
	v_fmac_f32_e32 v117, v225, v158
	v_fmac_f32_e32 v118, v226, v168
	v_fmac_f32_e32 v119, v227, v170
	v_fma_f32 v116, -v228, v157, v116
	v_fma_f32 v117, -v229, v159, v117
	v_fma_f32 v118, -v230, v169, v118
	v_fma_f32 v119, -v231, v171, v119
	v_fmac_f32_e32 v120, v224, v157
	v_fmac_f32_e32 v121, v225, v159
	v_fmac_f32_e32 v122, v226, v169
	v_fmac_f32_e32 v123, v227, v171
	v_fmac_f32_e32 v120, v228, v156
	v_fmac_f32_e32 v121, v229, v158
	v_fmac_f32_e32 v122, v230, v168
	v_fmac_f32_e32 v123, v231, v170
	s_mov_b64 exec, -1
	v_mov_b32_e32 v232, v116
	v_mov_b32_e32 v233, v117
	v_mov_b32_e32 v234, v118
	v_mov_b32_e32 v235, v119
	s_nop 1
	v_fmac_f32_dpp v116, v116, v224 row_shr:1 row_mask:0xf bank_mask:0xf bound_ctrl:0
	v_fmac_f32_dpp v117, v117, v225 row_shr:1 row_mask:0xf bank_mask:0xf bound_ctrl:0
	v_fmac_f32_dpp v118, v118, v226 row_shr:1 row_mask:0xf bank_mask:0xf bound_ctrl:0
	v_fmac_f32_dpp v119, v119, v227 row_shr:1 row_mask:0xf bank_mask:0xf bound_ctrl:0
	v_fmac_f32_dpp v116, v120, -v228 row_shr:1 row_mask:0xf bank_mask:0xf bound_ctrl:0
	v_fmac_f32_dpp v117, v121, -v229 row_shr:1 row_mask:0xf bank_mask:0xf bound_ctrl:0
	v_fmac_f32_dpp v118, v122, -v230 row_shr:1 row_mask:0xf bank_mask:0xf bound_ctrl:0
	v_fmac_f32_dpp v119, v123, -v231 row_shr:1 row_mask:0xf bank_mask:0xf bound_ctrl:0
	v_fmac_f32_dpp v120, v120, v224 row_shr:1 row_mask:0xf bank_mask:0xf bound_ctrl:0
	v_fmac_f32_dpp v121, v121, v225 row_shr:1 row_mask:0xf bank_mask:0xf bound_ctrl:0
	v_fmac_f32_dpp v122, v122, v226 row_shr:1 row_mask:0xf bank_mask:0xf bound_ctrl:0
	v_fmac_f32_dpp v123, v123, v227 row_shr:1 row_mask:0xf bank_mask:0xf bound_ctrl:0
	v_fmac_f32_dpp v120, v232, v228 row_shr:1 row_mask:0xf bank_mask:0xf bound_ctrl:0
	v_fmac_f32_dpp v121, v233, v229 row_shr:1 row_mask:0xf bank_mask:0xf bound_ctrl:0
	v_fmac_f32_dpp v122, v234, v230 row_shr:1 row_mask:0xf bank_mask:0xf bound_ctrl:0
	v_fmac_f32_dpp v123, v235, v231 row_shr:1 row_mask:0xf bank_mask:0xf bound_ctrl:0
	ds_read_b128 v[224:227], v18 offset:576
	ds_read_b128 v[228:231], v18 offset:832
	s_waitcnt lgkmcnt(2)
	v_mov_b32_e32 v232, v92
	v_mov_b32_e32 v233, v93
	v_mov_b32_e32 v234, v94
	v_mov_b32_e32 v235, v95
	v_fmac_f32_dpp v92, v92, v188 row_shr:2 row_mask:0xf bank_mask:0xf bound_ctrl:0
	v_fmac_f32_dpp v93, v93, v189 row_shr:2 row_mask:0xf bank_mask:0xf bound_ctrl:0
	v_fmac_f32_dpp v94, v94, v190 row_shr:2 row_mask:0xf bank_mask:0xf bound_ctrl:0
	v_fmac_f32_dpp v95, v95, v191 row_shr:2 row_mask:0xf bank_mask:0xf bound_ctrl:0
	v_fmac_f32_dpp v92, v96, -v192 row_shr:2 row_mask:0xf bank_mask:0xf bound_ctrl:0
	v_fmac_f32_dpp v93, v97, -v193 row_shr:2 row_mask:0xf bank_mask:0xf bound_ctrl:0
	v_fmac_f32_dpp v94, v98, -v194 row_shr:2 row_mask:0xf bank_mask:0xf bound_ctrl:0
	v_fmac_f32_dpp v95, v99, -v195 row_shr:2 row_mask:0xf bank_mask:0xf bound_ctrl:0
	v_fmac_f32_dpp v96, v96, v188 row_shr:2 row_mask:0xf bank_mask:0xf bound_ctrl:0
	v_fmac_f32_dpp v97, v97, v189 row_shr:2 row_mask:0xf bank_mask:0xf bound_ctrl:0
	v_fmac_f32_dpp v98, v98, v190 row_shr:2 row_mask:0xf bank_mask:0xf bound_ctrl:0
	v_fmac_f32_dpp v99, v99, v191 row_shr:2 row_mask:0xf bank_mask:0xf bound_ctrl:0
	v_fmac_f32_dpp v96, v232, v192 row_shr:2 row_mask:0xf bank_mask:0xf bound_ctrl:0
	v_fmac_f32_dpp v97, v233, v193 row_shr:2 row_mask:0xf bank_mask:0xf bound_ctrl:0
	v_fmac_f32_dpp v98, v234, v194 row_shr:2 row_mask:0xf bank_mask:0xf bound_ctrl:0
	v_fmac_f32_dpp v99, v235, v195 row_shr:2 row_mask:0xf bank_mask:0xf bound_ctrl:0
	ds_read_b128 v[188:191], v18 offset:640
	ds_read_b128 v[192:195], v18 offset:896
	s_waitcnt lgkmcnt(2)
	v_mov_b32_e32 v232, v100
	v_mov_b32_e32 v233, v101
	v_mov_b32_e32 v234, v102
	v_mov_b32_e32 v235, v103
	v_fmac_f32_dpp v100, v100, v224 row_shr:2 row_mask:0xf bank_mask:0xf bound_ctrl:0
	v_fmac_f32_dpp v101, v101, v225 row_shr:2 row_mask:0xf bank_mask:0xf bound_ctrl:0
	v_fmac_f32_dpp v102, v102, v226 row_shr:2 row_mask:0xf bank_mask:0xf bound_ctrl:0
	v_fmac_f32_dpp v103, v103, v227 row_shr:2 row_mask:0xf bank_mask:0xf bound_ctrl:0
	v_fmac_f32_dpp v100, v104, -v228 row_shr:2 row_mask:0xf bank_mask:0xf bound_ctrl:0
	v_fmac_f32_dpp v101, v105, -v229 row_shr:2 row_mask:0xf bank_mask:0xf bound_ctrl:0
	v_fmac_f32_dpp v102, v106, -v230 row_shr:2 row_mask:0xf bank_mask:0xf bound_ctrl:0
	v_fmac_f32_dpp v103, v107, -v231 row_shr:2 row_mask:0xf bank_mask:0xf bound_ctrl:0
	v_fmac_f32_dpp v104, v104, v224 row_shr:2 row_mask:0xf bank_mask:0xf bound_ctrl:0
	v_fmac_f32_dpp v105, v105, v225 row_shr:2 row_mask:0xf bank_mask:0xf bound_ctrl:0
	v_fmac_f32_dpp v106, v106, v226 row_shr:2 row_mask:0xf bank_mask:0xf bound_ctrl:0
	v_fmac_f32_dpp v107, v107, v227 row_shr:2 row_mask:0xf bank_mask:0xf bound_ctrl:0
	v_fmac_f32_dpp v104, v232, v228 row_shr:2 row_mask:0xf bank_mask:0xf bound_ctrl:0
	v_fmac_f32_dpp v105, v233, v229 row_shr:2 row_mask:0xf bank_mask:0xf bound_ctrl:0
	v_fmac_f32_dpp v106, v234, v230 row_shr:2 row_mask:0xf bank_mask:0xf bound_ctrl:0
	v_fmac_f32_dpp v107, v235, v231 row_shr:2 row_mask:0xf bank_mask:0xf bound_ctrl:0
	ds_read_b128 v[224:227], v18 offset:704
	ds_read_b128 v[228:231], v18 offset:960
	s_waitcnt lgkmcnt(2)
	v_mov_b32_e32 v232, v108
	v_mov_b32_e32 v233, v109
	v_mov_b32_e32 v234, v110
	v_mov_b32_e32 v235, v111
	v_fmac_f32_dpp v108, v108, v188 row_shr:2 row_mask:0xf bank_mask:0xf bound_ctrl:0
	v_fmac_f32_dpp v109, v109, v189 row_shr:2 row_mask:0xf bank_mask:0xf bound_ctrl:0
	v_fmac_f32_dpp v110, v110, v190 row_shr:2 row_mask:0xf bank_mask:0xf bound_ctrl:0
	v_fmac_f32_dpp v111, v111, v191 row_shr:2 row_mask:0xf bank_mask:0xf bound_ctrl:0
	v_fmac_f32_dpp v108, v112, -v192 row_shr:2 row_mask:0xf bank_mask:0xf bound_ctrl:0
	v_fmac_f32_dpp v109, v113, -v193 row_shr:2 row_mask:0xf bank_mask:0xf bound_ctrl:0
	v_fmac_f32_dpp v110, v114, -v194 row_shr:2 row_mask:0xf bank_mask:0xf bound_ctrl:0
	v_fmac_f32_dpp v111, v115, -v195 row_shr:2 row_mask:0xf bank_mask:0xf bound_ctrl:0
	v_fmac_f32_dpp v112, v112, v188 row_shr:2 row_mask:0xf bank_mask:0xf bound_ctrl:0
	v_fmac_f32_dpp v113, v113, v189 row_shr:2 row_mask:0xf bank_mask:0xf bound_ctrl:0
	v_fmac_f32_dpp v114, v114, v190 row_shr:2 row_mask:0xf bank_mask:0xf bound_ctrl:0
	v_fmac_f32_dpp v115, v115, v191 row_shr:2 row_mask:0xf bank_mask:0xf bound_ctrl:0
	v_fmac_f32_dpp v112, v232, v192 row_shr:2 row_mask:0xf bank_mask:0xf bound_ctrl:0
	v_fmac_f32_dpp v113, v233, v193 row_shr:2 row_mask:0xf bank_mask:0xf bound_ctrl:0
	v_fmac_f32_dpp v114, v234, v194 row_shr:2 row_mask:0xf bank_mask:0xf bound_ctrl:0
	v_fmac_f32_dpp v115, v235, v195 row_shr:2 row_mask:0xf bank_mask:0xf bound_ctrl:0
	ds_read_b128 v[188:191], v18 offset:1024
	ds_read_b128 v[192:195], v18 offset:1280
	s_waitcnt lgkmcnt(2)
	v_mov_b32_e32 v232, v116
	v_mov_b32_e32 v233, v117
	v_mov_b32_e32 v234, v118
	v_mov_b32_e32 v235, v119
	v_fmac_f32_dpp v116, v116, v224 row_shr:2 row_mask:0xf bank_mask:0xf bound_ctrl:0
	v_fmac_f32_dpp v117, v117, v225 row_shr:2 row_mask:0xf bank_mask:0xf bound_ctrl:0
	v_fmac_f32_dpp v118, v118, v226 row_shr:2 row_mask:0xf bank_mask:0xf bound_ctrl:0
	v_fmac_f32_dpp v119, v119, v227 row_shr:2 row_mask:0xf bank_mask:0xf bound_ctrl:0
	v_fmac_f32_dpp v116, v120, -v228 row_shr:2 row_mask:0xf bank_mask:0xf bound_ctrl:0
	v_fmac_f32_dpp v117, v121, -v229 row_shr:2 row_mask:0xf bank_mask:0xf bound_ctrl:0
	v_fmac_f32_dpp v118, v122, -v230 row_shr:2 row_mask:0xf bank_mask:0xf bound_ctrl:0
	v_fmac_f32_dpp v119, v123, -v231 row_shr:2 row_mask:0xf bank_mask:0xf bound_ctrl:0
	v_fmac_f32_dpp v120, v120, v224 row_shr:2 row_mask:0xf bank_mask:0xf bound_ctrl:0
	v_fmac_f32_dpp v121, v121, v225 row_shr:2 row_mask:0xf bank_mask:0xf bound_ctrl:0
	v_fmac_f32_dpp v122, v122, v226 row_shr:2 row_mask:0xf bank_mask:0xf bound_ctrl:0
	v_fmac_f32_dpp v123, v123, v227 row_shr:2 row_mask:0xf bank_mask:0xf bound_ctrl:0
	v_fmac_f32_dpp v120, v232, v228 row_shr:2 row_mask:0xf bank_mask:0xf bound_ctrl:0
	v_fmac_f32_dpp v121, v233, v229 row_shr:2 row_mask:0xf bank_mask:0xf bound_ctrl:0
	v_fmac_f32_dpp v122, v234, v230 row_shr:2 row_mask:0xf bank_mask:0xf bound_ctrl:0
	v_fmac_f32_dpp v123, v235, v231 row_shr:2 row_mask:0xf bank_mask:0xf bound_ctrl:0
	ds_read_b128 v[224:227], v18 offset:1088
	ds_read_b128 v[228:231], v18 offset:1344
	s_waitcnt lgkmcnt(2)
	v_mov_b32_e32 v232, v92
	v_mov_b32_e32 v233, v93
	v_mov_b32_e32 v234, v94
	v_mov_b32_e32 v235, v95
	v_fmac_f32_dpp v92, v92, v188 row_shr:4 row_mask:0xf bank_mask:0xf bound_ctrl:0
	v_fmac_f32_dpp v93, v93, v189 row_shr:4 row_mask:0xf bank_mask:0xf bound_ctrl:0
	v_fmac_f32_dpp v94, v94, v190 row_shr:4 row_mask:0xf bank_mask:0xf bound_ctrl:0
	v_fmac_f32_dpp v95, v95, v191 row_shr:4 row_mask:0xf bank_mask:0xf bound_ctrl:0
	v_fmac_f32_dpp v92, v96, -v192 row_shr:4 row_mask:0xf bank_mask:0xf bound_ctrl:0
	v_fmac_f32_dpp v93, v97, -v193 row_shr:4 row_mask:0xf bank_mask:0xf bound_ctrl:0
	v_fmac_f32_dpp v94, v98, -v194 row_shr:4 row_mask:0xf bank_mask:0xf bound_ctrl:0
	v_fmac_f32_dpp v95, v99, -v195 row_shr:4 row_mask:0xf bank_mask:0xf bound_ctrl:0
	v_fmac_f32_dpp v96, v96, v188 row_shr:4 row_mask:0xf bank_mask:0xf bound_ctrl:0
	v_fmac_f32_dpp v97, v97, v189 row_shr:4 row_mask:0xf bank_mask:0xf bound_ctrl:0
	v_fmac_f32_dpp v98, v98, v190 row_shr:4 row_mask:0xf bank_mask:0xf bound_ctrl:0
	v_fmac_f32_dpp v99, v99, v191 row_shr:4 row_mask:0xf bank_mask:0xf bound_ctrl:0
	v_fmac_f32_dpp v96, v232, v192 row_shr:4 row_mask:0xf bank_mask:0xf bound_ctrl:0
	v_fmac_f32_dpp v97, v233, v193 row_shr:4 row_mask:0xf bank_mask:0xf bound_ctrl:0
	v_fmac_f32_dpp v98, v234, v194 row_shr:4 row_mask:0xf bank_mask:0xf bound_ctrl:0
	v_fmac_f32_dpp v99, v235, v195 row_shr:4 row_mask:0xf bank_mask:0xf bound_ctrl:0
	ds_read_b128 v[188:191], v18 offset:1152
	ds_read_b128 v[192:195], v18 offset:1408
	s_waitcnt lgkmcnt(2)
	v_mov_b32_e32 v232, v100
	v_mov_b32_e32 v233, v101
	v_mov_b32_e32 v234, v102
	v_mov_b32_e32 v235, v103
	v_fmac_f32_dpp v100, v100, v224 row_shr:4 row_mask:0xf bank_mask:0xf bound_ctrl:0
	v_fmac_f32_dpp v101, v101, v225 row_shr:4 row_mask:0xf bank_mask:0xf bound_ctrl:0
	v_fmac_f32_dpp v102, v102, v226 row_shr:4 row_mask:0xf bank_mask:0xf bound_ctrl:0
	v_fmac_f32_dpp v103, v103, v227 row_shr:4 row_mask:0xf bank_mask:0xf bound_ctrl:0
	v_fmac_f32_dpp v100, v104, -v228 row_shr:4 row_mask:0xf bank_mask:0xf bound_ctrl:0
	v_fmac_f32_dpp v101, v105, -v229 row_shr:4 row_mask:0xf bank_mask:0xf bound_ctrl:0
	v_fmac_f32_dpp v102, v106, -v230 row_shr:4 row_mask:0xf bank_mask:0xf bound_ctrl:0
	v_fmac_f32_dpp v103, v107, -v231 row_shr:4 row_mask:0xf bank_mask:0xf bound_ctrl:0
	v_fmac_f32_dpp v104, v104, v224 row_shr:4 row_mask:0xf bank_mask:0xf bound_ctrl:0
	v_fmac_f32_dpp v105, v105, v225 row_shr:4 row_mask:0xf bank_mask:0xf bound_ctrl:0
	v_fmac_f32_dpp v106, v106, v226 row_shr:4 row_mask:0xf bank_mask:0xf bound_ctrl:0
	v_fmac_f32_dpp v107, v107, v227 row_shr:4 row_mask:0xf bank_mask:0xf bound_ctrl:0
	v_fmac_f32_dpp v104, v232, v228 row_shr:4 row_mask:0xf bank_mask:0xf bound_ctrl:0
	v_fmac_f32_dpp v105, v233, v229 row_shr:4 row_mask:0xf bank_mask:0xf bound_ctrl:0
	v_fmac_f32_dpp v106, v234, v230 row_shr:4 row_mask:0xf bank_mask:0xf bound_ctrl:0
	v_fmac_f32_dpp v107, v235, v231 row_shr:4 row_mask:0xf bank_mask:0xf bound_ctrl:0
	ds_read_b128 v[224:227], v18 offset:1216
	ds_read_b128 v[228:231], v18 offset:1472
	s_waitcnt lgkmcnt(2)
	v_mov_b32_e32 v232, v108
	v_mov_b32_e32 v233, v109
	v_mov_b32_e32 v234, v110
	v_mov_b32_e32 v235, v111
	v_fmac_f32_dpp v108, v108, v188 row_shr:4 row_mask:0xf bank_mask:0xf bound_ctrl:0
	v_fmac_f32_dpp v109, v109, v189 row_shr:4 row_mask:0xf bank_mask:0xf bound_ctrl:0
	v_fmac_f32_dpp v110, v110, v190 row_shr:4 row_mask:0xf bank_mask:0xf bound_ctrl:0
	v_fmac_f32_dpp v111, v111, v191 row_shr:4 row_mask:0xf bank_mask:0xf bound_ctrl:0
	v_fmac_f32_dpp v108, v112, -v192 row_shr:4 row_mask:0xf bank_mask:0xf bound_ctrl:0
	v_fmac_f32_dpp v109, v113, -v193 row_shr:4 row_mask:0xf bank_mask:0xf bound_ctrl:0
	v_fmac_f32_dpp v110, v114, -v194 row_shr:4 row_mask:0xf bank_mask:0xf bound_ctrl:0
	v_fmac_f32_dpp v111, v115, -v195 row_shr:4 row_mask:0xf bank_mask:0xf bound_ctrl:0
	v_fmac_f32_dpp v112, v112, v188 row_shr:4 row_mask:0xf bank_mask:0xf bound_ctrl:0
	v_fmac_f32_dpp v113, v113, v189 row_shr:4 row_mask:0xf bank_mask:0xf bound_ctrl:0
	v_fmac_f32_dpp v114, v114, v190 row_shr:4 row_mask:0xf bank_mask:0xf bound_ctrl:0
	v_fmac_f32_dpp v115, v115, v191 row_shr:4 row_mask:0xf bank_mask:0xf bound_ctrl:0
	v_fmac_f32_dpp v112, v232, v192 row_shr:4 row_mask:0xf bank_mask:0xf bound_ctrl:0
	v_fmac_f32_dpp v113, v233, v193 row_shr:4 row_mask:0xf bank_mask:0xf bound_ctrl:0
	v_fmac_f32_dpp v114, v234, v194 row_shr:4 row_mask:0xf bank_mask:0xf bound_ctrl:0
	v_fmac_f32_dpp v115, v235, v195 row_shr:4 row_mask:0xf bank_mask:0xf bound_ctrl:0
	ds_read_b128 v[188:191], v18 offset:1536
	ds_read_b128 v[192:195], v18 offset:1792
	s_waitcnt lgkmcnt(2)
	v_mov_b32_e32 v232, v116
	v_mov_b32_e32 v233, v117
	v_mov_b32_e32 v234, v118
	v_mov_b32_e32 v235, v119
	v_fmac_f32_dpp v116, v116, v224 row_shr:4 row_mask:0xf bank_mask:0xf bound_ctrl:0
	v_fmac_f32_dpp v117, v117, v225 row_shr:4 row_mask:0xf bank_mask:0xf bound_ctrl:0
	v_fmac_f32_dpp v118, v118, v226 row_shr:4 row_mask:0xf bank_mask:0xf bound_ctrl:0
	v_fmac_f32_dpp v119, v119, v227 row_shr:4 row_mask:0xf bank_mask:0xf bound_ctrl:0
	v_fmac_f32_dpp v116, v120, -v228 row_shr:4 row_mask:0xf bank_mask:0xf bound_ctrl:0
	v_fmac_f32_dpp v117, v121, -v229 row_shr:4 row_mask:0xf bank_mask:0xf bound_ctrl:0
	v_fmac_f32_dpp v118, v122, -v230 row_shr:4 row_mask:0xf bank_mask:0xf bound_ctrl:0
	v_fmac_f32_dpp v119, v123, -v231 row_shr:4 row_mask:0xf bank_mask:0xf bound_ctrl:0
	v_fmac_f32_dpp v120, v120, v224 row_shr:4 row_mask:0xf bank_mask:0xf bound_ctrl:0
	v_fmac_f32_dpp v121, v121, v225 row_shr:4 row_mask:0xf bank_mask:0xf bound_ctrl:0
	v_fmac_f32_dpp v122, v122, v226 row_shr:4 row_mask:0xf bank_mask:0xf bound_ctrl:0
	v_fmac_f32_dpp v123, v123, v227 row_shr:4 row_mask:0xf bank_mask:0xf bound_ctrl:0
	v_fmac_f32_dpp v120, v232, v228 row_shr:4 row_mask:0xf bank_mask:0xf bound_ctrl:0
	v_fmac_f32_dpp v121, v233, v229 row_shr:4 row_mask:0xf bank_mask:0xf bound_ctrl:0
	v_fmac_f32_dpp v122, v234, v230 row_shr:4 row_mask:0xf bank_mask:0xf bound_ctrl:0
	v_fmac_f32_dpp v123, v235, v231 row_shr:4 row_mask:0xf bank_mask:0xf bound_ctrl:0
	ds_read_b128 v[224:227], v18 offset:1600
	ds_read_b128 v[228:231], v18 offset:1856
	s_waitcnt lgkmcnt(2)
	v_mov_b32_e32 v232, v92
	v_mov_b32_e32 v233, v93
	v_mov_b32_e32 v234, v94
	v_mov_b32_e32 v235, v95
	v_fmac_f32_dpp v92, v92, v188 row_shr:8 row_mask:0xf bank_mask:0xf bound_ctrl:0
	v_fmac_f32_dpp v93, v93, v189 row_shr:8 row_mask:0xf bank_mask:0xf bound_ctrl:0
	v_fmac_f32_dpp v94, v94, v190 row_shr:8 row_mask:0xf bank_mask:0xf bound_ctrl:0
	v_fmac_f32_dpp v95, v95, v191 row_shr:8 row_mask:0xf bank_mask:0xf bound_ctrl:0
	v_fmac_f32_dpp v92, v96, -v192 row_shr:8 row_mask:0xf bank_mask:0xf bound_ctrl:0
	v_fmac_f32_dpp v93, v97, -v193 row_shr:8 row_mask:0xf bank_mask:0xf bound_ctrl:0
	v_fmac_f32_dpp v94, v98, -v194 row_shr:8 row_mask:0xf bank_mask:0xf bound_ctrl:0
	v_fmac_f32_dpp v95, v99, -v195 row_shr:8 row_mask:0xf bank_mask:0xf bound_ctrl:0
	v_fmac_f32_dpp v96, v96, v188 row_shr:8 row_mask:0xf bank_mask:0xf bound_ctrl:0
	v_fmac_f32_dpp v97, v97, v189 row_shr:8 row_mask:0xf bank_mask:0xf bound_ctrl:0
	v_fmac_f32_dpp v98, v98, v190 row_shr:8 row_mask:0xf bank_mask:0xf bound_ctrl:0
	v_fmac_f32_dpp v99, v99, v191 row_shr:8 row_mask:0xf bank_mask:0xf bound_ctrl:0
	v_fmac_f32_dpp v96, v232, v192 row_shr:8 row_mask:0xf bank_mask:0xf bound_ctrl:0
	v_fmac_f32_dpp v97, v233, v193 row_shr:8 row_mask:0xf bank_mask:0xf bound_ctrl:0
	v_fmac_f32_dpp v98, v234, v194 row_shr:8 row_mask:0xf bank_mask:0xf bound_ctrl:0
	v_fmac_f32_dpp v99, v235, v195 row_shr:8 row_mask:0xf bank_mask:0xf bound_ctrl:0
	ds_read_b128 v[188:191], v18 offset:1664
	ds_read_b128 v[192:195], v18 offset:1920
	s_waitcnt lgkmcnt(2)
	v_mov_b32_e32 v232, v100
	v_mov_b32_e32 v233, v101
	v_mov_b32_e32 v234, v102
	v_mov_b32_e32 v235, v103
	v_fmac_f32_dpp v100, v100, v224 row_shr:8 row_mask:0xf bank_mask:0xf bound_ctrl:0
	v_fmac_f32_dpp v101, v101, v225 row_shr:8 row_mask:0xf bank_mask:0xf bound_ctrl:0
	v_fmac_f32_dpp v102, v102, v226 row_shr:8 row_mask:0xf bank_mask:0xf bound_ctrl:0
	v_fmac_f32_dpp v103, v103, v227 row_shr:8 row_mask:0xf bank_mask:0xf bound_ctrl:0
	v_fmac_f32_dpp v100, v104, -v228 row_shr:8 row_mask:0xf bank_mask:0xf bound_ctrl:0
	v_fmac_f32_dpp v101, v105, -v229 row_shr:8 row_mask:0xf bank_mask:0xf bound_ctrl:0
	v_fmac_f32_dpp v102, v106, -v230 row_shr:8 row_mask:0xf bank_mask:0xf bound_ctrl:0
	v_fmac_f32_dpp v103, v107, -v231 row_shr:8 row_mask:0xf bank_mask:0xf bound_ctrl:0
	v_fmac_f32_dpp v104, v104, v224 row_shr:8 row_mask:0xf bank_mask:0xf bound_ctrl:0
	v_fmac_f32_dpp v105, v105, v225 row_shr:8 row_mask:0xf bank_mask:0xf bound_ctrl:0
	v_fmac_f32_dpp v106, v106, v226 row_shr:8 row_mask:0xf bank_mask:0xf bound_ctrl:0
	v_fmac_f32_dpp v107, v107, v227 row_shr:8 row_mask:0xf bank_mask:0xf bound_ctrl:0
	v_fmac_f32_dpp v104, v232, v228 row_shr:8 row_mask:0xf bank_mask:0xf bound_ctrl:0
	v_fmac_f32_dpp v105, v233, v229 row_shr:8 row_mask:0xf bank_mask:0xf bound_ctrl:0
	v_fmac_f32_dpp v106, v234, v230 row_shr:8 row_mask:0xf bank_mask:0xf bound_ctrl:0
	v_fmac_f32_dpp v107, v235, v231 row_shr:8 row_mask:0xf bank_mask:0xf bound_ctrl:0
	ds_read_b128 v[224:227], v18 offset:1728
	ds_read_b128 v[228:231], v18 offset:1984
	s_waitcnt lgkmcnt(2)
	v_mov_b32_e32 v232, v108
	v_mov_b32_e32 v233, v109
	v_mov_b32_e32 v234, v110
	v_mov_b32_e32 v235, v111
	v_fmac_f32_dpp v108, v108, v188 row_shr:8 row_mask:0xf bank_mask:0xf bound_ctrl:0
	v_fmac_f32_dpp v109, v109, v189 row_shr:8 row_mask:0xf bank_mask:0xf bound_ctrl:0
	v_fmac_f32_dpp v110, v110, v190 row_shr:8 row_mask:0xf bank_mask:0xf bound_ctrl:0
	v_fmac_f32_dpp v111, v111, v191 row_shr:8 row_mask:0xf bank_mask:0xf bound_ctrl:0
	v_fmac_f32_dpp v108, v112, -v192 row_shr:8 row_mask:0xf bank_mask:0xf bound_ctrl:0
	v_fmac_f32_dpp v109, v113, -v193 row_shr:8 row_mask:0xf bank_mask:0xf bound_ctrl:0
	v_fmac_f32_dpp v110, v114, -v194 row_shr:8 row_mask:0xf bank_mask:0xf bound_ctrl:0
	v_fmac_f32_dpp v111, v115, -v195 row_shr:8 row_mask:0xf bank_mask:0xf bound_ctrl:0
	v_fmac_f32_dpp v112, v112, v188 row_shr:8 row_mask:0xf bank_mask:0xf bound_ctrl:0
	v_fmac_f32_dpp v113, v113, v189 row_shr:8 row_mask:0xf bank_mask:0xf bound_ctrl:0
	v_fmac_f32_dpp v114, v114, v190 row_shr:8 row_mask:0xf bank_mask:0xf bound_ctrl:0
	v_fmac_f32_dpp v115, v115, v191 row_shr:8 row_mask:0xf bank_mask:0xf bound_ctrl:0
	v_fmac_f32_dpp v112, v232, v192 row_shr:8 row_mask:0xf bank_mask:0xf bound_ctrl:0
	v_fmac_f32_dpp v113, v233, v193 row_shr:8 row_mask:0xf bank_mask:0xf bound_ctrl:0
	v_fmac_f32_dpp v114, v234, v194 row_shr:8 row_mask:0xf bank_mask:0xf bound_ctrl:0
	v_fmac_f32_dpp v115, v235, v195 row_shr:8 row_mask:0xf bank_mask:0xf bound_ctrl:0
	s_waitcnt lgkmcnt(0)
	v_mov_b32_e32 v232, v116
	v_mov_b32_e32 v233, v117
	v_mov_b32_e32 v234, v118
	v_mov_b32_e32 v235, v119
	v_fmac_f32_dpp v116, v116, v224 row_shr:8 row_mask:0xf bank_mask:0xf bound_ctrl:0
	v_fmac_f32_dpp v117, v117, v225 row_shr:8 row_mask:0xf bank_mask:0xf bound_ctrl:0
	v_fmac_f32_dpp v118, v118, v226 row_shr:8 row_mask:0xf bank_mask:0xf bound_ctrl:0
	v_fmac_f32_dpp v119, v119, v227 row_shr:8 row_mask:0xf bank_mask:0xf bound_ctrl:0
	v_fmac_f32_dpp v116, v120, -v228 row_shr:8 row_mask:0xf bank_mask:0xf bound_ctrl:0
	v_fmac_f32_dpp v117, v121, -v229 row_shr:8 row_mask:0xf bank_mask:0xf bound_ctrl:0
	v_fmac_f32_dpp v118, v122, -v230 row_shr:8 row_mask:0xf bank_mask:0xf bound_ctrl:0
	v_fmac_f32_dpp v119, v123, -v231 row_shr:8 row_mask:0xf bank_mask:0xf bound_ctrl:0
	v_fmac_f32_dpp v120, v120, v224 row_shr:8 row_mask:0xf bank_mask:0xf bound_ctrl:0
	v_fmac_f32_dpp v121, v121, v225 row_shr:8 row_mask:0xf bank_mask:0xf bound_ctrl:0
	v_fmac_f32_dpp v122, v122, v226 row_shr:8 row_mask:0xf bank_mask:0xf bound_ctrl:0
	v_fmac_f32_dpp v123, v123, v227 row_shr:8 row_mask:0xf bank_mask:0xf bound_ctrl:0
	v_fmac_f32_dpp v120, v232, v228 row_shr:8 row_mask:0xf bank_mask:0xf bound_ctrl:0
	v_fmac_f32_dpp v121, v233, v229 row_shr:8 row_mask:0xf bank_mask:0xf bound_ctrl:0
	v_fmac_f32_dpp v122, v234, v230 row_shr:8 row_mask:0xf bank_mask:0xf bound_ctrl:0
	v_fmac_f32_dpp v123, v235, v231 row_shr:8 row_mask:0xf bank_mask:0xf bound_ctrl:0
	s_nop 1
	v_mov_b32_dpp v124, v92 row_newbcast:15 row_mask:0xf bank_mask:0xf
	v_mov_b32_dpp v125, v96 row_newbcast:15 row_mask:0xf bank_mask:0xf
	v_mov_b32_dpp v126, v93 row_newbcast:15 row_mask:0xf bank_mask:0xf
	v_mov_b32_dpp v127, v97 row_newbcast:15 row_mask:0xf bank_mask:0xf
	v_mov_b32_dpp v128, v94 row_newbcast:15 row_mask:0xf bank_mask:0xf
	v_mov_b32_dpp v129, v98 row_newbcast:15 row_mask:0xf bank_mask:0xf
	v_mov_b32_dpp v130, v95 row_newbcast:15 row_mask:0xf bank_mask:0xf
	v_mov_b32_dpp v131, v99 row_newbcast:15 row_mask:0xf bank_mask:0xf
	v_mov_b32_dpp v140, v100 row_newbcast:15 row_mask:0xf bank_mask:0xf
	v_mov_b32_dpp v141, v104 row_newbcast:15 row_mask:0xf bank_mask:0xf
	v_mov_b32_dpp v142, v101 row_newbcast:15 row_mask:0xf bank_mask:0xf
	v_mov_b32_dpp v143, v105 row_newbcast:15 row_mask:0xf bank_mask:0xf
	v_mov_b32_dpp v144, v102 row_newbcast:15 row_mask:0xf bank_mask:0xf
	v_mov_b32_dpp v145, v106 row_newbcast:15 row_mask:0xf bank_mask:0xf
	v_mov_b32_dpp v146, v103 row_newbcast:15 row_mask:0xf bank_mask:0xf
	v_mov_b32_dpp v147, v107 row_newbcast:15 row_mask:0xf bank_mask:0xf
	v_mov_b32_dpp v148, v108 row_newbcast:15 row_mask:0xf bank_mask:0xf
	v_mov_b32_dpp v149, v112 row_newbcast:15 row_mask:0xf bank_mask:0xf
	v_mov_b32_dpp v150, v109 row_newbcast:15 row_mask:0xf bank_mask:0xf
	v_mov_b32_dpp v151, v113 row_newbcast:15 row_mask:0xf bank_mask:0xf
	v_mov_b32_dpp v152, v110 row_newbcast:15 row_mask:0xf bank_mask:0xf
	v_mov_b32_dpp v153, v114 row_newbcast:15 row_mask:0xf bank_mask:0xf
	v_mov_b32_dpp v154, v111 row_newbcast:15 row_mask:0xf bank_mask:0xf
	v_mov_b32_dpp v155, v115 row_newbcast:15 row_mask:0xf bank_mask:0xf
	v_mov_b32_dpp v156, v116 row_newbcast:15 row_mask:0xf bank_mask:0xf
	v_mov_b32_dpp v157, v120 row_newbcast:15 row_mask:0xf bank_mask:0xf
	v_mov_b32_dpp v158, v117 row_newbcast:15 row_mask:0xf bank_mask:0xf
	v_mov_b32_dpp v159, v121 row_newbcast:15 row_mask:0xf bank_mask:0xf
	v_mov_b32_dpp v168, v118 row_newbcast:15 row_mask:0xf bank_mask:0xf
	v_mov_b32_dpp v169, v122 row_newbcast:15 row_mask:0xf bank_mask:0xf
	v_mov_b32_dpp v170, v119 row_newbcast:15 row_mask:0xf bank_mask:0xf
	v_mov_b32_dpp v171, v123 row_newbcast:15 row_mask:0xf bank_mask:0xf
	s_nop 1
	v_mfma_f32_16x16x4_f32 v[176:179], v92, v60, 0
	v_mfma_f32_16x16x4_f32 v[184:187], v96, v64, 0
	v_mfma_f32_16x16x4_f32 v[176:179], v93, v61, v[176:179]
	v_mfma_f32_16x16x4_f32 v[184:187], v97, v65, v[184:187]
	v_mfma_f32_16x16x4_f32 v[176:179], v94, v62, v[176:179]
	v_mfma_f32_16x16x4_f32 v[184:187], v98, v66, v[184:187]
	v_mfma_f32_16x16x4_f32 v[176:179], v95, v63, v[176:179]
	v_mfma_f32_16x16x4_f32 v[184:187], v99, v67, v[184:187]
	v_mfma_f32_16x16x4_f32 v[176:179], v100, v68, v[176:179]
	v_mfma_f32_16x16x4_f32 v[184:187], v104, v72, v[184:187]
	v_mfma_f32_16x16x4_f32 v[176:179], v101, v69, v[176:179]
	v_mfma_f32_16x16x4_f32 v[184:187], v105, v73, v[184:187]
	v_mfma_f32_16x16x4_f32 v[176:179], v102, v70, v[176:179]
	v_mfma_f32_16x16x4_f32 v[184:187], v106, v74, v[184:187]
	v_mfma_f32_16x16x4_f32 v[176:179], v103, v71, v[176:179]
	v_mfma_f32_16x16x4_f32 v[184:187], v107, v75, v[184:187]
	v_mfma_f32_16x16x4_f32 v[176:179], v108, v76, v[176:179]
	v_mfma_f32_16x16x4_f32 v[184:187], v112, v80, v[184:187]
	v_mfma_f32_16x16x4_f32 v[176:179], v109, v77, v[176:179]
	v_mfma_f32_16x16x4_f32 v[184:187], v113, v81, v[184:187]
	v_mfma_f32_16x16x4_f32 v[176:179], v110, v78, v[176:179]
	v_mfma_f32_16x16x4_f32 v[184:187], v114, v82, v[184:187]
	v_mfma_f32_16x16x4_f32 v[176:179], v111, v79, v[176:179]
	v_mfma_f32_16x16x4_f32 v[184:187], v115, v83, v[184:187]
	v_mfma_f32_16x16x4_f32 v[176:179], v116, v84, v[176:179]
	v_mfma_f32_16x16x4_f32 v[184:187], v120, v88, v[184:187]
	v_mfma_f32_16x16x4_f32 v[176:179], v117, v85, v[176:179]
	v_mfma_f32_16x16x4_f32 v[184:187], v121, v89, v[184:187]
	v_mfma_f32_16x16x4_f32 v[176:179], v118, v86, v[176:179]
	v_mfma_f32_16x16x4_f32 v[184:187], v122, v90, v[184:187]
	v_mfma_f32_16x16x4_f32 v[176:179], v119, v87, v[176:179]
	v_mfma_f32_16x16x4_f32 v[184:187], v123, v91, v[184:187]
	s_cmp_ge_u32 s0, 128
	s_cbranch_scc1 .Ls5b_nofin1
	s_and_b32 s55, s0, 7
	s_cmp_lg_u32 s55, 7
	s_cbranch_scc1 .Ls5b_nofin1
	s_lshr_b32 s55, s0, 3
	s_lshl_b32 s55, s55, 2
	s_add_i32 s55, s55, s6
	s_lshl_b32 s55, s55, 1
	s_add_i32 s55, s55, 0
	s_lshl_b32 s55, s55, 4
	s_add_i32 s55, s55, s5
	s_lshl_b32 s55, s55, 8
	s_add_u32 s48, s92, 0x4000000
	s_addc_u32 s49, s93, 0
	s_add_u32 s48, s48, s55
	s_addc_u32 s49, s49, 0
	s_add_u32 s50, s48, 0x80000
	s_addc_u32 s51, s49, 0
	s_mov_b64 exec, s[52:53]
	global_store_dword v16, v124, s[48:49] offset:0
	global_store_dword v16, v125, s[50:51] offset:0
	global_store_dword v16, v126, s[48:49] offset:4
	global_store_dword v16, v127, s[50:51] offset:4
	global_store_dword v16, v128, s[48:49] offset:8
	global_store_dword v16, v129, s[50:51] offset:8
	global_store_dword v16, v130, s[48:49] offset:12
	global_store_dword v16, v131, s[50:51] offset:12
	global_store_dword v16, v140, s[48:49] offset:64
	global_store_dword v16, v141, s[50:51] offset:64
	global_store_dword v16, v142, s[48:49] offset:68
	global_store_dword v16, v143, s[50:51] offset:68
	global_store_dword v16, v144, s[48:49] offset:72
	global_store_dword v16, v145, s[50:51] offset:72
	global_store_dword v16, v146, s[48:49] offset:76
	global_store_dword v16, v147, s[50:51] offset:76
	global_store_dword v16, v148, s[48:49] offset:128
	global_store_dword v16, v149, s[50:51] offset:128
	global_store_dword v16, v150, s[48:49] offset:132
	global_store_dword v16, v151, s[50:51] offset:132
	global_store_dword v16, v152, s[48:49] offset:136
	global_store_dword v16, v153, s[50:51] offset:136
	global_store_dword v16, v154, s[48:49] offset:140
	global_store_dword v16, v155, s[50:51] offset:140
	global_store_dword v16, v156, s[48:49] offset:192
	global_store_dword v16, v157, s[50:51] offset:192
	global_store_dword v16, v158, s[48:49] offset:196
	global_store_dword v16, v159, s[50:51] offset:196
	global_store_dword v16, v168, s[48:49] offset:200
	global_store_dword v16, v169, s[50:51] offset:200
	global_store_dword v16, v170, s[48:49] offset:204
	global_store_dword v16, v171, s[50:51] offset:204
	s_mov_b64 exec, -1
.Ls5b_nofin1:
	s_waitcnt vmcnt(0)
	s_add_i32 s55, s5, 16
	s_lshl_b32 s56, s55, 13
	s_add_u32 s12, s94, 0x12d96000
	s_addc_u32 s13, s95, 0
	s_add_u32 s12, s12, s56
	s_addc_u32 s13, s13, 0
	s_lshl_b32 s56, s55, 9
	s_add_u32 s38, s94, 0x12d92000
	s_addc_u32 s39, s95, 0
	s_add_u32 s38, s38, s56
	s_addc_u32 s39, s39, 0
	s_lshl_b32 s56, s6, 1
	s_add_i32 s56, s56, 1
	s_lshl_b32 s56, s56, 4
	s_add_i32 s56, s56, s5
	s_lshl_b32 s56, s56, 12
	s_add_u32 s14, s16, s56
	s_addc_u32 s15, s17, 0
	s_add_u32 s24, s18, s56
	s_addc_u32 s25, s19, 0
	s_lshl_b32 s56, s0, 5
	s_lshl_b32 s55, s5, 1
	s_add_i32 s56, s56, s55
	s_add_i32 s56, s56, 1
	s_lshl_b32 s56, s56, 9
	s_add_u32 s36, s94, 0x133d6000
	s_addc_u32 s37, s95, 0
	s_add_u32 s36, s36, s56
	s_addc_u32 s37, s37, 0
	global_load_dwordx2 v[2:3], v14, s[38:39]
	global_load_dwordx4 v[28:31], v11, s[12:13] offset:0
	global_load_dwordx4 v[32:35], v11, s[12:13] offset:1024
	global_load_dwordx4 v[36:39], v11, s[12:13] offset:256
	global_load_dwordx4 v[40:43], v11, s[12:13] offset:1280
	global_load_dwordx4 v[44:47], v11, s[12:13] offset:512
	global_load_dwordx4 v[48:51], v11, s[12:13] offset:1536
	global_load_dwordx4 v[52:55], v11, s[12:13] offset:768
	global_load_dwordx4 v[56:59], v11, s[12:13] offset:1792
	global_load_dwordx4 v[124:127], v13, s[36:37] offset:0
	global_load_dwordx4 v[128:131], v13, s[36:37] offset:16
	global_load_dwordx4 v[140:143], v13, s[36:37] offset:128
	global_load_dwordx4 v[144:147], v13, s[36:37] offset:144
	global_load_dwordx4 v[148:151], v13, s[36:37] offset:256
	global_load_dwordx4 v[152:155], v13, s[36:37] offset:272
	global_load_dwordx4 v[156:159], v13, s[36:37] offset:384
	global_load_dwordx4 v[168:171], v13, s[36:37] offset:400
	global_load_dwordx4 v[60:63], v12, s[14:15] offset:0
	global_load_dwordx4 v[64:67], v12, s[24:25] offset:0
	global_load_dwordx4 v[68:71], v12, s[14:15] offset:64
	global_load_dwordx4 v[72:75], v12, s[24:25] offset:64
	global_load_dwordx4 v[76:79], v12, s[14:15] offset:128
	global_load_dwordx4 v[80:83], v12, s[24:25] offset:128
	global_load_dwordx4 v[84:87], v12, s[14:15] offset:192
	global_load_dwordx4 v[88:91], v12, s[24:25] offset:192
	s_waitcnt vmcnt(24)
	ds_write_b32 v17, v2 offset:0
	ds_write_b32 v17, v3 offset:256
	v_mul_f32_e32 v232, v3, v3
	v_mul_f32_e32 v233, v2, v3
	v_fma_f32 v2, v2, v2, -v232
	v_add_f32_e32 v3, v233, v233
	ds_write_b32 v17, v2 offset:512
	ds_write_b32 v17, v3 offset:768
	v_mul_f32_e32 v232, v3, v3
	v_mul_f32_e32 v233, v2, v3
	v_fma_f32 v2, v2, v2, -v232
	v_add_f32_e32 v3, v233, v233
	ds_write_b32 v17, v2 offset:1024
	ds_write_b32 v17, v3 offset:1280
	v_mul_f32_e32 v232, v3, v3
	v_mul_f32_e32 v233, v2, v3
	v_fma_f32 v2, v2, v2, -v232
	v_add_f32_e32 v3, v233, v233
	ds_write_b32 v17, v2 offset:1536
	ds_write_b32 v17, v3 offset:1792
	s_waitcnt lgkmcnt(0)
	s_waitcnt vmcnt(23)
	v_mfma_f32_16x16x4_f32 v[92:95], v28, v24, 0
	v_mfma_f32_16x16x4_f32 v[96:99], v29, v24, 0
	s_waitcnt vmcnt(21)
	v_mfma_f32_16x16x4_f32 v[100:103], v36, v24, 0
	v_mfma_f32_16x16x4_f32 v[104:107], v37, v24, 0
	s_waitcnt vmcnt(19)
	v_mfma_f32_16x16x4_f32 v[108:111], v44, v24, 0
	v_mfma_f32_16x16x4_f32 v[112:115], v45, v24, 0
	s_waitcnt vmcnt(17)
	v_mfma_f32_16x16x4_f32 v[116:119], v52, v24, 0
	v_mfma_f32_16x16x4_f32 v[120:123], v53, v24, 0
	v_mfma_f32_16x16x4_f32 v[92:95], v30, v25, v[92:95]
	v_mfma_f32_16x16x4_f32 v[96:99], v31, v25, v[96:99]
	v_mfma_f32_16x16x4_f32 v[100:103], v38, v25, v[100:103]
	v_mfma_f32_16x16x4_f32 v[104:107], v39, v25, v[104:107]
	v_mfma_f32_16x16x4_f32 v[108:111], v46, v25, v[108:111]
	v_mfma_f32_16x16x4_f32 v[112:115], v47, v25, v[112:115]
	v_mfma_f32_16x16x4_f32 v[116:119], v54, v25, v[116:119]
	v_mfma_f32_16x16x4_f32 v[120:123], v55, v25, v[120:123]
	v_mfma_f32_16x16x4_f32 v[92:95], v32, v26, v[92:95]
	v_mfma_f32_16x16x4_f32 v[96:99], v33, v26, v[96:99]
	v_mfma_f32_16x16x4_f32 v[100:103], v40, v26, v[100:103]
	v_mfma_f32_16x16x4_f32 v[104:107], v41, v26, v[104:107]
	v_mfma_f32_16x16x4_f32 v[108:111], v48, v26, v[108:111]
	v_mfma_f32_16x16x4_f32 v[112:115], v49, v26, v[112:115]
	s_waitcnt vmcnt(16)
	v_mfma_f32_16x16x4_f32 v[116:119], v56, v26, v[116:119]
	v_mfma_f32_16x16x4_f32 v[120:123], v57, v26, v[120:123]
	v_mfma_f32_16x16x4_f32 v[92:95], v34, v27, v[92:95]
	v_mfma_f32_16x16x4_f32 v[96:99], v35, v27, v[96:99]
	v_mfma_f32_16x16x4_f32 v[100:103], v42, v27, v[100:103]
	v_mfma_f32_16x16x4_f32 v[104:107], v43, v27, v[104:107]
	v_mfma_f32_16x16x4_f32 v[108:111], v50, v27, v[108:111]
	v_mfma_f32_16x16x4_f32 v[112:115], v51, v27, v[112:115]
	v_mfma_f32_16x16x4_f32 v[116:119], v58, v27, v[116:119]
	v_mfma_f32_16x16x4_f32 v[120:123], v59, v27, v[120:123]
	ds_read_b128 v[188:191], v18 offset:0
	ds_read_b128 v[192:195], v18 offset:256
	s_waitcnt vmcnt(15)
	s_waitcnt vmcnt(14)
	s_waitcnt vmcnt(13)
	s_waitcnt vmcnt(12)
	s_waitcnt vmcnt(11)
	s_waitcnt vmcnt(10)
	s_waitcnt vmcnt(9)
	s_waitcnt vmcnt(8)
	s_nop 9
	ds_read_b128 v[224:227], v18 offset:64
	ds_read_b128 v[228:231], v18 offset:320
	s_waitcnt lgkmcnt(2)
	s_mov_b64 exec, s[62:63]
	v_fmac_f32_e32 v92, v188, v124
	v_fmac_f32_e32 v93, v189, v126
	v_fmac_f32_e32 v94, v190, v128
	v_fmac_f32_e32 v95, v191, v130
	v_fma_f32 v92, -v192, v125, v92
	v_fma_f32 v93, -v193, v127, v93
	v_fma_f32 v94, -v194, v129, v94
	v_fma_f32 v95, -v195, v131, v95
	v_fmac_f32_e32 v96, v188, v125
	v_fmac_f32_e32 v97, v189, v127
	v_fmac_f32_e32 v98, v190, v129
	v_fmac_f32_e32 v99, v191, v131
	v_fmac_f32_e32 v96, v192, v124
	v_fmac_f32_e32 v97, v193, v126
	v_fmac_f32_e32 v98, v194, v128
	v_fmac_f32_e32 v99, v195, v130
	s_mov_b64 exec, -1
	v_mov_b32_e32 v232, v92
	v_mov_b32_e32 v233, v93
	v_mov_b32_e32 v234, v94
	v_mov_b32_e32 v235, v95
	s_nop 1
	v_fmac_f32_dpp v92, v92, v188 row_shl:1 row_mask:0xf bank_mask:0xf bound_ctrl:0
	v_fmac_f32_dpp v93, v93, v189 row_shl:1 row_mask:0xf bank_mask:0xf bound_ctrl:0
	v_fmac_f32_dpp v94, v94, v190 row_shl:1 row_mask:0xf bank_mask:0xf bound_ctrl:0
	v_fmac_f32_dpp v95, v95, v191 row_shl:1 row_mask:0xf bank_mask:0xf bound_ctrl:0
	v_fmac_f32_dpp v92, v96, -v192 row_shl:1 row_mask:0xf bank_mask:0xf bound_ctrl:0
	v_fmac_f32_dpp v93, v97, -v193 row_shl:1 row_mask:0xf bank_mask:0xf bound_ctrl:0
	v_fmac_f32_dpp v94, v98, -v194 row_shl:1 row_mask:0xf bank_mask:0xf bound_ctrl:0
	v_fmac_f32_dpp v95, v99, -v195 row_shl:1 row_mask:0xf bank_mask:0xf bound_ctrl:0
	v_fmac_f32_dpp v96, v96, v188 row_shl:1 row_mask:0xf bank_mask:0xf bound_ctrl:0
	v_fmac_f32_dpp v97, v97, v189 row_shl:1 row_mask:0xf bank_mask:0xf bound_ctrl:0
	v_fmac_f32_dpp v98, v98, v190 row_shl:1 row_mask:0xf bank_mask:0xf bound_ctrl:0
	v_fmac_f32_dpp v99, v99, v191 row_shl:1 row_mask:0xf bank_mask:0xf bound_ctrl:0
	v_fmac_f32_dpp v96, v232, v192 row_shl:1 row_mask:0xf bank_mask:0xf bound_ctrl:0
	v_fmac_f32_dpp v97, v233, v193 row_shl:1 row_mask:0xf bank_mask:0xf bound_ctrl:0
	v_fmac_f32_dpp v98, v234, v194 row_shl:1 row_mask:0xf bank_mask:0xf bound_ctrl:0
	v_fmac_f32_dpp v99, v235, v195 row_shl:1 row_mask:0xf bank_mask:0xf bound_ctrl:0
	ds_read_b128 v[188:191], v18 offset:128
	ds_read_b128 v[192:195], v18 offset:384
	s_waitcnt lgkmcnt(2)
	s_mov_b64 exec, s[62:63]
	v_fmac_f32_e32 v100, v224, v140
	v_fmac_f32_e32 v101, v225, v142
	v_fmac_f32_e32 v102, v226, v144
	v_fmac_f32_e32 v103, v227, v146
	v_fma_f32 v100, -v228, v141, v100
	v_fma_f32 v101, -v229, v143, v101
	v_fma_f32 v102, -v230, v145, v102
	v_fma_f32 v103, -v231, v147, v103
	v_fmac_f32_e32 v104, v224, v141
	v_fmac_f32_e32 v105, v225, v143
	v_fmac_f32_e32 v106, v226, v145
	v_fmac_f32_e32 v107, v227, v147
	v_fmac_f32_e32 v104, v228, v140
	v_fmac_f32_e32 v105, v229, v142
	v_fmac_f32_e32 v106, v230, v144
	v_fmac_f32_e32 v107, v231, v146
	s_mov_b64 exec, -1
	v_mov_b32_e32 v232, v100
	v_mov_b32_e32 v233, v101
	v_mov_b32_e32 v234, v102
	v_mov_b32_e32 v235, v103
	s_nop 1
	v_fmac_f32_dpp v100, v100, v224 row_shl:1 row_mask:0xf bank_mask:0xf bound_ctrl:0
	v_fmac_f32_dpp v101, v101, v225 row_shl:1 row_mask:0xf bank_mask:0xf bound_ctrl:0
	v_fmac_f32_dpp v102, v102, v226 row_shl:1 row_mask:0xf bank_mask:0xf bound_ctrl:0
	v_fmac_f32_dpp v103, v103, v227 row_shl:1 row_mask:0xf bank_mask:0xf bound_ctrl:0
	v_fmac_f32_dpp v100, v104, -v228 row_shl:1 row_mask:0xf bank_mask:0xf bound_ctrl:0
	v_fmac_f32_dpp v101, v105, -v229 row_shl:1 row_mask:0xf bank_mask:0xf bound_ctrl:0
	v_fmac_f32_dpp v102, v106, -v230 row_shl:1 row_mask:0xf bank_mask:0xf bound_ctrl:0
	v_fmac_f32_dpp v103, v107, -v231 row_shl:1 row_mask:0xf bank_mask:0xf bound_ctrl:0
	v_fmac_f32_dpp v104, v104, v224 row_shl:1 row_mask:0xf bank_mask:0xf bound_ctrl:0
	v_fmac_f32_dpp v105, v105, v225 row_shl:1 row_mask:0xf bank_mask:0xf bound_ctrl:0
	v_fmac_f32_dpp v106, v106, v226 row_shl:1 row_mask:0xf bank_mask:0xf bound_ctrl:0
	v_fmac_f32_dpp v107, v107, v227 row_shl:1 row_mask:0xf bank_mask:0xf bound_ctrl:0
	v_fmac_f32_dpp v104, v232, v228 row_shl:1 row_mask:0xf bank_mask:0xf bound_ctrl:0
	v_fmac_f32_dpp v105, v233, v229 row_shl:1 row_mask:0xf bank_mask:0xf bound_ctrl:0
	v_fmac_f32_dpp v106, v234, v230 row_shl:1 row_mask:0xf bank_mask:0xf bound_ctrl:0
	v_fmac_f32_dpp v107, v235, v231 row_shl:1 row_mask:0xf bank_mask:0xf bound_ctrl:0
	ds_read_b128 v[224:227], v18 offset:192
	ds_read_b128 v[228:231], v18 offset:448
	s_waitcnt lgkmcnt(2)
	s_mov_b64 exec, s[62:63]
	v_fmac_f32_e32 v108, v188, v148
	v_fmac_f32_e32 v109, v189, v150
	v_fmac_f32_e32 v110, v190, v152
	v_fmac_f32_e32 v111, v191, v154
	v_fma_f32 v108, -v192, v149, v108
	v_fma_f32 v109, -v193, v151, v109
	v_fma_f32 v110, -v194, v153, v110
	v_fma_f32 v111, -v195, v155, v111
	v_fmac_f32_e32 v112, v188, v149
	v_fmac_f32_e32 v113, v189, v151
	v_fmac_f32_e32 v114, v190, v153
	v_fmac_f32_e32 v115, v191, v155
	v_fmac_f32_e32 v112, v192, v148
	v_fmac_f32_e32 v113, v193, v150
	v_fmac_f32_e32 v114, v194, v152
	v_fmac_f32_e32 v115, v195, v154
	s_mov_b64 exec, -1
	v_mov_b32_e32 v232, v108
	v_mov_b32_e32 v233, v109
	v_mov_b32_e32 v234, v110
	v_mov_b32_e32 v235, v111
	s_nop 1
	v_fmac_f32_dpp v108, v108, v188 row_shl:1 row_mask:0xf bank_mask:0xf bound_ctrl:0
	v_fmac_f32_dpp v109, v109, v189 row_shl:1 row_mask:0xf bank_mask:0xf bound_ctrl:0
	v_fmac_f32_dpp v110, v110, v190 row_shl:1 row_mask:0xf bank_mask:0xf bound_ctrl:0
	v_fmac_f32_dpp v111, v111, v191 row_shl:1 row_mask:0xf bank_mask:0xf bound_ctrl:0
	v_fmac_f32_dpp v108, v112, -v192 row_shl:1 row_mask:0xf bank_mask:0xf bound_ctrl:0
	v_fmac_f32_dpp v109, v113, -v193 row_shl:1 row_mask:0xf bank_mask:0xf bound_ctrl:0
	v_fmac_f32_dpp v110, v114, -v194 row_shl:1 row_mask:0xf bank_mask:0xf bound_ctrl:0
	v_fmac_f32_dpp v111, v115, -v195 row_shl:1 row_mask:0xf bank_mask:0xf bound_ctrl:0
	v_fmac_f32_dpp v112, v112, v188 row_shl:1 row_mask:0xf bank_mask:0xf bound_ctrl:0
	v_fmac_f32_dpp v113, v113, v189 row_shl:1 row_mask:0xf bank_mask:0xf bound_ctrl:0
	v_fmac_f32_dpp v114, v114, v190 row_shl:1 row_mask:0xf bank_mask:0xf bound_ctrl:0
	v_fmac_f32_dpp v115, v115, v191 row_shl:1 row_mask:0xf bank_mask:0xf bound_ctrl:0
	v_fmac_f32_dpp v112, v232, v192 row_shl:1 row_mask:0xf bank_mask:0xf bound_ctrl:0
	v_fmac_f32_dpp v113, v233, v193 row_shl:1 row_mask:0xf bank_mask:0xf bound_ctrl:0
	v_fmac_f32_dpp v114, v234, v194 row_shl:1 row_mask:0xf bank_mask:0xf bound_ctrl:0
	v_fmac_f32_dpp v115, v235, v195 row_shl:1 row_mask:0xf bank_mask:0xf bound_ctrl:0
	ds_read_b128 v[188:191], v18 offset:512
	ds_read_b128 v[192:195], v18 offset:768
	s_waitcnt lgkmcnt(2)
	s_mov_b64 exec, s[62:63]
	v_fmac_f32_e32 v116, v224, v156
	v_fmac_f32_e32 v117, v225, v158
	v_fmac_f32_e32 v118, v226, v168
	v_fmac_f32_e32 v119, v227, v170
	v_fma_f32 v116, -v228, v157, v116
	v_fma_f32 v117, -v229, v159, v117
	v_fma_f32 v118, -v230, v169, v118
	v_fma_f32 v119, -v231, v171, v119
	v_fmac_f32_e32 v120, v224, v157
	v_fmac_f32_e32 v121, v225, v159
	v_fmac_f32_e32 v122, v226, v169
	v_fmac_f32_e32 v123, v227, v171
	v_fmac_f32_e32 v120, v228, v156
	v_fmac_f32_e32 v121, v229, v158
	v_fmac_f32_e32 v122, v230, v168
	v_fmac_f32_e32 v123, v231, v170
	s_mov_b64 exec, -1
	v_mov_b32_e32 v232, v116
	v_mov_b32_e32 v233, v117
	v_mov_b32_e32 v234, v118
	v_mov_b32_e32 v235, v119
	s_nop 1
	v_fmac_f32_dpp v116, v116, v224 row_shl:1 row_mask:0xf bank_mask:0xf bound_ctrl:0
	v_fmac_f32_dpp v117, v117, v225 row_shl:1 row_mask:0xf bank_mask:0xf bound_ctrl:0
	v_fmac_f32_dpp v118, v118, v226 row_shl:1 row_mask:0xf bank_mask:0xf bound_ctrl:0
	v_fmac_f32_dpp v119, v119, v227 row_shl:1 row_mask:0xf bank_mask:0xf bound_ctrl:0
	v_fmac_f32_dpp v116, v120, -v228 row_shl:1 row_mask:0xf bank_mask:0xf bound_ctrl:0
	v_fmac_f32_dpp v117, v121, -v229 row_shl:1 row_mask:0xf bank_mask:0xf bound_ctrl:0
	v_fmac_f32_dpp v118, v122, -v230 row_shl:1 row_mask:0xf bank_mask:0xf bound_ctrl:0
	v_fmac_f32_dpp v119, v123, -v231 row_shl:1 row_mask:0xf bank_mask:0xf bound_ctrl:0
	v_fmac_f32_dpp v120, v120, v224 row_shl:1 row_mask:0xf bank_mask:0xf bound_ctrl:0
	v_fmac_f32_dpp v121, v121, v225 row_shl:1 row_mask:0xf bank_mask:0xf bound_ctrl:0
	v_fmac_f32_dpp v122, v122, v226 row_shl:1 row_mask:0xf bank_mask:0xf bound_ctrl:0
	v_fmac_f32_dpp v123, v123, v227 row_shl:1 row_mask:0xf bank_mask:0xf bound_ctrl:0
	v_fmac_f32_dpp v120, v232, v228 row_shl:1 row_mask:0xf bank_mask:0xf bound_ctrl:0
	v_fmac_f32_dpp v121, v233, v229 row_shl:1 row_mask:0xf bank_mask:0xf bound_ctrl:0
	v_fmac_f32_dpp v122, v234, v230 row_shl:1 row_mask:0xf bank_mask:0xf bound_ctrl:0
	v_fmac_f32_dpp v123, v235, v231 row_shl:1 row_mask:0xf bank_mask:0xf bound_ctrl:0
	ds_read_b128 v[224:227], v18 offset:576
	ds_read_b128 v[228:231], v18 offset:832
	s_waitcnt lgkmcnt(2)
	v_mov_b32_e32 v232, v92
	v_mov_b32_e32 v233, v93
	v_mov_b32_e32 v234, v94
	v_mov_b32_e32 v235, v95
	v_fmac_f32_dpp v92, v92, v188 row_shl:2 row_mask:0xf bank_mask:0xf bound_ctrl:0
	v_fmac_f32_dpp v93, v93, v189 row_shl:2 row_mask:0xf bank_mask:0xf bound_ctrl:0
	v_fmac_f32_dpp v94, v94, v190 row_shl:2 row_mask:0xf bank_mask:0xf bound_ctrl:0
	v_fmac_f32_dpp v95, v95, v191 row_shl:2 row_mask:0xf bank_mask:0xf bound_ctrl:0
	v_fmac_f32_dpp v92, v96, -v192 row_shl:2 row_mask:0xf bank_mask:0xf bound_ctrl:0
	v_fmac_f32_dpp v93, v97, -v193 row_shl:2 row_mask:0xf bank_mask:0xf bound_ctrl:0
	v_fmac_f32_dpp v94, v98, -v194 row_shl:2 row_mask:0xf bank_mask:0xf bound_ctrl:0
	v_fmac_f32_dpp v95, v99, -v195 row_shl:2 row_mask:0xf bank_mask:0xf bound_ctrl:0
	v_fmac_f32_dpp v96, v96, v188 row_shl:2 row_mask:0xf bank_mask:0xf bound_ctrl:0
	v_fmac_f32_dpp v97, v97, v189 row_shl:2 row_mask:0xf bank_mask:0xf bound_ctrl:0
	v_fmac_f32_dpp v98, v98, v190 row_shl:2 row_mask:0xf bank_mask:0xf bound_ctrl:0
	v_fmac_f32_dpp v99, v99, v191 row_shl:2 row_mask:0xf bank_mask:0xf bound_ctrl:0
	v_fmac_f32_dpp v96, v232, v192 row_shl:2 row_mask:0xf bank_mask:0xf bound_ctrl:0
	v_fmac_f32_dpp v97, v233, v193 row_shl:2 row_mask:0xf bank_mask:0xf bound_ctrl:0
	v_fmac_f32_dpp v98, v234, v194 row_shl:2 row_mask:0xf bank_mask:0xf bound_ctrl:0
	v_fmac_f32_dpp v99, v235, v195 row_shl:2 row_mask:0xf bank_mask:0xf bound_ctrl:0
	ds_read_b128 v[188:191], v18 offset:640
	ds_read_b128 v[192:195], v18 offset:896
	s_waitcnt lgkmcnt(2)
	v_mov_b32_e32 v232, v100
	v_mov_b32_e32 v233, v101
	v_mov_b32_e32 v234, v102
	v_mov_b32_e32 v235, v103
	v_fmac_f32_dpp v100, v100, v224 row_shl:2 row_mask:0xf bank_mask:0xf bound_ctrl:0
	v_fmac_f32_dpp v101, v101, v225 row_shl:2 row_mask:0xf bank_mask:0xf bound_ctrl:0
	v_fmac_f32_dpp v102, v102, v226 row_shl:2 row_mask:0xf bank_mask:0xf bound_ctrl:0
	v_fmac_f32_dpp v103, v103, v227 row_shl:2 row_mask:0xf bank_mask:0xf bound_ctrl:0
	v_fmac_f32_dpp v100, v104, -v228 row_shl:2 row_mask:0xf bank_mask:0xf bound_ctrl:0
	v_fmac_f32_dpp v101, v105, -v229 row_shl:2 row_mask:0xf bank_mask:0xf bound_ctrl:0
	v_fmac_f32_dpp v102, v106, -v230 row_shl:2 row_mask:0xf bank_mask:0xf bound_ctrl:0
	v_fmac_f32_dpp v103, v107, -v231 row_shl:2 row_mask:0xf bank_mask:0xf bound_ctrl:0
	v_fmac_f32_dpp v104, v104, v224 row_shl:2 row_mask:0xf bank_mask:0xf bound_ctrl:0
	v_fmac_f32_dpp v105, v105, v225 row_shl:2 row_mask:0xf bank_mask:0xf bound_ctrl:0
	v_fmac_f32_dpp v106, v106, v226 row_shl:2 row_mask:0xf bank_mask:0xf bound_ctrl:0
	v_fmac_f32_dpp v107, v107, v227 row_shl:2 row_mask:0xf bank_mask:0xf bound_ctrl:0
	v_fmac_f32_dpp v104, v232, v228 row_shl:2 row_mask:0xf bank_mask:0xf bound_ctrl:0
	v_fmac_f32_dpp v105, v233, v229 row_shl:2 row_mask:0xf bank_mask:0xf bound_ctrl:0
	v_fmac_f32_dpp v106, v234, v230 row_shl:2 row_mask:0xf bank_mask:0xf bound_ctrl:0
	v_fmac_f32_dpp v107, v235, v231 row_shl:2 row_mask:0xf bank_mask:0xf bound_ctrl:0
	ds_read_b128 v[224:227], v18 offset:704
	ds_read_b128 v[228:231], v18 offset:960
	s_waitcnt lgkmcnt(2)
	v_mov_b32_e32 v232, v108
	v_mov_b32_e32 v233, v109
	v_mov_b32_e32 v234, v110
	v_mov_b32_e32 v235, v111
	v_fmac_f32_dpp v108, v108, v188 row_shl:2 row_mask:0xf bank_mask:0xf bound_ctrl:0
	v_fmac_f32_dpp v109, v109, v189 row_shl:2 row_mask:0xf bank_mask:0xf bound_ctrl:0
	v_fmac_f32_dpp v110, v110, v190 row_shl:2 row_mask:0xf bank_mask:0xf bound_ctrl:0
	v_fmac_f32_dpp v111, v111, v191 row_shl:2 row_mask:0xf bank_mask:0xf bound_ctrl:0
	v_fmac_f32_dpp v108, v112, -v192 row_shl:2 row_mask:0xf bank_mask:0xf bound_ctrl:0
	v_fmac_f32_dpp v109, v113, -v193 row_shl:2 row_mask:0xf bank_mask:0xf bound_ctrl:0
	v_fmac_f32_dpp v110, v114, -v194 row_shl:2 row_mask:0xf bank_mask:0xf bound_ctrl:0
	v_fmac_f32_dpp v111, v115, -v195 row_shl:2 row_mask:0xf bank_mask:0xf bound_ctrl:0
	v_fmac_f32_dpp v112, v112, v188 row_shl:2 row_mask:0xf bank_mask:0xf bound_ctrl:0
	v_fmac_f32_dpp v113, v113, v189 row_shl:2 row_mask:0xf bank_mask:0xf bound_ctrl:0
	v_fmac_f32_dpp v114, v114, v190 row_shl:2 row_mask:0xf bank_mask:0xf bound_ctrl:0
	v_fmac_f32_dpp v115, v115, v191 row_shl:2 row_mask:0xf bank_mask:0xf bound_ctrl:0
	v_fmac_f32_dpp v112, v232, v192 row_shl:2 row_mask:0xf bank_mask:0xf bound_ctrl:0
	v_fmac_f32_dpp v113, v233, v193 row_shl:2 row_mask:0xf bank_mask:0xf bound_ctrl:0
	v_fmac_f32_dpp v114, v234, v194 row_shl:2 row_mask:0xf bank_mask:0xf bound_ctrl:0
	v_fmac_f32_dpp v115, v235, v195 row_shl:2 row_mask:0xf bank_mask:0xf bound_ctrl:0
	ds_read_b128 v[188:191], v18 offset:1024
	ds_read_b128 v[192:195], v18 offset:1280
	s_waitcnt lgkmcnt(2)
	v_mov_b32_e32 v232, v116
	v_mov_b32_e32 v233, v117
	v_mov_b32_e32 v234, v118
	v_mov_b32_e32 v235, v119
	v_fmac_f32_dpp v116, v116, v224 row_shl:2 row_mask:0xf bank_mask:0xf bound_ctrl:0
	v_fmac_f32_dpp v117, v117, v225 row_shl:2 row_mask:0xf bank_mask:0xf bound_ctrl:0
	v_fmac_f32_dpp v118, v118, v226 row_shl:2 row_mask:0xf bank_mask:0xf bound_ctrl:0
	v_fmac_f32_dpp v119, v119, v227 row_shl:2 row_mask:0xf bank_mask:0xf bound_ctrl:0
	v_fmac_f32_dpp v116, v120, -v228 row_shl:2 row_mask:0xf bank_mask:0xf bound_ctrl:0
	v_fmac_f32_dpp v117, v121, -v229 row_shl:2 row_mask:0xf bank_mask:0xf bound_ctrl:0
	v_fmac_f32_dpp v118, v122, -v230 row_shl:2 row_mask:0xf bank_mask:0xf bound_ctrl:0
	v_fmac_f32_dpp v119, v123, -v231 row_shl:2 row_mask:0xf bank_mask:0xf bound_ctrl:0
	v_fmac_f32_dpp v120, v120, v224 row_shl:2 row_mask:0xf bank_mask:0xf bound_ctrl:0
	v_fmac_f32_dpp v121, v121, v225 row_shl:2 row_mask:0xf bank_mask:0xf bound_ctrl:0
	v_fmac_f32_dpp v122, v122, v226 row_shl:2 row_mask:0xf bank_mask:0xf bound_ctrl:0
	v_fmac_f32_dpp v123, v123, v227 row_shl:2 row_mask:0xf bank_mask:0xf bound_ctrl:0
	v_fmac_f32_dpp v120, v232, v228 row_shl:2 row_mask:0xf bank_mask:0xf bound_ctrl:0
	v_fmac_f32_dpp v121, v233, v229 row_shl:2 row_mask:0xf bank_mask:0xf bound_ctrl:0
	v_fmac_f32_dpp v122, v234, v230 row_shl:2 row_mask:0xf bank_mask:0xf bound_ctrl:0
	v_fmac_f32_dpp v123, v235, v231 row_shl:2 row_mask:0xf bank_mask:0xf bound_ctrl:0
	ds_read_b128 v[224:227], v18 offset:1088
	ds_read_b128 v[228:231], v18 offset:1344
	s_waitcnt lgkmcnt(2)
	v_mov_b32_e32 v232, v92
	v_mov_b32_e32 v233, v93
	v_mov_b32_e32 v234, v94
	v_mov_b32_e32 v235, v95
	v_fmac_f32_dpp v92, v92, v188 row_shl:4 row_mask:0xf bank_mask:0xf bound_ctrl:0
	v_fmac_f32_dpp v93, v93, v189 row_shl:4 row_mask:0xf bank_mask:0xf bound_ctrl:0
	v_fmac_f32_dpp v94, v94, v190 row_shl:4 row_mask:0xf bank_mask:0xf bound_ctrl:0
	v_fmac_f32_dpp v95, v95, v191 row_shl:4 row_mask:0xf bank_mask:0xf bound_ctrl:0
	v_fmac_f32_dpp v92, v96, -v192 row_shl:4 row_mask:0xf bank_mask:0xf bound_ctrl:0
	v_fmac_f32_dpp v93, v97, -v193 row_shl:4 row_mask:0xf bank_mask:0xf bound_ctrl:0
	v_fmac_f32_dpp v94, v98, -v194 row_shl:4 row_mask:0xf bank_mask:0xf bound_ctrl:0
	v_fmac_f32_dpp v95, v99, -v195 row_shl:4 row_mask:0xf bank_mask:0xf bound_ctrl:0
	v_fmac_f32_dpp v96, v96, v188 row_shl:4 row_mask:0xf bank_mask:0xf bound_ctrl:0
	v_fmac_f32_dpp v97, v97, v189 row_shl:4 row_mask:0xf bank_mask:0xf bound_ctrl:0
	v_fmac_f32_dpp v98, v98, v190 row_shl:4 row_mask:0xf bank_mask:0xf bound_ctrl:0
	v_fmac_f32_dpp v99, v99, v191 row_shl:4 row_mask:0xf bank_mask:0xf bound_ctrl:0
	v_fmac_f32_dpp v96, v232, v192 row_shl:4 row_mask:0xf bank_mask:0xf bound_ctrl:0
	v_fmac_f32_dpp v97, v233, v193 row_shl:4 row_mask:0xf bank_mask:0xf bound_ctrl:0
	v_fmac_f32_dpp v98, v234, v194 row_shl:4 row_mask:0xf bank_mask:0xf bound_ctrl:0
	v_fmac_f32_dpp v99, v235, v195 row_shl:4 row_mask:0xf bank_mask:0xf bound_ctrl:0
	ds_read_b128 v[188:191], v18 offset:1152
	ds_read_b128 v[192:195], v18 offset:1408
	s_waitcnt lgkmcnt(2)
	v_mov_b32_e32 v232, v100
	v_mov_b32_e32 v233, v101
	v_mov_b32_e32 v234, v102
	v_mov_b32_e32 v235, v103
	v_fmac_f32_dpp v100, v100, v224 row_shl:4 row_mask:0xf bank_mask:0xf bound_ctrl:0
	v_fmac_f32_dpp v101, v101, v225 row_shl:4 row_mask:0xf bank_mask:0xf bound_ctrl:0
	v_fmac_f32_dpp v102, v102, v226 row_shl:4 row_mask:0xf bank_mask:0xf bound_ctrl:0
	v_fmac_f32_dpp v103, v103, v227 row_shl:4 row_mask:0xf bank_mask:0xf bound_ctrl:0
	v_fmac_f32_dpp v100, v104, -v228 row_shl:4 row_mask:0xf bank_mask:0xf bound_ctrl:0
	v_fmac_f32_dpp v101, v105, -v229 row_shl:4 row_mask:0xf bank_mask:0xf bound_ctrl:0
	v_fmac_f32_dpp v102, v106, -v230 row_shl:4 row_mask:0xf bank_mask:0xf bound_ctrl:0
	v_fmac_f32_dpp v103, v107, -v231 row_shl:4 row_mask:0xf bank_mask:0xf bound_ctrl:0
	v_fmac_f32_dpp v104, v104, v224 row_shl:4 row_mask:0xf bank_mask:0xf bound_ctrl:0
	v_fmac_f32_dpp v105, v105, v225 row_shl:4 row_mask:0xf bank_mask:0xf bound_ctrl:0
	v_fmac_f32_dpp v106, v106, v226 row_shl:4 row_mask:0xf bank_mask:0xf bound_ctrl:0
	v_fmac_f32_dpp v107, v107, v227 row_shl:4 row_mask:0xf bank_mask:0xf bound_ctrl:0
	v_fmac_f32_dpp v104, v232, v228 row_shl:4 row_mask:0xf bank_mask:0xf bound_ctrl:0
	v_fmac_f32_dpp v105, v233, v229 row_shl:4 row_mask:0xf bank_mask:0xf bound_ctrl:0
	v_fmac_f32_dpp v106, v234, v230 row_shl:4 row_mask:0xf bank_mask:0xf bound_ctrl:0
	v_fmac_f32_dpp v107, v235, v231 row_shl:4 row_mask:0xf bank_mask:0xf bound_ctrl:0
	ds_read_b128 v[224:227], v18 offset:1216
	ds_read_b128 v[228:231], v18 offset:1472
	s_waitcnt lgkmcnt(2)
	v_mov_b32_e32 v232, v108
	v_mov_b32_e32 v233, v109
	v_mov_b32_e32 v234, v110
	v_mov_b32_e32 v235, v111
	v_fmac_f32_dpp v108, v108, v188 row_shl:4 row_mask:0xf bank_mask:0xf bound_ctrl:0
	v_fmac_f32_dpp v109, v109, v189 row_shl:4 row_mask:0xf bank_mask:0xf bound_ctrl:0
	v_fmac_f32_dpp v110, v110, v190 row_shl:4 row_mask:0xf bank_mask:0xf bound_ctrl:0
	v_fmac_f32_dpp v111, v111, v191 row_shl:4 row_mask:0xf bank_mask:0xf bound_ctrl:0
	v_fmac_f32_dpp v108, v112, -v192 row_shl:4 row_mask:0xf bank_mask:0xf bound_ctrl:0
	v_fmac_f32_dpp v109, v113, -v193 row_shl:4 row_mask:0xf bank_mask:0xf bound_ctrl:0
	v_fmac_f32_dpp v110, v114, -v194 row_shl:4 row_mask:0xf bank_mask:0xf bound_ctrl:0
	v_fmac_f32_dpp v111, v115, -v195 row_shl:4 row_mask:0xf bank_mask:0xf bound_ctrl:0
	v_fmac_f32_dpp v112, v112, v188 row_shl:4 row_mask:0xf bank_mask:0xf bound_ctrl:0
	v_fmac_f32_dpp v113, v113, v189 row_shl:4 row_mask:0xf bank_mask:0xf bound_ctrl:0
	v_fmac_f32_dpp v114, v114, v190 row_shl:4 row_mask:0xf bank_mask:0xf bound_ctrl:0
	v_fmac_f32_dpp v115, v115, v191 row_shl:4 row_mask:0xf bank_mask:0xf bound_ctrl:0
	v_fmac_f32_dpp v112, v232, v192 row_shl:4 row_mask:0xf bank_mask:0xf bound_ctrl:0
	v_fmac_f32_dpp v113, v233, v193 row_shl:4 row_mask:0xf bank_mask:0xf bound_ctrl:0
	v_fmac_f32_dpp v114, v234, v194 row_shl:4 row_mask:0xf bank_mask:0xf bound_ctrl:0
	v_fmac_f32_dpp v115, v235, v195 row_shl:4 row_mask:0xf bank_mask:0xf bound_ctrl:0
	ds_read_b128 v[188:191], v18 offset:1536
	ds_read_b128 v[192:195], v18 offset:1792
	s_waitcnt lgkmcnt(2)
	v_mov_b32_e32 v232, v116
	v_mov_b32_e32 v233, v117
	v_mov_b32_e32 v234, v118
	v_mov_b32_e32 v235, v119
	v_fmac_f32_dpp v116, v116, v224 row_shl:4 row_mask:0xf bank_mask:0xf bound_ctrl:0
	v_fmac_f32_dpp v117, v117, v225 row_shl:4 row_mask:0xf bank_mask:0xf bound_ctrl:0
	v_fmac_f32_dpp v118, v118, v226 row_shl:4 row_mask:0xf bank_mask:0xf bound_ctrl:0
	v_fmac_f32_dpp v119, v119, v227 row_shl:4 row_mask:0xf bank_mask:0xf bound_ctrl:0
	v_fmac_f32_dpp v116, v120, -v228 row_shl:4 row_mask:0xf bank_mask:0xf bound_ctrl:0
	v_fmac_f32_dpp v117, v121, -v229 row_shl:4 row_mask:0xf bank_mask:0xf bound_ctrl:0
	v_fmac_f32_dpp v118, v122, -v230 row_shl:4 row_mask:0xf bank_mask:0xf bound_ctrl:0
	v_fmac_f32_dpp v119, v123, -v231 row_shl:4 row_mask:0xf bank_mask:0xf bound_ctrl:0
	v_fmac_f32_dpp v120, v120, v224 row_shl:4 row_mask:0xf bank_mask:0xf bound_ctrl:0
	v_fmac_f32_dpp v121, v121, v225 row_shl:4 row_mask:0xf bank_mask:0xf bound_ctrl:0
	v_fmac_f32_dpp v122, v122, v226 row_shl:4 row_mask:0xf bank_mask:0xf bound_ctrl:0
	v_fmac_f32_dpp v123, v123, v227 row_shl:4 row_mask:0xf bank_mask:0xf bound_ctrl:0
	v_fmac_f32_dpp v120, v232, v228 row_shl:4 row_mask:0xf bank_mask:0xf bound_ctrl:0
	v_fmac_f32_dpp v121, v233, v229 row_shl:4 row_mask:0xf bank_mask:0xf bound_ctrl:0
	v_fmac_f32_dpp v122, v234, v230 row_shl:4 row_mask:0xf bank_mask:0xf bound_ctrl:0
	v_fmac_f32_dpp v123, v235, v231 row_shl:4 row_mask:0xf bank_mask:0xf bound_ctrl:0
	ds_read_b128 v[224:227], v18 offset:1600
	ds_read_b128 v[228:231], v18 offset:1856
	s_waitcnt lgkmcnt(2)
	v_mov_b32_e32 v232, v92
	v_mov_b32_e32 v233, v93
	v_mov_b32_e32 v234, v94
	v_mov_b32_e32 v235, v95
	v_fmac_f32_dpp v92, v92, v188 row_shl:8 row_mask:0xf bank_mask:0xf bound_ctrl:0
	v_fmac_f32_dpp v93, v93, v189 row_shl:8 row_mask:0xf bank_mask:0xf bound_ctrl:0
	v_fmac_f32_dpp v94, v94, v190 row_shl:8 row_mask:0xf bank_mask:0xf bound_ctrl:0
	v_fmac_f32_dpp v95, v95, v191 row_shl:8 row_mask:0xf bank_mask:0xf bound_ctrl:0
	v_fmac_f32_dpp v92, v96, -v192 row_shl:8 row_mask:0xf bank_mask:0xf bound_ctrl:0
	v_fmac_f32_dpp v93, v97, -v193 row_shl:8 row_mask:0xf bank_mask:0xf bound_ctrl:0
	v_fmac_f32_dpp v94, v98, -v194 row_shl:8 row_mask:0xf bank_mask:0xf bound_ctrl:0
	v_fmac_f32_dpp v95, v99, -v195 row_shl:8 row_mask:0xf bank_mask:0xf bound_ctrl:0
	v_fmac_f32_dpp v96, v96, v188 row_shl:8 row_mask:0xf bank_mask:0xf bound_ctrl:0
	v_fmac_f32_dpp v97, v97, v189 row_shl:8 row_mask:0xf bank_mask:0xf bound_ctrl:0
	v_fmac_f32_dpp v98, v98, v190 row_shl:8 row_mask:0xf bank_mask:0xf bound_ctrl:0
	v_fmac_f32_dpp v99, v99, v191 row_shl:8 row_mask:0xf bank_mask:0xf bound_ctrl:0
	v_fmac_f32_dpp v96, v232, v192 row_shl:8 row_mask:0xf bank_mask:0xf bound_ctrl:0
	v_fmac_f32_dpp v97, v233, v193 row_shl:8 row_mask:0xf bank_mask:0xf bound_ctrl:0
	v_fmac_f32_dpp v98, v234, v194 row_shl:8 row_mask:0xf bank_mask:0xf bound_ctrl:0
	v_fmac_f32_dpp v99, v235, v195 row_shl:8 row_mask:0xf bank_mask:0xf bound_ctrl:0
	ds_read_b128 v[188:191], v18 offset:1664
	ds_read_b128 v[192:195], v18 offset:1920
	s_waitcnt lgkmcnt(2)
	v_mov_b32_e32 v232, v100
	v_mov_b32_e32 v233, v101
	v_mov_b32_e32 v234, v102
	v_mov_b32_e32 v235, v103
	v_fmac_f32_dpp v100, v100, v224 row_shl:8 row_mask:0xf bank_mask:0xf bound_ctrl:0
	v_fmac_f32_dpp v101, v101, v225 row_shl:8 row_mask:0xf bank_mask:0xf bound_ctrl:0
	v_fmac_f32_dpp v102, v102, v226 row_shl:8 row_mask:0xf bank_mask:0xf bound_ctrl:0
	v_fmac_f32_dpp v103, v103, v227 row_shl:8 row_mask:0xf bank_mask:0xf bound_ctrl:0
	v_fmac_f32_dpp v100, v104, -v228 row_shl:8 row_mask:0xf bank_mask:0xf bound_ctrl:0
	v_fmac_f32_dpp v101, v105, -v229 row_shl:8 row_mask:0xf bank_mask:0xf bound_ctrl:0
	v_fmac_f32_dpp v102, v106, -v230 row_shl:8 row_mask:0xf bank_mask:0xf bound_ctrl:0
	v_fmac_f32_dpp v103, v107, -v231 row_shl:8 row_mask:0xf bank_mask:0xf bound_ctrl:0
	v_fmac_f32_dpp v104, v104, v224 row_shl:8 row_mask:0xf bank_mask:0xf bound_ctrl:0
	v_fmac_f32_dpp v105, v105, v225 row_shl:8 row_mask:0xf bank_mask:0xf bound_ctrl:0
	v_fmac_f32_dpp v106, v106, v226 row_shl:8 row_mask:0xf bank_mask:0xf bound_ctrl:0
	v_fmac_f32_dpp v107, v107, v227 row_shl:8 row_mask:0xf bank_mask:0xf bound_ctrl:0
	v_fmac_f32_dpp v104, v232, v228 row_shl:8 row_mask:0xf bank_mask:0xf bound_ctrl:0
	v_fmac_f32_dpp v105, v233, v229 row_shl:8 row_mask:0xf bank_mask:0xf bound_ctrl:0
	v_fmac_f32_dpp v106, v234, v230 row_shl:8 row_mask:0xf bank_mask:0xf bound_ctrl:0
	v_fmac_f32_dpp v107, v235, v231 row_shl:8 row_mask:0xf bank_mask:0xf bound_ctrl:0
	ds_read_b128 v[224:227], v18 offset:1728
	ds_read_b128 v[228:231], v18 offset:1984
	s_waitcnt lgkmcnt(2)
	v_mov_b32_e32 v232, v108
	v_mov_b32_e32 v233, v109
	v_mov_b32_e32 v234, v110
	v_mov_b32_e32 v235, v111
	v_fmac_f32_dpp v108, v108, v188 row_shl:8 row_mask:0xf bank_mask:0xf bound_ctrl:0
	v_fmac_f32_dpp v109, v109, v189 row_shl:8 row_mask:0xf bank_mask:0xf bound_ctrl:0
	v_fmac_f32_dpp v110, v110, v190 row_shl:8 row_mask:0xf bank_mask:0xf bound_ctrl:0
	v_fmac_f32_dpp v111, v111, v191 row_shl:8 row_mask:0xf bank_mask:0xf bound_ctrl:0
	v_fmac_f32_dpp v108, v112, -v192 row_shl:8 row_mask:0xf bank_mask:0xf bound_ctrl:0
	v_fmac_f32_dpp v109, v113, -v193 row_shl:8 row_mask:0xf bank_mask:0xf bound_ctrl:0
	v_fmac_f32_dpp v110, v114, -v194 row_shl:8 row_mask:0xf bank_mask:0xf bound_ctrl:0
	v_fmac_f32_dpp v111, v115, -v195 row_shl:8 row_mask:0xf bank_mask:0xf bound_ctrl:0
	v_fmac_f32_dpp v112, v112, v188 row_shl:8 row_mask:0xf bank_mask:0xf bound_ctrl:0
	v_fmac_f32_dpp v113, v113, v189 row_shl:8 row_mask:0xf bank_mask:0xf bound_ctrl:0
	v_fmac_f32_dpp v114, v114, v190 row_shl:8 row_mask:0xf bank_mask:0xf bound_ctrl:0
	v_fmac_f32_dpp v115, v115, v191 row_shl:8 row_mask:0xf bank_mask:0xf bound_ctrl:0
	v_fmac_f32_dpp v112, v232, v192 row_shl:8 row_mask:0xf bank_mask:0xf bound_ctrl:0
	v_fmac_f32_dpp v113, v233, v193 row_shl:8 row_mask:0xf bank_mask:0xf bound_ctrl:0
	v_fmac_f32_dpp v114, v234, v194 row_shl:8 row_mask:0xf bank_mask:0xf bound_ctrl:0
	v_fmac_f32_dpp v115, v235, v195 row_shl:8 row_mask:0xf bank_mask:0xf bound_ctrl:0
	s_waitcnt lgkmcnt(0)
	v_mov_b32_e32 v232, v116
	v_mov_b32_e32 v233, v117
	v_mov_b32_e32 v234, v118
	v_mov_b32_e32 v235, v119
	v_fmac_f32_dpp v116, v116, v224 row_shl:8 row_mask:0xf bank_mask:0xf bound_ctrl:0
	v_fmac_f32_dpp v117, v117, v225 row_shl:8 row_mask:0xf bank_mask:0xf bound_ctrl:0
	v_fmac_f32_dpp v118, v118, v226 row_shl:8 row_mask:0xf bank_mask:0xf bound_ctrl:0
	v_fmac_f32_dpp v119, v119, v227 row_shl:8 row_mask:0xf bank_mask:0xf bound_ctrl:0
	v_fmac_f32_dpp v116, v120, -v228 row_shl:8 row_mask:0xf bank_mask:0xf bound_ctrl:0
	v_fmac_f32_dpp v117, v121, -v229 row_shl:8 row_mask:0xf bank_mask:0xf bound_ctrl:0
	v_fmac_f32_dpp v118, v122, -v230 row_shl:8 row_mask:0xf bank_mask:0xf bound_ctrl:0
	v_fmac_f32_dpp v119, v123, -v231 row_shl:8 row_mask:0xf bank_mask:0xf bound_ctrl:0
	v_fmac_f32_dpp v120, v120, v224 row_shl:8 row_mask:0xf bank_mask:0xf bound_ctrl:0
	v_fmac_f32_dpp v121, v121, v225 row_shl:8 row_mask:0xf bank_mask:0xf bound_ctrl:0
	v_fmac_f32_dpp v122, v122, v226 row_shl:8 row_mask:0xf bank_mask:0xf bound_ctrl:0
	v_fmac_f32_dpp v123, v123, v227 row_shl:8 row_mask:0xf bank_mask:0xf bound_ctrl:0
	v_fmac_f32_dpp v120, v232, v228 row_shl:8 row_mask:0xf bank_mask:0xf bound_ctrl:0
	v_fmac_f32_dpp v121, v233, v229 row_shl:8 row_mask:0xf bank_mask:0xf bound_ctrl:0
	v_fmac_f32_dpp v122, v234, v230 row_shl:8 row_mask:0xf bank_mask:0xf bound_ctrl:0
	v_fmac_f32_dpp v123, v235, v231 row_shl:8 row_mask:0xf bank_mask:0xf bound_ctrl:0
	s_nop 1
	v_mov_b32_dpp v124, v92 row_newbcast:0 row_mask:0xf bank_mask:0xf
	v_mov_b32_dpp v125, v96 row_newbcast:0 row_mask:0xf bank_mask:0xf
	v_mov_b32_dpp v126, v93 row_newbcast:0 row_mask:0xf bank_mask:0xf
	v_mov_b32_dpp v127, v97 row_newbcast:0 row_mask:0xf bank_mask:0xf
	v_mov_b32_dpp v128, v94 row_newbcast:0 row_mask:0xf bank_mask:0xf
	v_mov_b32_dpp v129, v98 row_newbcast:0 row_mask:0xf bank_mask:0xf
	v_mov_b32_dpp v130, v95 row_newbcast:0 row_mask:0xf bank_mask:0xf
	v_mov_b32_dpp v131, v99 row_newbcast:0 row_mask:0xf bank_mask:0xf
	v_mov_b32_dpp v140, v100 row_newbcast:0 row_mask:0xf bank_mask:0xf
	v_mov_b32_dpp v141, v104 row_newbcast:0 row_mask:0xf bank_mask:0xf
	v_mov_b32_dpp v142, v101 row_newbcast:0 row_mask:0xf bank_mask:0xf
	v_mov_b32_dpp v143, v105 row_newbcast:0 row_mask:0xf bank_mask:0xf
	v_mov_b32_dpp v144, v102 row_newbcast:0 row_mask:0xf bank_mask:0xf
	v_mov_b32_dpp v145, v106 row_newbcast:0 row_mask:0xf bank_mask:0xf
	v_mov_b32_dpp v146, v103 row_newbcast:0 row_mask:0xf bank_mask:0xf
	v_mov_b32_dpp v147, v107 row_newbcast:0 row_mask:0xf bank_mask:0xf
	v_mov_b32_dpp v148, v108 row_newbcast:0 row_mask:0xf bank_mask:0xf
	v_mov_b32_dpp v149, v112 row_newbcast:0 row_mask:0xf bank_mask:0xf
	v_mov_b32_dpp v150, v109 row_newbcast:0 row_mask:0xf bank_mask:0xf
	v_mov_b32_dpp v151, v113 row_newbcast:0 row_mask:0xf bank_mask:0xf
	v_mov_b32_dpp v152, v110 row_newbcast:0 row_mask:0xf bank_mask:0xf
	v_mov_b32_dpp v153, v114 row_newbcast:0 row_mask:0xf bank_mask:0xf
	v_mov_b32_dpp v154, v111 row_newbcast:0 row_mask:0xf bank_mask:0xf
	v_mov_b32_dpp v155, v115 row_newbcast:0 row_mask:0xf bank_mask:0xf
	v_mov_b32_dpp v156, v116 row_newbcast:0 row_mask:0xf bank_mask:0xf
	v_mov_b32_dpp v157, v120 row_newbcast:0 row_mask:0xf bank_mask:0xf
	v_mov_b32_dpp v158, v117 row_newbcast:0 row_mask:0xf bank_mask:0xf
	v_mov_b32_dpp v159, v121 row_newbcast:0 row_mask:0xf bank_mask:0xf
	v_mov_b32_dpp v168, v118 row_newbcast:0 row_mask:0xf bank_mask:0xf
	v_mov_b32_dpp v169, v122 row_newbcast:0 row_mask:0xf bank_mask:0xf
	v_mov_b32_dpp v170, v119 row_newbcast:0 row_mask:0xf bank_mask:0xf
	v_mov_b32_dpp v171, v123 row_newbcast:0 row_mask:0xf bank_mask:0xf
	s_waitcnt vmcnt(7)
	s_waitcnt vmcnt(6)
	s_waitcnt vmcnt(5)
	s_waitcnt vmcnt(4)
	s_waitcnt vmcnt(3)
	s_waitcnt vmcnt(2)
	s_waitcnt vmcnt(1)
	s_waitcnt vmcnt(0)
	v_xor_b32_e32 v64, 0x80000000, v64
	v_xor_b32_e32 v65, 0x80000000, v65
	v_xor_b32_e32 v66, 0x80000000, v66
	v_xor_b32_e32 v67, 0x80000000, v67
	v_xor_b32_e32 v72, 0x80000000, v72
	v_xor_b32_e32 v73, 0x80000000, v73
	v_xor_b32_e32 v74, 0x80000000, v74
	v_xor_b32_e32 v75, 0x80000000, v75
	v_xor_b32_e32 v80, 0x80000000, v80
	v_xor_b32_e32 v81, 0x80000000, v81
	v_xor_b32_e32 v82, 0x80000000, v82
	v_xor_b32_e32 v83, 0x80000000, v83
	v_xor_b32_e32 v88, 0x80000000, v88
	v_xor_b32_e32 v89, 0x80000000, v89
	v_xor_b32_e32 v90, 0x80000000, v90
	v_xor_b32_e32 v91, 0x80000000, v91
	s_nop 1
	v_mfma_f32_16x16x4_f32 v[176:179], v92, v60, v[176:179]
	v_mfma_f32_16x16x4_f32 v[184:187], v96, v64, v[184:187]
	v_mfma_f32_16x16x4_f32 v[176:179], v93, v61, v[176:179]
	v_mfma_f32_16x16x4_f32 v[184:187], v97, v65, v[184:187]
	v_mfma_f32_16x16x4_f32 v[176:179], v94, v62, v[176:179]
	v_mfma_f32_16x16x4_f32 v[184:187], v98, v66, v[184:187]
	v_mfma_f32_16x16x4_f32 v[176:179], v95, v63, v[176:179]
	v_mfma_f32_16x16x4_f32 v[184:187], v99, v67, v[184:187]
	v_mfma_f32_16x16x4_f32 v[176:179], v100, v68, v[176:179]
	v_mfma_f32_16x16x4_f32 v[184:187], v104, v72, v[184:187]
	v_mfma_f32_16x16x4_f32 v[176:179], v101, v69, v[176:179]
	v_mfma_f32_16x16x4_f32 v[184:187], v105, v73, v[184:187]
	v_mfma_f32_16x16x4_f32 v[176:179], v102, v70, v[176:179]
	v_mfma_f32_16x16x4_f32 v[184:187], v106, v74, v[184:187]
	v_mfma_f32_16x16x4_f32 v[176:179], v103, v71, v[176:179]
	v_mfma_f32_16x16x4_f32 v[184:187], v107, v75, v[184:187]
	v_mfma_f32_16x16x4_f32 v[176:179], v108, v76, v[176:179]
	v_mfma_f32_16x16x4_f32 v[184:187], v112, v80, v[184:187]
	v_mfma_f32_16x16x4_f32 v[176:179], v109, v77, v[176:179]
	v_mfma_f32_16x16x4_f32 v[184:187], v113, v81, v[184:187]
	v_mfma_f32_16x16x4_f32 v[176:179], v110, v78, v[176:179]
	v_mfma_f32_16x16x4_f32 v[184:187], v114, v82, v[184:187]
	v_mfma_f32_16x16x4_f32 v[176:179], v111, v79, v[176:179]
	v_mfma_f32_16x16x4_f32 v[184:187], v115, v83, v[184:187]
	v_mfma_f32_16x16x4_f32 v[176:179], v116, v84, v[176:179]
	v_mfma_f32_16x16x4_f32 v[184:187], v120, v88, v[184:187]
	v_mfma_f32_16x16x4_f32 v[176:179], v117, v85, v[176:179]
	v_mfma_f32_16x16x4_f32 v[184:187], v121, v89, v[184:187]
	v_mfma_f32_16x16x4_f32 v[176:179], v118, v86, v[176:179]
	v_mfma_f32_16x16x4_f32 v[184:187], v122, v90, v[184:187]
	v_mfma_f32_16x16x4_f32 v[176:179], v119, v87, v[176:179]
	v_mfma_f32_16x16x4_f32 v[184:187], v123, v91, v[184:187]
	v_mfma_f32_16x16x4_f32 v[92:95], v28, v20, 0
	v_mfma_f32_16x16x4_f32 v[96:99], v29, v20, 0
	v_mfma_f32_16x16x4_f32 v[100:103], v36, v20, 0
	v_mfma_f32_16x16x4_f32 v[104:107], v37, v20, 0
	v_mfma_f32_16x16x4_f32 v[108:111], v44, v20, 0
	v_mfma_f32_16x16x4_f32 v[112:115], v45, v20, 0
	v_mfma_f32_16x16x4_f32 v[116:119], v52, v20, 0
	v_mfma_f32_16x16x4_f32 v[120:123], v53, v20, 0
	v_mfma_f32_16x16x4_f32 v[92:95], v30, v21, v[92:95]
	v_mfma_f32_16x16x4_f32 v[96:99], v31, v21, v[96:99]
	v_mfma_f32_16x16x4_f32 v[100:103], v38, v21, v[100:103]
	v_mfma_f32_16x16x4_f32 v[104:107], v39, v21, v[104:107]
	v_mfma_f32_16x16x4_f32 v[108:111], v46, v21, v[108:111]
	v_mfma_f32_16x16x4_f32 v[112:115], v47, v21, v[112:115]
	v_mfma_f32_16x16x4_f32 v[116:119], v54, v21, v[116:119]
	v_mfma_f32_16x16x4_f32 v[120:123], v55, v21, v[120:123]
	v_mfma_f32_16x16x4_f32 v[92:95], v32, v22, v[92:95]
	v_mfma_f32_16x16x4_f32 v[96:99], v33, v22, v[96:99]
	v_mfma_f32_16x16x4_f32 v[100:103], v40, v22, v[100:103]
	v_mfma_f32_16x16x4_f32 v[104:107], v41, v22, v[104:107]
	v_mfma_f32_16x16x4_f32 v[108:111], v48, v22, v[108:111]
	v_mfma_f32_16x16x4_f32 v[112:115], v49, v22, v[112:115]
	v_mfma_f32_16x16x4_f32 v[116:119], v56, v22, v[116:119]
	v_mfma_f32_16x16x4_f32 v[120:123], v57, v22, v[120:123]
	v_mfma_f32_16x16x4_f32 v[92:95], v34, v23, v[92:95]
	v_mfma_f32_16x16x4_f32 v[96:99], v35, v23, v[96:99]
	v_mfma_f32_16x16x4_f32 v[100:103], v42, v23, v[100:103]
	v_mfma_f32_16x16x4_f32 v[104:107], v43, v23, v[104:107]
	v_mfma_f32_16x16x4_f32 v[108:111], v50, v23, v[108:111]
	v_mfma_f32_16x16x4_f32 v[112:115], v51, v23, v[112:115]
	v_mfma_f32_16x16x4_f32 v[116:119], v58, v23, v[116:119]
	v_mfma_f32_16x16x4_f32 v[120:123], v59, v23, v[120:123]
	ds_read_b128 v[188:191], v18 offset:0
	ds_read_b128 v[192:195], v18 offset:256
	s_nop 9
	ds_read_b128 v[224:227], v18 offset:64
	ds_read_b128 v[228:231], v18 offset:320
	s_waitcnt lgkmcnt(2)
	s_mov_b64 exec, s[62:63]
	v_fmac_f32_e32 v92, v188, v124
	v_fmac_f32_e32 v93, v189, v126
	v_fmac_f32_e32 v94, v190, v128
	v_fmac_f32_e32 v95, v191, v130
	v_fma_f32 v92, -v192, v125, v92
	v_fma_f32 v93, -v193, v127, v93
	v_fma_f32 v94, -v194, v129, v94
	v_fma_f32 v95, -v195, v131, v95
	v_fmac_f32_e32 v96, v188, v125
	v_fmac_f32_e32 v97, v189, v127
	v_fmac_f32_e32 v98, v190, v129
	v_fmac_f32_e32 v99, v191, v131
	v_fmac_f32_e32 v96, v192, v124
	v_fmac_f32_e32 v97, v193, v126
	v_fmac_f32_e32 v98, v194, v128
	v_fmac_f32_e32 v99, v195, v130
	s_mov_b64 exec, -1
	v_mov_b32_e32 v232, v92
	v_mov_b32_e32 v233, v93
	v_mov_b32_e32 v234, v94
	v_mov_b32_e32 v235, v95
	s_nop 1
	v_fmac_f32_dpp v92, v92, v188 row_shl:1 row_mask:0xf bank_mask:0xf bound_ctrl:0
	v_fmac_f32_dpp v93, v93, v189 row_shl:1 row_mask:0xf bank_mask:0xf bound_ctrl:0
	v_fmac_f32_dpp v94, v94, v190 row_shl:1 row_mask:0xf bank_mask:0xf bound_ctrl:0
	v_fmac_f32_dpp v95, v95, v191 row_shl:1 row_mask:0xf bank_mask:0xf bound_ctrl:0
	v_fmac_f32_dpp v92, v96, -v192 row_shl:1 row_mask:0xf bank_mask:0xf bound_ctrl:0
	v_fmac_f32_dpp v93, v97, -v193 row_shl:1 row_mask:0xf bank_mask:0xf bound_ctrl:0
	v_fmac_f32_dpp v94, v98, -v194 row_shl:1 row_mask:0xf bank_mask:0xf bound_ctrl:0
	v_fmac_f32_dpp v95, v99, -v195 row_shl:1 row_mask:0xf bank_mask:0xf bound_ctrl:0
	v_fmac_f32_dpp v96, v96, v188 row_shl:1 row_mask:0xf bank_mask:0xf bound_ctrl:0
	v_fmac_f32_dpp v97, v97, v189 row_shl:1 row_mask:0xf bank_mask:0xf bound_ctrl:0
	v_fmac_f32_dpp v98, v98, v190 row_shl:1 row_mask:0xf bank_mask:0xf bound_ctrl:0
	v_fmac_f32_dpp v99, v99, v191 row_shl:1 row_mask:0xf bank_mask:0xf bound_ctrl:0
	v_fmac_f32_dpp v96, v232, v192 row_shl:1 row_mask:0xf bank_mask:0xf bound_ctrl:0
	v_fmac_f32_dpp v97, v233, v193 row_shl:1 row_mask:0xf bank_mask:0xf bound_ctrl:0
	v_fmac_f32_dpp v98, v234, v194 row_shl:1 row_mask:0xf bank_mask:0xf bound_ctrl:0
	v_fmac_f32_dpp v99, v235, v195 row_shl:1 row_mask:0xf bank_mask:0xf bound_ctrl:0
	ds_read_b128 v[188:191], v18 offset:128
	ds_read_b128 v[192:195], v18 offset:384
	s_waitcnt lgkmcnt(2)
	s_mov_b64 exec, s[62:63]
	v_fmac_f32_e32 v100, v224, v140
	v_fmac_f32_e32 v101, v225, v142
	v_fmac_f32_e32 v102, v226, v144
	v_fmac_f32_e32 v103, v227, v146
	v_fma_f32 v100, -v228, v141, v100
	v_fma_f32 v101, -v229, v143, v101
	v_fma_f32 v102, -v230, v145, v102
	v_fma_f32 v103, -v231, v147, v103
	v_fmac_f32_e32 v104, v224, v141
	v_fmac_f32_e32 v105, v225, v143
	v_fmac_f32_e32 v106, v226, v145
	v_fmac_f32_e32 v107, v227, v147
	v_fmac_f32_e32 v104, v228, v140
	v_fmac_f32_e32 v105, v229, v142
	v_fmac_f32_e32 v106, v230, v144
	v_fmac_f32_e32 v107, v231, v146
	s_mov_b64 exec, -1
	v_mov_b32_e32 v232, v100
	v_mov_b32_e32 v233, v101
	v_mov_b32_e32 v234, v102
	v_mov_b32_e32 v235, v103
	s_nop 1
	v_fmac_f32_dpp v100, v100, v224 row_shl:1 row_mask:0xf bank_mask:0xf bound_ctrl:0
	v_fmac_f32_dpp v101, v101, v225 row_shl:1 row_mask:0xf bank_mask:0xf bound_ctrl:0
	v_fmac_f32_dpp v102, v102, v226 row_shl:1 row_mask:0xf bank_mask:0xf bound_ctrl:0
	v_fmac_f32_dpp v103, v103, v227 row_shl:1 row_mask:0xf bank_mask:0xf bound_ctrl:0
	v_fmac_f32_dpp v100, v104, -v228 row_shl:1 row_mask:0xf bank_mask:0xf bound_ctrl:0
	v_fmac_f32_dpp v101, v105, -v229 row_shl:1 row_mask:0xf bank_mask:0xf bound_ctrl:0
	v_fmac_f32_dpp v102, v106, -v230 row_shl:1 row_mask:0xf bank_mask:0xf bound_ctrl:0
	v_fmac_f32_dpp v103, v107, -v231 row_shl:1 row_mask:0xf bank_mask:0xf bound_ctrl:0
	v_fmac_f32_dpp v104, v104, v224 row_shl:1 row_mask:0xf bank_mask:0xf bound_ctrl:0
	v_fmac_f32_dpp v105, v105, v225 row_shl:1 row_mask:0xf bank_mask:0xf bound_ctrl:0
	v_fmac_f32_dpp v106, v106, v226 row_shl:1 row_mask:0xf bank_mask:0xf bound_ctrl:0
	v_fmac_f32_dpp v107, v107, v227 row_shl:1 row_mask:0xf bank_mask:0xf bound_ctrl:0
	v_fmac_f32_dpp v104, v232, v228 row_shl:1 row_mask:0xf bank_mask:0xf bound_ctrl:0
	v_fmac_f32_dpp v105, v233, v229 row_shl:1 row_mask:0xf bank_mask:0xf bound_ctrl:0
	v_fmac_f32_dpp v106, v234, v230 row_shl:1 row_mask:0xf bank_mask:0xf bound_ctrl:0
	v_fmac_f32_dpp v107, v235, v231 row_shl:1 row_mask:0xf bank_mask:0xf bound_ctrl:0
	ds_read_b128 v[224:227], v18 offset:192
	ds_read_b128 v[228:231], v18 offset:448
	s_waitcnt lgkmcnt(2)
	s_mov_b64 exec, s[62:63]
	v_fmac_f32_e32 v108, v188, v148
	v_fmac_f32_e32 v109, v189, v150
	v_fmac_f32_e32 v110, v190, v152
	v_fmac_f32_e32 v111, v191, v154
	v_fma_f32 v108, -v192, v149, v108
	v_fma_f32 v109, -v193, v151, v109
	v_fma_f32 v110, -v194, v153, v110
	v_fma_f32 v111, -v195, v155, v111
	v_fmac_f32_e32 v112, v188, v149
	v_fmac_f32_e32 v113, v189, v151
	v_fmac_f32_e32 v114, v190, v153
	v_fmac_f32_e32 v115, v191, v155
	v_fmac_f32_e32 v112, v192, v148
	v_fmac_f32_e32 v113, v193, v150
	v_fmac_f32_e32 v114, v194, v152
	v_fmac_f32_e32 v115, v195, v154
	s_mov_b64 exec, -1
	v_mov_b32_e32 v232, v108
	v_mov_b32_e32 v233, v109
	v_mov_b32_e32 v234, v110
	v_mov_b32_e32 v235, v111
	s_nop 1
	v_fmac_f32_dpp v108, v108, v188 row_shl:1 row_mask:0xf bank_mask:0xf bound_ctrl:0
	v_fmac_f32_dpp v109, v109, v189 row_shl:1 row_mask:0xf bank_mask:0xf bound_ctrl:0
	v_fmac_f32_dpp v110, v110, v190 row_shl:1 row_mask:0xf bank_mask:0xf bound_ctrl:0
	v_fmac_f32_dpp v111, v111, v191 row_shl:1 row_mask:0xf bank_mask:0xf bound_ctrl:0
	v_fmac_f32_dpp v108, v112, -v192 row_shl:1 row_mask:0xf bank_mask:0xf bound_ctrl:0
	v_fmac_f32_dpp v109, v113, -v193 row_shl:1 row_mask:0xf bank_mask:0xf bound_ctrl:0
	v_fmac_f32_dpp v110, v114, -v194 row_shl:1 row_mask:0xf bank_mask:0xf bound_ctrl:0
	v_fmac_f32_dpp v111, v115, -v195 row_shl:1 row_mask:0xf bank_mask:0xf bound_ctrl:0
	v_fmac_f32_dpp v112, v112, v188 row_shl:1 row_mask:0xf bank_mask:0xf bound_ctrl:0
	v_fmac_f32_dpp v113, v113, v189 row_shl:1 row_mask:0xf bank_mask:0xf bound_ctrl:0
	v_fmac_f32_dpp v114, v114, v190 row_shl:1 row_mask:0xf bank_mask:0xf bound_ctrl:0
	v_fmac_f32_dpp v115, v115, v191 row_shl:1 row_mask:0xf bank_mask:0xf bound_ctrl:0
	v_fmac_f32_dpp v112, v232, v192 row_shl:1 row_mask:0xf bank_mask:0xf bound_ctrl:0
	v_fmac_f32_dpp v113, v233, v193 row_shl:1 row_mask:0xf bank_mask:0xf bound_ctrl:0
	v_fmac_f32_dpp v114, v234, v194 row_shl:1 row_mask:0xf bank_mask:0xf bound_ctrl:0
	v_fmac_f32_dpp v115, v235, v195 row_shl:1 row_mask:0xf bank_mask:0xf bound_ctrl:0
	ds_read_b128 v[188:191], v18 offset:512
	ds_read_b128 v[192:195], v18 offset:768
	s_waitcnt lgkmcnt(2)
	s_mov_b64 exec, s[62:63]
	v_fmac_f32_e32 v116, v224, v156
	v_fmac_f32_e32 v117, v225, v158
	v_fmac_f32_e32 v118, v226, v168
	v_fmac_f32_e32 v119, v227, v170
	v_fma_f32 v116, -v228, v157, v116
	v_fma_f32 v117, -v229, v159, v117
	v_fma_f32 v118, -v230, v169, v118
	v_fma_f32 v119, -v231, v171, v119
	v_fmac_f32_e32 v120, v224, v157
	v_fmac_f32_e32 v121, v225, v159
	v_fmac_f32_e32 v122, v226, v169
	v_fmac_f32_e32 v123, v227, v171
	v_fmac_f32_e32 v120, v228, v156
	v_fmac_f32_e32 v121, v229, v158
	v_fmac_f32_e32 v122, v230, v168
	v_fmac_f32_e32 v123, v231, v170
	s_mov_b64 exec, -1
	v_mov_b32_e32 v232, v116
	v_mov_b32_e32 v233, v117
	v_mov_b32_e32 v234, v118
	v_mov_b32_e32 v235, v119
	s_nop 1
	v_fmac_f32_dpp v116, v116, v224 row_shl:1 row_mask:0xf bank_mask:0xf bound_ctrl:0
	v_fmac_f32_dpp v117, v117, v225 row_shl:1 row_mask:0xf bank_mask:0xf bound_ctrl:0
	v_fmac_f32_dpp v118, v118, v226 row_shl:1 row_mask:0xf bank_mask:0xf bound_ctrl:0
	v_fmac_f32_dpp v119, v119, v227 row_shl:1 row_mask:0xf bank_mask:0xf bound_ctrl:0
	v_fmac_f32_dpp v116, v120, -v228 row_shl:1 row_mask:0xf bank_mask:0xf bound_ctrl:0
	v_fmac_f32_dpp v117, v121, -v229 row_shl:1 row_mask:0xf bank_mask:0xf bound_ctrl:0
	v_fmac_f32_dpp v118, v122, -v230 row_shl:1 row_mask:0xf bank_mask:0xf bound_ctrl:0
	v_fmac_f32_dpp v119, v123, -v231 row_shl:1 row_mask:0xf bank_mask:0xf bound_ctrl:0
	v_fmac_f32_dpp v120, v120, v224 row_shl:1 row_mask:0xf bank_mask:0xf bound_ctrl:0
	v_fmac_f32_dpp v121, v121, v225 row_shl:1 row_mask:0xf bank_mask:0xf bound_ctrl:0
	v_fmac_f32_dpp v122, v122, v226 row_shl:1 row_mask:0xf bank_mask:0xf bound_ctrl:0
	v_fmac_f32_dpp v123, v123, v227 row_shl:1 row_mask:0xf bank_mask:0xf bound_ctrl:0
	v_fmac_f32_dpp v120, v232, v228 row_shl:1 row_mask:0xf bank_mask:0xf bound_ctrl:0
	v_fmac_f32_dpp v121, v233, v229 row_shl:1 row_mask:0xf bank_mask:0xf bound_ctrl:0
	v_fmac_f32_dpp v122, v234, v230 row_shl:1 row_mask:0xf bank_mask:0xf bound_ctrl:0
	v_fmac_f32_dpp v123, v235, v231 row_shl:1 row_mask:0xf bank_mask:0xf bound_ctrl:0
	ds_read_b128 v[224:227], v18 offset:576
	ds_read_b128 v[228:231], v18 offset:832
	s_waitcnt lgkmcnt(2)
	v_mov_b32_e32 v232, v92
	v_mov_b32_e32 v233, v93
	v_mov_b32_e32 v234, v94
	v_mov_b32_e32 v235, v95
	v_fmac_f32_dpp v92, v92, v188 row_shl:2 row_mask:0xf bank_mask:0xf bound_ctrl:0
	v_fmac_f32_dpp v93, v93, v189 row_shl:2 row_mask:0xf bank_mask:0xf bound_ctrl:0
	v_fmac_f32_dpp v94, v94, v190 row_shl:2 row_mask:0xf bank_mask:0xf bound_ctrl:0
	v_fmac_f32_dpp v95, v95, v191 row_shl:2 row_mask:0xf bank_mask:0xf bound_ctrl:0
	v_fmac_f32_dpp v92, v96, -v192 row_shl:2 row_mask:0xf bank_mask:0xf bound_ctrl:0
	v_fmac_f32_dpp v93, v97, -v193 row_shl:2 row_mask:0xf bank_mask:0xf bound_ctrl:0
	v_fmac_f32_dpp v94, v98, -v194 row_shl:2 row_mask:0xf bank_mask:0xf bound_ctrl:0
	v_fmac_f32_dpp v95, v99, -v195 row_shl:2 row_mask:0xf bank_mask:0xf bound_ctrl:0
	v_fmac_f32_dpp v96, v96, v188 row_shl:2 row_mask:0xf bank_mask:0xf bound_ctrl:0
	v_fmac_f32_dpp v97, v97, v189 row_shl:2 row_mask:0xf bank_mask:0xf bound_ctrl:0
	v_fmac_f32_dpp v98, v98, v190 row_shl:2 row_mask:0xf bank_mask:0xf bound_ctrl:0
	v_fmac_f32_dpp v99, v99, v191 row_shl:2 row_mask:0xf bank_mask:0xf bound_ctrl:0
	v_fmac_f32_dpp v96, v232, v192 row_shl:2 row_mask:0xf bank_mask:0xf bound_ctrl:0
	v_fmac_f32_dpp v97, v233, v193 row_shl:2 row_mask:0xf bank_mask:0xf bound_ctrl:0
	v_fmac_f32_dpp v98, v234, v194 row_shl:2 row_mask:0xf bank_mask:0xf bound_ctrl:0
	v_fmac_f32_dpp v99, v235, v195 row_shl:2 row_mask:0xf bank_mask:0xf bound_ctrl:0
	ds_read_b128 v[188:191], v18 offset:640
	ds_read_b128 v[192:195], v18 offset:896
	s_waitcnt lgkmcnt(2)
	v_mov_b32_e32 v232, v100
	v_mov_b32_e32 v233, v101
	v_mov_b32_e32 v234, v102
	v_mov_b32_e32 v235, v103
	v_fmac_f32_dpp v100, v100, v224 row_shl:2 row_mask:0xf bank_mask:0xf bound_ctrl:0
	v_fmac_f32_dpp v101, v101, v225 row_shl:2 row_mask:0xf bank_mask:0xf bound_ctrl:0
	v_fmac_f32_dpp v102, v102, v226 row_shl:2 row_mask:0xf bank_mask:0xf bound_ctrl:0
	v_fmac_f32_dpp v103, v103, v227 row_shl:2 row_mask:0xf bank_mask:0xf bound_ctrl:0
	v_fmac_f32_dpp v100, v104, -v228 row_shl:2 row_mask:0xf bank_mask:0xf bound_ctrl:0
	v_fmac_f32_dpp v101, v105, -v229 row_shl:2 row_mask:0xf bank_mask:0xf bound_ctrl:0
	v_fmac_f32_dpp v102, v106, -v230 row_shl:2 row_mask:0xf bank_mask:0xf bound_ctrl:0
	v_fmac_f32_dpp v103, v107, -v231 row_shl:2 row_mask:0xf bank_mask:0xf bound_ctrl:0
	v_fmac_f32_dpp v104, v104, v224 row_shl:2 row_mask:0xf bank_mask:0xf bound_ctrl:0
	v_fmac_f32_dpp v105, v105, v225 row_shl:2 row_mask:0xf bank_mask:0xf bound_ctrl:0
	v_fmac_f32_dpp v106, v106, v226 row_shl:2 row_mask:0xf bank_mask:0xf bound_ctrl:0
	v_fmac_f32_dpp v107, v107, v227 row_shl:2 row_mask:0xf bank_mask:0xf bound_ctrl:0
	v_fmac_f32_dpp v104, v232, v228 row_shl:2 row_mask:0xf bank_mask:0xf bound_ctrl:0
	v_fmac_f32_dpp v105, v233, v229 row_shl:2 row_mask:0xf bank_mask:0xf bound_ctrl:0
	v_fmac_f32_dpp v106, v234, v230 row_shl:2 row_mask:0xf bank_mask:0xf bound_ctrl:0
	v_fmac_f32_dpp v107, v235, v231 row_shl:2 row_mask:0xf bank_mask:0xf bound_ctrl:0
	ds_read_b128 v[224:227], v18 offset:704
	ds_read_b128 v[228:231], v18 offset:960
	s_waitcnt lgkmcnt(2)
	v_mov_b32_e32 v232, v108
	v_mov_b32_e32 v233, v109
	v_mov_b32_e32 v234, v110
	v_mov_b32_e32 v235, v111
	v_fmac_f32_dpp v108, v108, v188 row_shl:2 row_mask:0xf bank_mask:0xf bound_ctrl:0
	v_fmac_f32_dpp v109, v109, v189 row_shl:2 row_mask:0xf bank_mask:0xf bound_ctrl:0
	v_fmac_f32_dpp v110, v110, v190 row_shl:2 row_mask:0xf bank_mask:0xf bound_ctrl:0
	v_fmac_f32_dpp v111, v111, v191 row_shl:2 row_mask:0xf bank_mask:0xf bound_ctrl:0
	v_fmac_f32_dpp v108, v112, -v192 row_shl:2 row_mask:0xf bank_mask:0xf bound_ctrl:0
	v_fmac_f32_dpp v109, v113, -v193 row_shl:2 row_mask:0xf bank_mask:0xf bound_ctrl:0
	v_fmac_f32_dpp v110, v114, -v194 row_shl:2 row_mask:0xf bank_mask:0xf bound_ctrl:0
	v_fmac_f32_dpp v111, v115, -v195 row_shl:2 row_mask:0xf bank_mask:0xf bound_ctrl:0
	v_fmac_f32_dpp v112, v112, v188 row_shl:2 row_mask:0xf bank_mask:0xf bound_ctrl:0
	v_fmac_f32_dpp v113, v113, v189 row_shl:2 row_mask:0xf bank_mask:0xf bound_ctrl:0
	v_fmac_f32_dpp v114, v114, v190 row_shl:2 row_mask:0xf bank_mask:0xf bound_ctrl:0
	v_fmac_f32_dpp v115, v115, v191 row_shl:2 row_mask:0xf bank_mask:0xf bound_ctrl:0
	v_fmac_f32_dpp v112, v232, v192 row_shl:2 row_mask:0xf bank_mask:0xf bound_ctrl:0
	v_fmac_f32_dpp v113, v233, v193 row_shl:2 row_mask:0xf bank_mask:0xf bound_ctrl:0
	v_fmac_f32_dpp v114, v234, v194 row_shl:2 row_mask:0xf bank_mask:0xf bound_ctrl:0
	v_fmac_f32_dpp v115, v235, v195 row_shl:2 row_mask:0xf bank_mask:0xf bound_ctrl:0
	ds_read_b128 v[188:191], v18 offset:1024
	ds_read_b128 v[192:195], v18 offset:1280
	s_waitcnt lgkmcnt(2)
	v_mov_b32_e32 v232, v116
	v_mov_b32_e32 v233, v117
	v_mov_b32_e32 v234, v118
	v_mov_b32_e32 v235, v119
	v_fmac_f32_dpp v116, v116, v224 row_shl:2 row_mask:0xf bank_mask:0xf bound_ctrl:0
	v_fmac_f32_dpp v117, v117, v225 row_shl:2 row_mask:0xf bank_mask:0xf bound_ctrl:0
	v_fmac_f32_dpp v118, v118, v226 row_shl:2 row_mask:0xf bank_mask:0xf bound_ctrl:0
	v_fmac_f32_dpp v119, v119, v227 row_shl:2 row_mask:0xf bank_mask:0xf bound_ctrl:0
	v_fmac_f32_dpp v116, v120, -v228 row_shl:2 row_mask:0xf bank_mask:0xf bound_ctrl:0
	v_fmac_f32_dpp v117, v121, -v229 row_shl:2 row_mask:0xf bank_mask:0xf bound_ctrl:0
	v_fmac_f32_dpp v118, v122, -v230 row_shl:2 row_mask:0xf bank_mask:0xf bound_ctrl:0
	v_fmac_f32_dpp v119, v123, -v231 row_shl:2 row_mask:0xf bank_mask:0xf bound_ctrl:0
	v_fmac_f32_dpp v120, v120, v224 row_shl:2 row_mask:0xf bank_mask:0xf bound_ctrl:0
	v_fmac_f32_dpp v121, v121, v225 row_shl:2 row_mask:0xf bank_mask:0xf bound_ctrl:0
	v_fmac_f32_dpp v122, v122, v226 row_shl:2 row_mask:0xf bank_mask:0xf bound_ctrl:0
	v_fmac_f32_dpp v123, v123, v227 row_shl:2 row_mask:0xf bank_mask:0xf bound_ctrl:0
	v_fmac_f32_dpp v120, v232, v228 row_shl:2 row_mask:0xf bank_mask:0xf bound_ctrl:0
	v_fmac_f32_dpp v121, v233, v229 row_shl:2 row_mask:0xf bank_mask:0xf bound_ctrl:0
	v_fmac_f32_dpp v122, v234, v230 row_shl:2 row_mask:0xf bank_mask:0xf bound_ctrl:0
	v_fmac_f32_dpp v123, v235, v231 row_shl:2 row_mask:0xf bank_mask:0xf bound_ctrl:0
	ds_read_b128 v[224:227], v18 offset:1088
	ds_read_b128 v[228:231], v18 offset:1344
	s_waitcnt lgkmcnt(2)
	v_mov_b32_e32 v232, v92
	v_mov_b32_e32 v233, v93
	v_mov_b32_e32 v234, v94
	v_mov_b32_e32 v235, v95
	v_fmac_f32_dpp v92, v92, v188 row_shl:4 row_mask:0xf bank_mask:0xf bound_ctrl:0
	v_fmac_f32_dpp v93, v93, v189 row_shl:4 row_mask:0xf bank_mask:0xf bound_ctrl:0
	v_fmac_f32_dpp v94, v94, v190 row_shl:4 row_mask:0xf bank_mask:0xf bound_ctrl:0
	v_fmac_f32_dpp v95, v95, v191 row_shl:4 row_mask:0xf bank_mask:0xf bound_ctrl:0
	v_fmac_f32_dpp v92, v96, -v192 row_shl:4 row_mask:0xf bank_mask:0xf bound_ctrl:0
	v_fmac_f32_dpp v93, v97, -v193 row_shl:4 row_mask:0xf bank_mask:0xf bound_ctrl:0
	v_fmac_f32_dpp v94, v98, -v194 row_shl:4 row_mask:0xf bank_mask:0xf bound_ctrl:0
	v_fmac_f32_dpp v95, v99, -v195 row_shl:4 row_mask:0xf bank_mask:0xf bound_ctrl:0
	v_fmac_f32_dpp v96, v96, v188 row_shl:4 row_mask:0xf bank_mask:0xf bound_ctrl:0
	v_fmac_f32_dpp v97, v97, v189 row_shl:4 row_mask:0xf bank_mask:0xf bound_ctrl:0
	v_fmac_f32_dpp v98, v98, v190 row_shl:4 row_mask:0xf bank_mask:0xf bound_ctrl:0
	v_fmac_f32_dpp v99, v99, v191 row_shl:4 row_mask:0xf bank_mask:0xf bound_ctrl:0
	v_fmac_f32_dpp v96, v232, v192 row_shl:4 row_mask:0xf bank_mask:0xf bound_ctrl:0
	v_fmac_f32_dpp v97, v233, v193 row_shl:4 row_mask:0xf bank_mask:0xf bound_ctrl:0
	v_fmac_f32_dpp v98, v234, v194 row_shl:4 row_mask:0xf bank_mask:0xf bound_ctrl:0
	v_fmac_f32_dpp v99, v235, v195 row_shl:4 row_mask:0xf bank_mask:0xf bound_ctrl:0
	ds_read_b128 v[188:191], v18 offset:1152
	ds_read_b128 v[192:195], v18 offset:1408
	s_waitcnt lgkmcnt(2)
	v_mov_b32_e32 v232, v100
	v_mov_b32_e32 v233, v101
	v_mov_b32_e32 v234, v102
	v_mov_b32_e32 v235, v103
	v_fmac_f32_dpp v100, v100, v224 row_shl:4 row_mask:0xf bank_mask:0xf bound_ctrl:0
	v_fmac_f32_dpp v101, v101, v225 row_shl:4 row_mask:0xf bank_mask:0xf bound_ctrl:0
	v_fmac_f32_dpp v102, v102, v226 row_shl:4 row_mask:0xf bank_mask:0xf bound_ctrl:0
	v_fmac_f32_dpp v103, v103, v227 row_shl:4 row_mask:0xf bank_mask:0xf bound_ctrl:0
	v_fmac_f32_dpp v100, v104, -v228 row_shl:4 row_mask:0xf bank_mask:0xf bound_ctrl:0
	v_fmac_f32_dpp v101, v105, -v229 row_shl:4 row_mask:0xf bank_mask:0xf bound_ctrl:0
	v_fmac_f32_dpp v102, v106, -v230 row_shl:4 row_mask:0xf bank_mask:0xf bound_ctrl:0
	v_fmac_f32_dpp v103, v107, -v231 row_shl:4 row_mask:0xf bank_mask:0xf bound_ctrl:0
	v_fmac_f32_dpp v104, v104, v224 row_shl:4 row_mask:0xf bank_mask:0xf bound_ctrl:0
	v_fmac_f32_dpp v105, v105, v225 row_shl:4 row_mask:0xf bank_mask:0xf bound_ctrl:0
	v_fmac_f32_dpp v106, v106, v226 row_shl:4 row_mask:0xf bank_mask:0xf bound_ctrl:0
	v_fmac_f32_dpp v107, v107, v227 row_shl:4 row_mask:0xf bank_mask:0xf bound_ctrl:0
	v_fmac_f32_dpp v104, v232, v228 row_shl:4 row_mask:0xf bank_mask:0xf bound_ctrl:0
	v_fmac_f32_dpp v105, v233, v229 row_shl:4 row_mask:0xf bank_mask:0xf bound_ctrl:0
	v_fmac_f32_dpp v106, v234, v230 row_shl:4 row_mask:0xf bank_mask:0xf bound_ctrl:0
	v_fmac_f32_dpp v107, v235, v231 row_shl:4 row_mask:0xf bank_mask:0xf bound_ctrl:0
	ds_read_b128 v[224:227], v18 offset:1216
	ds_read_b128 v[228:231], v18 offset:1472
	s_waitcnt lgkmcnt(2)
	v_mov_b32_e32 v232, v108
	v_mov_b32_e32 v233, v109
	v_mov_b32_e32 v234, v110
	v_mov_b32_e32 v235, v111
	v_fmac_f32_dpp v108, v108, v188 row_shl:4 row_mask:0xf bank_mask:0xf bound_ctrl:0
	v_fmac_f32_dpp v109, v109, v189 row_shl:4 row_mask:0xf bank_mask:0xf bound_ctrl:0
	v_fmac_f32_dpp v110, v110, v190 row_shl:4 row_mask:0xf bank_mask:0xf bound_ctrl:0
	v_fmac_f32_dpp v111, v111, v191 row_shl:4 row_mask:0xf bank_mask:0xf bound_ctrl:0
	v_fmac_f32_dpp v108, v112, -v192 row_shl:4 row_mask:0xf bank_mask:0xf bound_ctrl:0
	v_fmac_f32_dpp v109, v113, -v193 row_shl:4 row_mask:0xf bank_mask:0xf bound_ctrl:0
	v_fmac_f32_dpp v110, v114, -v194 row_shl:4 row_mask:0xf bank_mask:0xf bound_ctrl:0
	v_fmac_f32_dpp v111, v115, -v195 row_shl:4 row_mask:0xf bank_mask:0xf bound_ctrl:0
	v_fmac_f32_dpp v112, v112, v188 row_shl:4 row_mask:0xf bank_mask:0xf bound_ctrl:0
	v_fmac_f32_dpp v113, v113, v189 row_shl:4 row_mask:0xf bank_mask:0xf bound_ctrl:0
	v_fmac_f32_dpp v114, v114, v190 row_shl:4 row_mask:0xf bank_mask:0xf bound_ctrl:0
	v_fmac_f32_dpp v115, v115, v191 row_shl:4 row_mask:0xf bank_mask:0xf bound_ctrl:0
	v_fmac_f32_dpp v112, v232, v192 row_shl:4 row_mask:0xf bank_mask:0xf bound_ctrl:0
	v_fmac_f32_dpp v113, v233, v193 row_shl:4 row_mask:0xf bank_mask:0xf bound_ctrl:0
	v_fmac_f32_dpp v114, v234, v194 row_shl:4 row_mask:0xf bank_mask:0xf bound_ctrl:0
	v_fmac_f32_dpp v115, v235, v195 row_shl:4 row_mask:0xf bank_mask:0xf bound_ctrl:0
	ds_read_b128 v[188:191], v18 offset:1536
	ds_read_b128 v[192:195], v18 offset:1792
	s_waitcnt lgkmcnt(2)
	v_mov_b32_e32 v232, v116
	v_mov_b32_e32 v233, v117
	v_mov_b32_e32 v234, v118
	v_mov_b32_e32 v235, v119
	v_fmac_f32_dpp v116, v116, v224 row_shl:4 row_mask:0xf bank_mask:0xf bound_ctrl:0
	v_fmac_f32_dpp v117, v117, v225 row_shl:4 row_mask:0xf bank_mask:0xf bound_ctrl:0
	v_fmac_f32_dpp v118, v118, v226 row_shl:4 row_mask:0xf bank_mask:0xf bound_ctrl:0
	v_fmac_f32_dpp v119, v119, v227 row_shl:4 row_mask:0xf bank_mask:0xf bound_ctrl:0
	v_fmac_f32_dpp v116, v120, -v228 row_shl:4 row_mask:0xf bank_mask:0xf bound_ctrl:0
	v_fmac_f32_dpp v117, v121, -v229 row_shl:4 row_mask:0xf bank_mask:0xf bound_ctrl:0
	v_fmac_f32_dpp v118, v122, -v230 row_shl:4 row_mask:0xf bank_mask:0xf bound_ctrl:0
	v_fmac_f32_dpp v119, v123, -v231 row_shl:4 row_mask:0xf bank_mask:0xf bound_ctrl:0
	v_fmac_f32_dpp v120, v120, v224 row_shl:4 row_mask:0xf bank_mask:0xf bound_ctrl:0
	v_fmac_f32_dpp v121, v121, v225 row_shl:4 row_mask:0xf bank_mask:0xf bound_ctrl:0
	v_fmac_f32_dpp v122, v122, v226 row_shl:4 row_mask:0xf bank_mask:0xf bound_ctrl:0
	v_fmac_f32_dpp v123, v123, v227 row_shl:4 row_mask:0xf bank_mask:0xf bound_ctrl:0
	v_fmac_f32_dpp v120, v232, v228 row_shl:4 row_mask:0xf bank_mask:0xf bound_ctrl:0
	v_fmac_f32_dpp v121, v233, v229 row_shl:4 row_mask:0xf bank_mask:0xf bound_ctrl:0
	v_fmac_f32_dpp v122, v234, v230 row_shl:4 row_mask:0xf bank_mask:0xf bound_ctrl:0
	v_fmac_f32_dpp v123, v235, v231 row_shl:4 row_mask:0xf bank_mask:0xf bound_ctrl:0
	ds_read_b128 v[224:227], v18 offset:1600
	ds_read_b128 v[228:231], v18 offset:1856
	s_waitcnt lgkmcnt(2)
	v_mov_b32_e32 v232, v92
	v_mov_b32_e32 v233, v93
	v_mov_b32_e32 v234, v94
	v_mov_b32_e32 v235, v95
	v_fmac_f32_dpp v92, v92, v188 row_shl:8 row_mask:0xf bank_mask:0xf bound_ctrl:0
	v_fmac_f32_dpp v93, v93, v189 row_shl:8 row_mask:0xf bank_mask:0xf bound_ctrl:0
	v_fmac_f32_dpp v94, v94, v190 row_shl:8 row_mask:0xf bank_mask:0xf bound_ctrl:0
	v_fmac_f32_dpp v95, v95, v191 row_shl:8 row_mask:0xf bank_mask:0xf bound_ctrl:0
	v_fmac_f32_dpp v92, v96, -v192 row_shl:8 row_mask:0xf bank_mask:0xf bound_ctrl:0
	v_fmac_f32_dpp v93, v97, -v193 row_shl:8 row_mask:0xf bank_mask:0xf bound_ctrl:0
	v_fmac_f32_dpp v94, v98, -v194 row_shl:8 row_mask:0xf bank_mask:0xf bound_ctrl:0
	v_fmac_f32_dpp v95, v99, -v195 row_shl:8 row_mask:0xf bank_mask:0xf bound_ctrl:0
	v_fmac_f32_dpp v96, v96, v188 row_shl:8 row_mask:0xf bank_mask:0xf bound_ctrl:0
	v_fmac_f32_dpp v97, v97, v189 row_shl:8 row_mask:0xf bank_mask:0xf bound_ctrl:0
	v_fmac_f32_dpp v98, v98, v190 row_shl:8 row_mask:0xf bank_mask:0xf bound_ctrl:0
	v_fmac_f32_dpp v99, v99, v191 row_shl:8 row_mask:0xf bank_mask:0xf bound_ctrl:0
	v_fmac_f32_dpp v96, v232, v192 row_shl:8 row_mask:0xf bank_mask:0xf bound_ctrl:0
	v_fmac_f32_dpp v97, v233, v193 row_shl:8 row_mask:0xf bank_mask:0xf bound_ctrl:0
	v_fmac_f32_dpp v98, v234, v194 row_shl:8 row_mask:0xf bank_mask:0xf bound_ctrl:0
	v_fmac_f32_dpp v99, v235, v195 row_shl:8 row_mask:0xf bank_mask:0xf bound_ctrl:0
	ds_read_b128 v[188:191], v18 offset:1664
	ds_read_b128 v[192:195], v18 offset:1920
	s_waitcnt lgkmcnt(2)
	v_mov_b32_e32 v232, v100
	v_mov_b32_e32 v233, v101
	v_mov_b32_e32 v234, v102
	v_mov_b32_e32 v235, v103
	v_fmac_f32_dpp v100, v100, v224 row_shl:8 row_mask:0xf bank_mask:0xf bound_ctrl:0
	v_fmac_f32_dpp v101, v101, v225 row_shl:8 row_mask:0xf bank_mask:0xf bound_ctrl:0
	v_fmac_f32_dpp v102, v102, v226 row_shl:8 row_mask:0xf bank_mask:0xf bound_ctrl:0
	v_fmac_f32_dpp v103, v103, v227 row_shl:8 row_mask:0xf bank_mask:0xf bound_ctrl:0
	v_fmac_f32_dpp v100, v104, -v228 row_shl:8 row_mask:0xf bank_mask:0xf bound_ctrl:0
	v_fmac_f32_dpp v101, v105, -v229 row_shl:8 row_mask:0xf bank_mask:0xf bound_ctrl:0
	v_fmac_f32_dpp v102, v106, -v230 row_shl:8 row_mask:0xf bank_mask:0xf bound_ctrl:0
	v_fmac_f32_dpp v103, v107, -v231 row_shl:8 row_mask:0xf bank_mask:0xf bound_ctrl:0
	v_fmac_f32_dpp v104, v104, v224 row_shl:8 row_mask:0xf bank_mask:0xf bound_ctrl:0
	v_fmac_f32_dpp v105, v105, v225 row_shl:8 row_mask:0xf bank_mask:0xf bound_ctrl:0
	v_fmac_f32_dpp v106, v106, v226 row_shl:8 row_mask:0xf bank_mask:0xf bound_ctrl:0
	v_fmac_f32_dpp v107, v107, v227 row_shl:8 row_mask:0xf bank_mask:0xf bound_ctrl:0
	v_fmac_f32_dpp v104, v232, v228 row_shl:8 row_mask:0xf bank_mask:0xf bound_ctrl:0
	v_fmac_f32_dpp v105, v233, v229 row_shl:8 row_mask:0xf bank_mask:0xf bound_ctrl:0
	v_fmac_f32_dpp v106, v234, v230 row_shl:8 row_mask:0xf bank_mask:0xf bound_ctrl:0
	v_fmac_f32_dpp v107, v235, v231 row_shl:8 row_mask:0xf bank_mask:0xf bound_ctrl:0
	ds_read_b128 v[224:227], v18 offset:1728
	ds_read_b128 v[228:231], v18 offset:1984
	s_waitcnt lgkmcnt(2)
	v_mov_b32_e32 v232, v108
	v_mov_b32_e32 v233, v109
	v_mov_b32_e32 v234, v110
	v_mov_b32_e32 v235, v111
	v_fmac_f32_dpp v108, v108, v188 row_shl:8 row_mask:0xf bank_mask:0xf bound_ctrl:0
	v_fmac_f32_dpp v109, v109, v189 row_shl:8 row_mask:0xf bank_mask:0xf bound_ctrl:0
	v_fmac_f32_dpp v110, v110, v190 row_shl:8 row_mask:0xf bank_mask:0xf bound_ctrl:0
	v_fmac_f32_dpp v111, v111, v191 row_shl:8 row_mask:0xf bank_mask:0xf bound_ctrl:0
	v_fmac_f32_dpp v108, v112, -v192 row_shl:8 row_mask:0xf bank_mask:0xf bound_ctrl:0
	v_fmac_f32_dpp v109, v113, -v193 row_shl:8 row_mask:0xf bank_mask:0xf bound_ctrl:0
	v_fmac_f32_dpp v110, v114, -v194 row_shl:8 row_mask:0xf bank_mask:0xf bound_ctrl:0
	v_fmac_f32_dpp v111, v115, -v195 row_shl:8 row_mask:0xf bank_mask:0xf bound_ctrl:0
	v_fmac_f32_dpp v112, v112, v188 row_shl:8 row_mask:0xf bank_mask:0xf bound_ctrl:0
	v_fmac_f32_dpp v113, v113, v189 row_shl:8 row_mask:0xf bank_mask:0xf bound_ctrl:0
	v_fmac_f32_dpp v114, v114, v190 row_shl:8 row_mask:0xf bank_mask:0xf bound_ctrl:0
	v_fmac_f32_dpp v115, v115, v191 row_shl:8 row_mask:0xf bank_mask:0xf bound_ctrl:0
	v_fmac_f32_dpp v112, v232, v192 row_shl:8 row_mask:0xf bank_mask:0xf bound_ctrl:0
	v_fmac_f32_dpp v113, v233, v193 row_shl:8 row_mask:0xf bank_mask:0xf bound_ctrl:0
	v_fmac_f32_dpp v114, v234, v194 row_shl:8 row_mask:0xf bank_mask:0xf bound_ctrl:0
	v_fmac_f32_dpp v115, v235, v195 row_shl:8 row_mask:0xf bank_mask:0xf bound_ctrl:0
	s_waitcnt lgkmcnt(0)
	v_mov_b32_e32 v232, v116
	v_mov_b32_e32 v233, v117
	v_mov_b32_e32 v234, v118
	v_mov_b32_e32 v235, v119
	v_fmac_f32_dpp v116, v116, v224 row_shl:8 row_mask:0xf bank_mask:0xf bound_ctrl:0
	v_fmac_f32_dpp v117, v117, v225 row_shl:8 row_mask:0xf bank_mask:0xf bound_ctrl:0
	v_fmac_f32_dpp v118, v118, v226 row_shl:8 row_mask:0xf bank_mask:0xf bound_ctrl:0
	v_fmac_f32_dpp v119, v119, v227 row_shl:8 row_mask:0xf bank_mask:0xf bound_ctrl:0
	v_fmac_f32_dpp v116, v120, -v228 row_shl:8 row_mask:0xf bank_mask:0xf bound_ctrl:0
	v_fmac_f32_dpp v117, v121, -v229 row_shl:8 row_mask:0xf bank_mask:0xf bound_ctrl:0
	v_fmac_f32_dpp v118, v122, -v230 row_shl:8 row_mask:0xf bank_mask:0xf bound_ctrl:0
	v_fmac_f32_dpp v119, v123, -v231 row_shl:8 row_mask:0xf bank_mask:0xf bound_ctrl:0
	v_fmac_f32_dpp v120, v120, v224 row_shl:8 row_mask:0xf bank_mask:0xf bound_ctrl:0
	v_fmac_f32_dpp v121, v121, v225 row_shl:8 row_mask:0xf bank_mask:0xf bound_ctrl:0
	v_fmac_f32_dpp v122, v122, v226 row_shl:8 row_mask:0xf bank_mask:0xf bound_ctrl:0
	v_fmac_f32_dpp v123, v123, v227 row_shl:8 row_mask:0xf bank_mask:0xf bound_ctrl:0
	v_fmac_f32_dpp v120, v232, v228 row_shl:8 row_mask:0xf bank_mask:0xf bound_ctrl:0
	v_fmac_f32_dpp v121, v233, v229 row_shl:8 row_mask:0xf bank_mask:0xf bound_ctrl:0
	v_fmac_f32_dpp v122, v234, v230 row_shl:8 row_mask:0xf bank_mask:0xf bound_ctrl:0
	v_fmac_f32_dpp v123, v235, v231 row_shl:8 row_mask:0xf bank_mask:0xf bound_ctrl:0
	s_nop 1
	v_mov_b32_dpp v124, v92 row_newbcast:0 row_mask:0xf bank_mask:0xf
	v_mov_b32_dpp v125, v96 row_newbcast:0 row_mask:0xf bank_mask:0xf
	v_mov_b32_dpp v126, v93 row_newbcast:0 row_mask:0xf bank_mask:0xf
	v_mov_b32_dpp v127, v97 row_newbcast:0 row_mask:0xf bank_mask:0xf
	v_mov_b32_dpp v128, v94 row_newbcast:0 row_mask:0xf bank_mask:0xf
	v_mov_b32_dpp v129, v98 row_newbcast:0 row_mask:0xf bank_mask:0xf
	v_mov_b32_dpp v130, v95 row_newbcast:0 row_mask:0xf bank_mask:0xf
	v_mov_b32_dpp v131, v99 row_newbcast:0 row_mask:0xf bank_mask:0xf
	v_mov_b32_dpp v140, v100 row_newbcast:0 row_mask:0xf bank_mask:0xf
	v_mov_b32_dpp v141, v104 row_newbcast:0 row_mask:0xf bank_mask:0xf
	v_mov_b32_dpp v142, v101 row_newbcast:0 row_mask:0xf bank_mask:0xf
	v_mov_b32_dpp v143, v105 row_newbcast:0 row_mask:0xf bank_mask:0xf
	v_mov_b32_dpp v144, v102 row_newbcast:0 row_mask:0xf bank_mask:0xf
	v_mov_b32_dpp v145, v106 row_newbcast:0 row_mask:0xf bank_mask:0xf
	v_mov_b32_dpp v146, v103 row_newbcast:0 row_mask:0xf bank_mask:0xf
	v_mov_b32_dpp v147, v107 row_newbcast:0 row_mask:0xf bank_mask:0xf
	v_mov_b32_dpp v148, v108 row_newbcast:0 row_mask:0xf bank_mask:0xf
	v_mov_b32_dpp v149, v112 row_newbcast:0 row_mask:0xf bank_mask:0xf
	v_mov_b32_dpp v150, v109 row_newbcast:0 row_mask:0xf bank_mask:0xf
	v_mov_b32_dpp v151, v113 row_newbcast:0 row_mask:0xf bank_mask:0xf
	v_mov_b32_dpp v152, v110 row_newbcast:0 row_mask:0xf bank_mask:0xf
	v_mov_b32_dpp v153, v114 row_newbcast:0 row_mask:0xf bank_mask:0xf
	v_mov_b32_dpp v154, v111 row_newbcast:0 row_mask:0xf bank_mask:0xf
	v_mov_b32_dpp v155, v115 row_newbcast:0 row_mask:0xf bank_mask:0xf
	v_mov_b32_dpp v156, v116 row_newbcast:0 row_mask:0xf bank_mask:0xf
	v_mov_b32_dpp v157, v120 row_newbcast:0 row_mask:0xf bank_mask:0xf
	v_mov_b32_dpp v158, v117 row_newbcast:0 row_mask:0xf bank_mask:0xf
	v_mov_b32_dpp v159, v121 row_newbcast:0 row_mask:0xf bank_mask:0xf
	v_mov_b32_dpp v168, v118 row_newbcast:0 row_mask:0xf bank_mask:0xf
	v_mov_b32_dpp v169, v122 row_newbcast:0 row_mask:0xf bank_mask:0xf
	v_mov_b32_dpp v170, v119 row_newbcast:0 row_mask:0xf bank_mask:0xf
	v_mov_b32_dpp v171, v123 row_newbcast:0 row_mask:0xf bank_mask:0xf
	s_nop 1
	v_mfma_f32_16x16x4_f32 v[172:175], v92, v60, v[172:175]
	v_mfma_f32_16x16x4_f32 v[180:183], v96, v64, v[180:183]
	v_mfma_f32_16x16x4_f32 v[172:175], v93, v61, v[172:175]
	v_mfma_f32_16x16x4_f32 v[180:183], v97, v65, v[180:183]
	v_mfma_f32_16x16x4_f32 v[172:175], v94, v62, v[172:175]
	v_mfma_f32_16x16x4_f32 v[180:183], v98, v66, v[180:183]
	v_mfma_f32_16x16x4_f32 v[172:175], v95, v63, v[172:175]
	v_mfma_f32_16x16x4_f32 v[180:183], v99, v67, v[180:183]
	v_mfma_f32_16x16x4_f32 v[172:175], v100, v68, v[172:175]
	v_mfma_f32_16x16x4_f32 v[180:183], v104, v72, v[180:183]
	v_mfma_f32_16x16x4_f32 v[172:175], v101, v69, v[172:175]
	v_mfma_f32_16x16x4_f32 v[180:183], v105, v73, v[180:183]
	v_mfma_f32_16x16x4_f32 v[172:175], v102, v70, v[172:175]
	v_mfma_f32_16x16x4_f32 v[180:183], v106, v74, v[180:183]
	v_mfma_f32_16x16x4_f32 v[172:175], v103, v71, v[172:175]
	v_mfma_f32_16x16x4_f32 v[180:183], v107, v75, v[180:183]
	v_mfma_f32_16x16x4_f32 v[172:175], v108, v76, v[172:175]
	v_mfma_f32_16x16x4_f32 v[180:183], v112, v80, v[180:183]
	v_mfma_f32_16x16x4_f32 v[172:175], v109, v77, v[172:175]
	v_mfma_f32_16x16x4_f32 v[180:183], v113, v81, v[180:183]
	v_mfma_f32_16x16x4_f32 v[172:175], v110, v78, v[172:175]
	v_mfma_f32_16x16x4_f32 v[180:183], v114, v82, v[180:183]
	v_mfma_f32_16x16x4_f32 v[172:175], v111, v79, v[172:175]
	v_mfma_f32_16x16x4_f32 v[180:183], v115, v83, v[180:183]
	v_mfma_f32_16x16x4_f32 v[172:175], v116, v84, v[172:175]
	v_mfma_f32_16x16x4_f32 v[180:183], v120, v88, v[180:183]
	v_mfma_f32_16x16x4_f32 v[172:175], v117, v85, v[172:175]
	v_mfma_f32_16x16x4_f32 v[180:183], v121, v89, v[180:183]
	v_mfma_f32_16x16x4_f32 v[172:175], v118, v86, v[172:175]
	v_mfma_f32_16x16x4_f32 v[180:183], v122, v90, v[180:183]
	v_mfma_f32_16x16x4_f32 v[172:175], v119, v87, v[172:175]
	v_mfma_f32_16x16x4_f32 v[180:183], v123, v91, v[180:183]
	s_cmp_ge_u32 s0, 128
	s_cbranch_scc1 .Ls5b_nofin2
	s_and_b32 s55, s0, 7
	s_cmp_lg_u32 s55, 0
	s_cbranch_scc1 .Ls5b_nofin2
	s_lshr_b32 s55, s0, 3
	s_lshl_b32 s55, s55, 2
	s_add_i32 s55, s55, s6
	s_lshl_b32 s55, s55, 1
	s_add_i32 s55, s55, 1
	s_lshl_b32 s55, s55, 4
	s_add_i32 s55, s55, s5
	s_lshl_b32 s55, s55, 8
	s_add_u32 s48, s92, 0x4000000
	s_addc_u32 s49, s93, 0
	s_add_u32 s48, s48, s55
	s_addc_u32 s49, s49, 0
	s_add_u32 s50, s48, 0x80000
	s_addc_u32 s51, s49, 0
	s_mov_b64 exec, s[52:53]
	global_store_dword v16, v124, s[48:49] offset:0
	global_store_dword v16, v125, s[50:51] offset:0
	global_store_dword v16, v126, s[48:49] offset:4
	global_store_dword v16, v127, s[50:51] offset:4
	global_store_dword v16, v128, s[48:49] offset:8
	global_store_dword v16, v129, s[50:51] offset:8
	global_store_dword v16, v130, s[48:49] offset:12
	global_store_dword v16, v131, s[50:51] offset:12
	global_store_dword v16, v140, s[48:49] offset:64
	global_store_dword v16, v141, s[50:51] offset:64
	global_store_dword v16, v142, s[48:49] offset:68
	global_store_dword v16, v143, s[50:51] offset:68
	global_store_dword v16, v144, s[48:49] offset:72
	global_store_dword v16, v145, s[50:51] offset:72
	global_store_dword v16, v146, s[48:49] offset:76
	global_store_dword v16, v147, s[50:51] offset:76
	global_store_dword v16, v148, s[48:49] offset:128
	global_store_dword v16, v149, s[50:51] offset:128
	global_store_dword v16, v150, s[48:49] offset:132
	global_store_dword v16, v151, s[50:51] offset:132
	global_store_dword v16, v152, s[48:49] offset:136
	global_store_dword v16, v153, s[50:51] offset:136
	global_store_dword v16, v154, s[48:49] offset:140
	global_store_dword v16, v155, s[50:51] offset:140
	global_store_dword v16, v156, s[48:49] offset:192
	global_store_dword v16, v157, s[50:51] offset:192
	global_store_dword v16, v158, s[48:49] offset:196
	global_store_dword v16, v159, s[50:51] offset:196
	global_store_dword v16, v168, s[48:49] offset:200
	global_store_dword v16, v169, s[50:51] offset:200
	global_store_dword v16, v170, s[48:49] offset:204
	global_store_dword v16, v171, s[50:51] offset:204
	s_mov_b64 exec, -1
.Ls5b_nofin2:
	global_load_dword v36, v15, s[20:21]
	global_load_dword v28, v7, s[8:9] offset:0
	global_load_dword v29, v7, s[8:9] offset:1024
	global_load_dword v30, v7, s[8:9] offset:2048
	global_load_dword v31, v7, s[8:9] offset:3072
	global_load_dword v32, v8, s[8:9] offset:0
	global_load_dword v33, v8, s[8:9] offset:1024
	global_load_dword v34, v8, s[8:9] offset:2048
	global_load_dword v35, v8, s[8:9] offset:3072
	s_nop 9
	v_add_f32_e32 v172, v172, v180
	v_add_f32_e32 v173, v173, v181
	v_add_f32_e32 v174, v174, v182
	v_add_f32_e32 v175, v175, v183
	v_add_f32_e32 v176, v176, v184
	v_add_f32_e32 v177, v177, v185
	v_add_f32_e32 v178, v178, v186
	v_add_f32_e32 v179, v179, v187
	s_waitcnt vmcnt(8)
	s_waitcnt vmcnt(7)
	v_fmac_f32_e32 v172, v28, v36
	s_waitcnt vmcnt(6)
	v_fmac_f32_e32 v173, v29, v36
	s_waitcnt vmcnt(5)
	v_fmac_f32_e32 v174, v30, v36
	s_waitcnt vmcnt(4)
	v_fmac_f32_e32 v175, v31, v36
	s_waitcnt vmcnt(3)
	v_fmac_f32_e32 v176, v32, v36
	s_waitcnt vmcnt(2)
	v_fmac_f32_e32 v177, v33, v36
	s_waitcnt vmcnt(1)
	v_fmac_f32_e32 v178, v34, v36
	s_waitcnt vmcnt(0)
	v_fmac_f32_e32 v179, v35, v36
	v_cvt_pk_bf16_f32 v180, v172, v172
	v_cvt_pk_bf16_f32 v181, v173, v173
	v_cvt_pk_bf16_f32 v182, v174, v174
	v_cvt_pk_bf16_f32 v183, v175, v175
	v_cvt_pk_bf16_f32 v184, v176, v176
	v_cvt_pk_bf16_f32 v185, v177, v177
	v_cvt_pk_bf16_f32 v186, v178, v178
	v_cvt_pk_bf16_f32 v187, v179, v179
	global_store_short v9, v180, s[44:45] offset:0
	global_store_short v9, v181, s[44:45] offset:512
	global_store_short v9, v182, s[44:45] offset:1024
	global_store_short v9, v183, s[44:45] offset:1536
	global_store_short v10, v184, s[44:45] offset:0
	global_store_short v10, v185, s[44:45] offset:512
	global_store_short v10, v186, s[44:45] offset:1024
	global_store_short v10, v187, s[44:45] offset:1536
	s_movk_i32 s33, 0x1ff
	v_readlane_b32 s4, v249, 11
	v_readlane_b32 s5, v249, 12
	v_readlane_b32 s6, v249, 13
	v_readlane_b32 s7, v249, 14
	v_readlane_b32 s8, v249, 15
	v_readlane_b32 s9, v249, 16
	v_readlane_b32 s10, v249, 17
	v_readlane_b32 s11, v249, 18
	v_readlane_b32 s12, v249, 19
	v_readlane_b32 s13, v249, 20
	v_readlane_b32 s14, v249, 21
	v_readlane_b32 s15, v249, 22
	v_readlane_b32 s16, v249, 23
	v_readlane_b32 s17, v249, 24
	v_readlane_b32 s18, v249, 25
	v_readlane_b32 s19, v249, 26
	s_branch .LBB0_408
